# stack_i + static priority raise for the younger half: waves 4-7 run a K-loop copy with every setprio +1
# baseline (speedup 1.0000x reference)
;     __host__ __device__ bool next(int i, Unit& u) const { const int t = i / 3, b = i - 3 * t; Unit v; if (!StaticOrder::next(t, v)) return false; u.pm = v.pm; u.pn = 8 * b + v.pn; return true; }
; #define PG8_STAGE(bufoff, gbase, voff) do { const int so_ = (int)(unsigned)((const char*)(gbase) - base_##voff); _Pragma("unroll") for (int _i = 0; _i < 2; ++_i) \
;         __builtin_amdgcn_raw_ptr_buffer_load_lds(rs_##voff, (PG8_LAS unsigned*)(lds + (bufoff) + ldsw + _i * 8192), 16, (int)(voff)[_i], so_, 0, 0); } while (0)
; #define PG8_LDA(dst, b, h) do { _Pragma("unroll") for (int m = 0; m < 4; ++m) _Pragma("unroll") for (int k = 0; k < 2; ++k) dst[m][k] = *(const PG8_LAS bf16x8*)(lds + PG8_SA(b, h) + aoff + m * 2048 + k * 1024); } while (0)
; #define PG8_WAIT_V(n) asm volatile("s_waitcnt vmcnt(" #n ")" ::: "memory")
; #define PG8_WAIT_L(n) asm volatile("s_waitcnt lgkmcnt(" #n ")" ::: "memory")
; #define PG8_BAR __builtin_amdgcn_s_barrier()
; template <class Epi, class Sched, bool ALIGN_EPI = false, bool SP2 = false>
; __device__ __forceinline__ void gemm_phase(PG8_LAS unsigned char* lds, const Gemm g, const Sched& S, const Epi& E, int tid_in) {
;     ...
;         const bool has_next = S.next(ui + 1, nxt);
;         const char* nA = has_next ? (const char*)g.A + (size_t)nxt.pm * tstepA + (g.grp ? (size_t)(nxt.pn / g.grp) * g.agrp : (size_t)0) : cA; const char* nB = has_next ? (const char*)g.Bt + (size_t)nxt.pn * tstepB : cB;
;         for (int t = 0; t < nt; t += 2) {
;             const bool last = (t == nt - 2);
;             const char* a1 = cA + (size_t)(t + 1) * kstep;
;             const char* a2 = last ? nA : cA + (size_t)(t + 2) * kstep; const char* b2 = last ? nB : cB + (size_t)(t + 2) * kstep;
;             const char* a3 = a2 + kstep; const char* b3 = b2 + kstep;
;             if (last && has_next) S.a_ready(nxt);
;             if constexpr (SP2) {
;             PG8_LDB(B0, 0, 0); PG8_LDB(B1, 0, 1); PG8_SCHED; PG8_LDA(At, 0, 0); PG8_STAGE(PG8_SA(1, 1), a1 + hstepA, voffA);
;             PG8_WAIT_V(8); PG8_WAIT_L(0); PG8_BAR; PG8_MMA(0, 0, At, B0); PG8_MMA(0, 1, At, B1); PG8_BAR; PG8_SCHED;
;             PG8_LDA(At, 0, 1); PG8_STAGE(PG8_SB(0, 0), b2, voffB); PG8_STAGE(PG8_SB(0, 1), b2 + hstepB, voffB); PG8_STAGE(PG8_SA(0, 0), a2, voffA);
;             PG8_WAIT_V(8); PG8_WAIT_L(0); PG8_BAR; PG8_MMA(1, 0, At, B0); PG8_MMA(1, 1, At, B1); PG8_BAR; PG8_SCHED;
.LBB0_311:
	s_ashr_i32 s23, s22, 31
	s_lshl_b64 s[10:11], s[22:23], 20
	s_add_u32 s24, s4, s10
	s_addc_u32 s25, s26, s11
	s_and_b64 s[10:11], s[34:35], exec
	s_cselect_b32 s19, s24, s12
	s_ashr_i32 s15, s14, 31
	s_lshl_b64 s[10:11], s[14:15], 20
	s_add_u32 s10, s40, s10
	s_addc_u32 s11, s60, s11
	s_and_b64 s[20:21], s[34:35], exec
	s_cselect_b32 s15, s10, s16
	s_add_u32 s20, s16, 0x100
	v_mov_b32_e32 v2, 0
	s_addc_u32 s21, s17, 0
	s_mov_b32 s23, -2
	v_add_u32_e32 v0, 0x10000, v237
	ds_read_b128 v[130:133], v0
	ds_read_b128 v[134:137], v0 offset:1024
	ds_read_b128 v[138:141], v0 offset:2048
	ds_read_b128 v[142:145], v0 offset:3072
	v_add_u32_e32 v0, 0x14000, v237
	ds_read_b128 v[146:149], v0
	ds_read_b128 v[150:153], v0 offset:1024
	ds_read_b128 v[154:157], v0 offset:2048
	ds_read_b128 v[158:161], v0 offset:3072
	s_add_u32 s16, s12, 0x100
	s_addc_u32 s17, s13, 0
	s_sub_i32 s12, s12, s4
	s_add_i32 s12, s12, 0x80080
	s_sub_i32 s36, s12, 0x80000
	s_cmp_eq_u32 s23, 28
	s_cselect_b32 s13, s19, s16
	s_mov_b32 m0, s69
	ds_read_b128 v[162:165], v238
	ds_read_b128 v[166:169], v238 offset:1024
	ds_read_b128 v[170:173], v238 offset:2048
	ds_read_b128 v[174:177], v238 offset:3072
	ds_read_b128 v[178:181], v238 offset:4096
	ds_read_b128 v[182:185], v238 offset:5120
	ds_read_b128 v[186:189], v238 offset:6144
	ds_read_b128 v[190:193], v238 offset:7168
	s_mov_b32 m0, s78
	s_nop 0
	buffer_load_dwordx4 v211, s[4:7], s36 offen lds
	s_mov_b32 m0, s69
	s_nop 0
	buffer_load_dwordx4 v195, s[4:7], s12 offen lds
	s_mov_b32 m0, s67
	s_nop 0
	buffer_load_dwordx4 v211, s[4:7], s12 offen lds
	s_waitcnt vmcnt(8)
	s_waitcnt lgkmcnt(0)
	s_setprio 1
	s_barrier
	v_mfma_f32_16x16x32_bf16 v[126:129], v[130:133], v[162:165], 0
	v_mfma_f32_16x16x32_bf16 v[122:125], v[138:141], v[162:165], 0
	v_mfma_f32_16x16x32_bf16 v[106:109], v[138:141], v[170:173], 0
	v_mfma_f32_16x16x32_bf16 v[110:113], v[130:133], v[170:173], 0
	v_mfma_f32_16x16x32_bf16 v[94:97], v[130:133], v[178:181], 0
	v_mfma_f32_16x16x32_bf16 v[90:93], v[138:141], v[178:181], 0
	v_mfma_f32_16x16x32_bf16 v[74:77], v[138:141], v[186:189], 0
	v_mfma_f32_16x16x32_bf16 v[78:81], v[130:133], v[186:189], 0
	v_mfma_f32_16x16x32_bf16 v[126:129], v[134:137], v[166:169], v[126:129]
	v_mfma_f32_16x16x32_bf16 v[122:125], v[142:145], v[166:169], v[122:125]
	v_mfma_f32_16x16x32_bf16 v[106:109], v[142:145], v[174:177], v[106:109]
	v_mfma_f32_16x16x32_bf16 v[110:113], v[134:137], v[174:177], v[110:113]
	v_mfma_f32_16x16x32_bf16 v[94:97], v[134:137], v[182:185], v[94:97]
	v_mfma_f32_16x16x32_bf16 v[90:93], v[142:145], v[182:185], v[90:93]
	v_mfma_f32_16x16x32_bf16 v[74:77], v[142:145], v[190:193], v[74:77]
	v_mfma_f32_16x16x32_bf16 v[78:81], v[134:137], v[190:193], v[78:81]
	v_mfma_f32_16x16x32_bf16 v[118:121], v[146:149], v[162:165], 0
	v_mfma_f32_16x16x32_bf16 v[114:117], v[154:157], v[162:165], 0
	v_mfma_f32_16x16x32_bf16 v[98:101], v[154:157], v[170:173], 0
	v_mfma_f32_16x16x32_bf16 v[102:105], v[146:149], v[170:173], 0
	v_mfma_f32_16x16x32_bf16 v[86:89], v[146:149], v[178:181], 0
	v_mfma_f32_16x16x32_bf16 v[82:85], v[154:157], v[178:181], 0
	v_mfma_f32_16x16x32_bf16 v[66:69], v[154:157], v[186:189], 0
	v_mfma_f32_16x16x32_bf16 v[70:73], v[146:149], v[186:189], 0
	v_mfma_f32_16x16x32_bf16 v[118:121], v[150:153], v[166:169], v[118:121]
	v_mfma_f32_16x16x32_bf16 v[114:117], v[158:161], v[166:169], v[114:117]
	v_mfma_f32_16x16x32_bf16 v[98:101], v[158:161], v[174:177], v[98:101]
	v_mfma_f32_16x16x32_bf16 v[102:105], v[150:153], v[174:177], v[102:105]
	v_mfma_f32_16x16x32_bf16 v[86:89], v[150:153], v[182:185], v[86:89]
	v_mfma_f32_16x16x32_bf16 v[82:85], v[158:161], v[182:185], v[82:85]
	v_mfma_f32_16x16x32_bf16 v[66:69], v[158:161], v[190:193], v[66:69]
	v_mfma_f32_16x16x32_bf16 v[70:73], v[150:153], v[190:193], v[70:73]
	s_barrier
	s_setprio 0
	s_cselect_b32 s12, s15, s20
	s_mov_b32 m0, s61
	s_mov_b32 s42, s6
	s_mov_b32 s43, s7
	s_sub_i32 s12, s12, s40
	ds_read_b128 v[162:165], v238 offset:16384
	ds_read_b128 v[166:169], v238 offset:17408
	ds_read_b128 v[170:173], v238 offset:18432
	ds_read_b128 v[174:177], v238 offset:19456
	ds_read_b128 v[178:181], v238 offset:20480
	ds_read_b128 v[182:185], v238 offset:21504
	ds_read_b128 v[186:189], v238 offset:22528
	ds_read_b128 v[190:193], v238 offset:23552
	buffer_load_dwordx4 v207, s[40:43], s12 offen lds
	s_mov_b32 m0, s62
	s_add_i32 s36, s12, 0x80000
	buffer_load_dwordx4 v224, s[40:43], s12 offen lds
	s_mov_b32 m0, s63
	s_sub_i32 s13, s13, s4
	buffer_load_dwordx4 v207, s[40:43], s36 offen lds
	s_mov_b32 m0, s71
	s_nop 0
	buffer_load_dwordx4 v224, s[40:43], s36 offen lds
	s_mov_b32 m0, s53
	s_nop 0
	buffer_load_dwordx4 v195, s[4:7], s13 offen lds
	s_waitcnt vmcnt(7)
	s_waitcnt lgkmcnt(0)
	s_setprio 1
	s_barrier
; #define PG8_STAGE(bufoff, gbase, voff) do { const int so_ = (int)(unsigned)((const char*)(gbase) - base_##voff); _Pragma("unroll") for (int _i = 0; _i < 2; ++_i) \
;         __builtin_amdgcn_raw_ptr_buffer_load_lds(rs_##voff, (PG8_LAS unsigned*)(lds + (bufoff) + ldsw + _i * 8192), 16, (int)(voff)[_i], so_, 0, 0); } while (0)
; #define PG8_LDA(dst, b, h) do { _Pragma("unroll") for (int m = 0; m < 4; ++m) _Pragma("unroll") for (int k = 0; k < 2; ++k) dst[m][k] = *(const PG8_LAS bf16x8*)(lds + PG8_SA(b, h) + aoff + m * 2048 + k * 1024); } while (0)
; #define PG8_LDB(dst, b, h) do { _Pragma("unroll") for (int n = 0; n < 2; ++n) _Pragma("unroll") for (int k = 0; k < 2; ++k) dst[n][k] = *(const PG8_LAS bf16x8*)(lds + PG8_SB(b, h) + boff + n * 2048 + k * 1024); } while (0)
; #define PG8_MMA(ai, bj, At, Bt) do { __builtin_amdgcn_s_setprio(1); _Pragma("unroll") for (int m = 0; m < 4; ++m) _Pragma("unroll") for (int n = 0; n < 2; ++n) _Pragma("unroll") for (int k = 0; k < 2; ++k) \
;         acc[ai][bj][m][n] = __builtin_amdgcn_mfma_f32_16x16x32_bf16(Bt[n][k], At[m][k], acc[ai][bj][m][n], 0, 0, 0); __builtin_amdgcn_s_setprio(0); } while (0)
; #define PG8_WAIT_V(n) asm volatile("s_waitcnt vmcnt(" #n ")" ::: "memory")
; #define PG8_WAIT_L(n) asm volatile("s_waitcnt lgkmcnt(" #n ")" ::: "memory")
; #define PG8_BAR __builtin_amdgcn_s_barrier()
; #define PG8_SCHED __builtin_amdgcn_sched_barrier(0)
; template <class Epi, class Sched, bool ALIGN_EPI = false, bool SP2 = false>
; __device__ __forceinline__ void gemm_phase(PG8_LAS unsigned char* lds, const Gemm g, const Sched& S, const Epi& E, int tid_in) {
;     ...
;             PG8_WAIT_V(8); PG8_WAIT_L(0); PG8_BAR; PG8_MMA(1, 0, At, B0); PG8_MMA(1, 1, At, B1); PG8_BAR; PG8_SCHED;
;             PG8_LDB(B0, 1, 0); PG8_LDB(B1, 1, 1); PG8_SCHED; PG8_LDA(At, 1, 0); PG8_STAGE(PG8_SA(0, 1), a2 + hstepA, voffA);
;             PG8_WAIT_V(8); PG8_WAIT_L(0); PG8_BAR; PG8_MMA(0, 0, At, B0); PG8_MMA(0, 1, At, B1); PG8_BAR; PG8_SCHED;
	v_mfma_f32_16x16x32_bf16 v[62:65], v[130:133], v[162:165], 0
	v_mfma_f32_16x16x32_bf16 v[58:61], v[138:141], v[162:165], 0
	v_mfma_f32_16x16x32_bf16 v[42:45], v[138:141], v[170:173], 0
	v_mfma_f32_16x16x32_bf16 v[46:49], v[130:133], v[170:173], 0
	v_mfma_f32_16x16x32_bf16 v[30:33], v[130:133], v[178:181], 0
	v_mfma_f32_16x16x32_bf16 v[26:29], v[138:141], v[178:181], 0
	v_mfma_f32_16x16x32_bf16 v[10:13], v[138:141], v[186:189], 0
	v_mfma_f32_16x16x32_bf16 v[14:17], v[130:133], v[186:189], 0
	v_mfma_f32_16x16x32_bf16 v[62:65], v[134:137], v[166:169], v[62:65]
	v_mfma_f32_16x16x32_bf16 v[58:61], v[142:145], v[166:169], v[58:61]
	v_mfma_f32_16x16x32_bf16 v[42:45], v[142:145], v[174:177], v[42:45]
	v_mfma_f32_16x16x32_bf16 v[46:49], v[134:137], v[174:177], v[46:49]
	v_mfma_f32_16x16x32_bf16 v[30:33], v[134:137], v[182:185], v[30:33]
	v_mfma_f32_16x16x32_bf16 v[26:29], v[142:145], v[182:185], v[26:29]
	v_mfma_f32_16x16x32_bf16 v[10:13], v[142:145], v[190:193], v[10:13]
	v_mfma_f32_16x16x32_bf16 v[14:17], v[134:137], v[190:193], v[14:17]
	v_mfma_f32_16x16x32_bf16 v[54:57], v[146:149], v[162:165], 0
	v_mfma_f32_16x16x32_bf16 v[50:53], v[154:157], v[162:165], 0
	v_mfma_f32_16x16x32_bf16 v[34:37], v[154:157], v[170:173], 0
	v_mfma_f32_16x16x32_bf16 v[38:41], v[146:149], v[170:173], 0
	v_mfma_f32_16x16x32_bf16 v[22:25], v[146:149], v[178:181], 0
	v_mfma_f32_16x16x32_bf16 v[18:21], v[154:157], v[178:181], 0
	v_mfma_f32_16x16x32_bf16 v[2:5], v[154:157], v[186:189], 0
	v_mfma_f32_16x16x32_bf16 v[6:9], v[146:149], v[186:189], 0
	v_mfma_f32_16x16x32_bf16 v[54:57], v[150:153], v[166:169], v[54:57]
	v_mfma_f32_16x16x32_bf16 v[50:53], v[158:161], v[166:169], v[50:53]
	v_mfma_f32_16x16x32_bf16 v[34:37], v[158:161], v[174:177], v[34:37]
	v_mfma_f32_16x16x32_bf16 v[38:41], v[150:153], v[174:177], v[38:41]
	v_mfma_f32_16x16x32_bf16 v[22:25], v[150:153], v[182:185], v[22:25]
	v_mfma_f32_16x16x32_bf16 v[18:21], v[158:161], v[182:185], v[18:21]
	v_mfma_f32_16x16x32_bf16 v[2:5], v[158:161], v[190:193], v[2:5]
	v_mfma_f32_16x16x32_bf16 v[6:9], v[150:153], v[190:193], v[6:9]
	s_barrier
	s_setprio 0
	v_add_u32_e32 v0, 0x18000, v237
	ds_read_b128 v[130:133], v0
	ds_read_b128 v[134:137], v0 offset:1024
	ds_read_b128 v[138:141], v0 offset:2048
	ds_read_b128 v[142:145], v0 offset:3072
	v_add_u32_e32 v0, 0x1c000, v237
	ds_read_b128 v[146:149], v0
	ds_read_b128 v[150:153], v0 offset:1024
	ds_read_b128 v[154:157], v0 offset:2048
	ds_read_b128 v[158:161], v0 offset:3072
	s_add_i32 s36, s13, 0x80000
	s_mov_b32 m0, s73
	ds_read_b128 v[162:165], v238 offset:32768
	ds_read_b128 v[166:169], v238 offset:33792
	ds_read_b128 v[170:173], v238 offset:34816
	ds_read_b128 v[174:177], v238 offset:35840
	ds_read_b128 v[178:181], v238 offset:36864
	ds_read_b128 v[182:185], v238 offset:37888
	ds_read_b128 v[186:189], v238 offset:38912
	ds_read_b128 v[190:193], v238 offset:39936
	s_mov_b32 m0, s72
	s_nop 0
	buffer_load_dwordx4 v211, s[4:7], s13 offen lds
	s_mov_b32 m0, s73
	s_nop 0
	buffer_load_dwordx4 v195, s[4:7], s36 offen lds
	s_mov_b32 m0, s74
	s_nop 0
	buffer_load_dwordx4 v211, s[4:7], s36 offen lds
	s_waitcnt vmcnt(8)
	s_waitcnt lgkmcnt(0)
	s_setprio 1
	s_barrier
	v_mfma_f32_16x16x32_bf16 v[126:129], v[130:133], v[162:165], v[126:129]
	v_mfma_f32_16x16x32_bf16 v[122:125], v[138:141], v[162:165], v[122:125]
	v_mfma_f32_16x16x32_bf16 v[106:109], v[138:141], v[170:173], v[106:109]
	v_mfma_f32_16x16x32_bf16 v[110:113], v[130:133], v[170:173], v[110:113]
	v_mfma_f32_16x16x32_bf16 v[94:97], v[130:133], v[178:181], v[94:97]
	v_mfma_f32_16x16x32_bf16 v[90:93], v[138:141], v[178:181], v[90:93]
	v_mfma_f32_16x16x32_bf16 v[74:77], v[138:141], v[186:189], v[74:77]
	v_mfma_f32_16x16x32_bf16 v[78:81], v[130:133], v[186:189], v[78:81]
	v_mfma_f32_16x16x32_bf16 v[126:129], v[134:137], v[166:169], v[126:129]
	v_mfma_f32_16x16x32_bf16 v[122:125], v[142:145], v[166:169], v[122:125]
	v_mfma_f32_16x16x32_bf16 v[106:109], v[142:145], v[174:177], v[106:109]
	v_mfma_f32_16x16x32_bf16 v[110:113], v[134:137], v[174:177], v[110:113]
	v_mfma_f32_16x16x32_bf16 v[94:97], v[134:137], v[182:185], v[94:97]
	v_mfma_f32_16x16x32_bf16 v[90:93], v[142:145], v[182:185], v[90:93]
	v_mfma_f32_16x16x32_bf16 v[74:77], v[142:145], v[190:193], v[74:77]
	v_mfma_f32_16x16x32_bf16 v[78:81], v[134:137], v[190:193], v[78:81]
	v_mfma_f32_16x16x32_bf16 v[118:121], v[146:149], v[162:165], v[118:121]
	v_mfma_f32_16x16x32_bf16 v[114:117], v[154:157], v[162:165], v[114:117]
	v_mfma_f32_16x16x32_bf16 v[98:101], v[154:157], v[170:173], v[98:101]
	v_mfma_f32_16x16x32_bf16 v[102:105], v[146:149], v[170:173], v[102:105]
	v_mfma_f32_16x16x32_bf16 v[86:89], v[146:149], v[178:181], v[86:89]
	v_mfma_f32_16x16x32_bf16 v[82:85], v[154:157], v[178:181], v[82:85]
	v_mfma_f32_16x16x32_bf16 v[66:69], v[154:157], v[186:189], v[66:69]
	v_mfma_f32_16x16x32_bf16 v[70:73], v[146:149], v[186:189], v[70:73]
	v_mfma_f32_16x16x32_bf16 v[118:121], v[150:153], v[166:169], v[118:121]
	v_mfma_f32_16x16x32_bf16 v[114:117], v[158:161], v[166:169], v[114:117]
	v_mfma_f32_16x16x32_bf16 v[98:101], v[158:161], v[174:177], v[98:101]
	v_mfma_f32_16x16x32_bf16 v[102:105], v[150:153], v[174:177], v[102:105]
	v_mfma_f32_16x16x32_bf16 v[86:89], v[150:153], v[182:185], v[86:89]
	v_mfma_f32_16x16x32_bf16 v[82:85], v[158:161], v[182:185], v[82:85]
	v_mfma_f32_16x16x32_bf16 v[66:69], v[158:161], v[190:193], v[66:69]
	v_mfma_f32_16x16x32_bf16 v[70:73], v[150:153], v[190:193], v[70:73]
	s_barrier
; #define PG8_STAGE(bufoff, gbase, voff) do { const int so_ = (int)(unsigned)((const char*)(gbase) - base_##voff); _Pragma("unroll") for (int _i = 0; _i < 2; ++_i) \
;         __builtin_amdgcn_raw_ptr_buffer_load_lds(rs_##voff, (PG8_LAS unsigned*)(lds + (bufoff) + ldsw + _i * 8192), 16, (int)(voff)[_i], so_, 0, 0); } while (0)
; #define PG8_LDA(dst, b, h) do { _Pragma("unroll") for (int m = 0; m < 4; ++m) _Pragma("unroll") for (int k = 0; k < 2; ++k) dst[m][k] = *(const PG8_LAS bf16x8*)(lds + PG8_SA(b, h) + aoff + m * 2048 + k * 1024); } while (0)
; #define PG8_LDB(dst, b, h) do { _Pragma("unroll") for (int n = 0; n < 2; ++n) _Pragma("unroll") for (int k = 0; k < 2; ++k) dst[n][k] = *(const PG8_LAS bf16x8*)(lds + PG8_SB(b, h) + boff + n * 2048 + k * 1024); } while (0)
; #define PG8_MMA(ai, bj, At, Bt) do { __builtin_amdgcn_s_setprio(1); _Pragma("unroll") for (int m = 0; m < 4; ++m) _Pragma("unroll") for (int n = 0; n < 2; ++n) _Pragma("unroll") for (int k = 0; k < 2; ++k) \
;         acc[ai][bj][m][n] = __builtin_amdgcn_mfma_f32_16x16x32_bf16(Bt[n][k], At[m][k], acc[ai][bj][m][n], 0, 0, 0); __builtin_amdgcn_s_setprio(0); } while (0)
; template <class Epi, class Sched, bool ALIGN_EPI = false, bool SP2 = false>
; __device__ __forceinline__ void gemm_phase(PG8_LAS unsigned char* lds, const Gemm g, const Sched& S, const Epi& E, int tid_in) {
;     ...
;             PG8_LDB(B0, 0, 0); PG8_LDB(B1, 0, 1); PG8_SCHED; PG8_LDA(At, 0, 0); PG8_STAGE(PG8_SA(1, 1), a1 + hstepA, voffA);
;             PG8_WAIT_V(8); PG8_WAIT_L(0); PG8_BAR; PG8_MMA(0, 0, At, B0); PG8_MMA(0, 1, At, B1); PG8_BAR; PG8_SCHED;
;             PG8_LDA(At, 0, 1); PG8_STAGE(PG8_SB(0, 0), b2, voffB); PG8_STAGE(PG8_SB(0, 1), b2 + hstepB, voffB); PG8_STAGE(PG8_SA(0, 0), a2, voffA);
;             PG8_WAIT_V(8); PG8_WAIT_L(0); PG8_BAR; PG8_MMA(1, 0, At, B0); PG8_MMA(1, 1, At, B1); PG8_BAR; PG8_SCHED;
;             PG8_LDB(B0, 1, 0); PG8_LDB(B1, 1, 1); PG8_SCHED; PG8_LDA(At, 1, 0); PG8_STAGE(PG8_SA(0, 1), a2 + hstepA, voffA);
;             PG8_WAIT_V(8); PG8_WAIT_L(0); PG8_BAR; PG8_MMA(0, 0, At, B0); PG8_MMA(0, 1, At, B1); PG8_BAR; PG8_SCHED;
;             PG8_LDA(At, 1, 1); PG8_STAGE(PG8_SB(1, 0), b3, voffB); PG8_STAGE(PG8_SB(1, 1), b3 + hstepB, voffB); PG8_STAGE(PG8_SA(1, 0), a3, voffA);
;             PG8_WAIT_V(8); PG8_WAIT_L(0); PG8_BAR; PG8_MMA(1, 0, At, B0); PG8_MMA(1, 1, At, B1); PG8_BAR; PG8_SCHED;
	s_setprio 0
	s_mov_b32 m0, s75
	s_add_i32 s36, s12, 0x80
	ds_read_b128 v[162:165], v238 offset:49152
	ds_read_b128 v[166:169], v238 offset:50176
	ds_read_b128 v[170:173], v238 offset:51200
	ds_read_b128 v[174:177], v238 offset:52224
	ds_read_b128 v[178:181], v238 offset:53248
	ds_read_b128 v[182:185], v238 offset:54272
	ds_read_b128 v[186:189], v238 offset:55296
	ds_read_b128 v[190:193], v238 offset:56320
	buffer_load_dwordx4 v207, s[40:43], s36 offen lds
	s_mov_b32 m0, s76
	s_add_i32 s12, s12, 0x80080
	buffer_load_dwordx4 v224, s[40:43], s36 offen lds
	s_mov_b32 m0, s79
	s_addk_i32 s13, 0x80
	buffer_load_dwordx4 v207, s[40:43], s12 offen lds
	s_mov_b32 m0, s68
	s_nop 0
	buffer_load_dwordx4 v224, s[40:43], s12 offen lds
	s_mov_b32 m0, s77
	s_nop 0
	buffer_load_dwordx4 v195, s[4:7], s13 offen lds
	s_waitcnt vmcnt(7)
	s_waitcnt lgkmcnt(0)
	s_setprio 1
	s_barrier
	v_mfma_f32_16x16x32_bf16 v[62:65], v[130:133], v[162:165], v[62:65]
	v_mfma_f32_16x16x32_bf16 v[58:61], v[138:141], v[162:165], v[58:61]
	v_mfma_f32_16x16x32_bf16 v[42:45], v[138:141], v[170:173], v[42:45]
	v_mfma_f32_16x16x32_bf16 v[46:49], v[130:133], v[170:173], v[46:49]
	v_mfma_f32_16x16x32_bf16 v[30:33], v[130:133], v[178:181], v[30:33]
	v_mfma_f32_16x16x32_bf16 v[26:29], v[138:141], v[178:181], v[26:29]
	v_mfma_f32_16x16x32_bf16 v[10:13], v[138:141], v[186:189], v[10:13]
	v_mfma_f32_16x16x32_bf16 v[14:17], v[130:133], v[186:189], v[14:17]
	v_mfma_f32_16x16x32_bf16 v[62:65], v[134:137], v[166:169], v[62:65]
	v_mfma_f32_16x16x32_bf16 v[58:61], v[142:145], v[166:169], v[58:61]
	v_mfma_f32_16x16x32_bf16 v[42:45], v[142:145], v[174:177], v[42:45]
	v_mfma_f32_16x16x32_bf16 v[46:49], v[134:137], v[174:177], v[46:49]
	v_mfma_f32_16x16x32_bf16 v[30:33], v[134:137], v[182:185], v[30:33]
	v_mfma_f32_16x16x32_bf16 v[26:29], v[142:145], v[182:185], v[26:29]
	v_mfma_f32_16x16x32_bf16 v[10:13], v[142:145], v[190:193], v[10:13]
	v_mfma_f32_16x16x32_bf16 v[14:17], v[134:137], v[190:193], v[14:17]
	v_mfma_f32_16x16x32_bf16 v[54:57], v[146:149], v[162:165], v[54:57]
	v_mfma_f32_16x16x32_bf16 v[50:53], v[154:157], v[162:165], v[50:53]
	v_mfma_f32_16x16x32_bf16 v[34:37], v[154:157], v[170:173], v[34:37]
	v_mfma_f32_16x16x32_bf16 v[38:41], v[146:149], v[170:173], v[38:41]
	v_mfma_f32_16x16x32_bf16 v[22:25], v[146:149], v[178:181], v[22:25]
	v_mfma_f32_16x16x32_bf16 v[18:21], v[154:157], v[178:181], v[18:21]
	v_mfma_f32_16x16x32_bf16 v[2:5], v[154:157], v[186:189], v[2:5]
	v_mfma_f32_16x16x32_bf16 v[6:9], v[146:149], v[186:189], v[6:9]
	v_mfma_f32_16x16x32_bf16 v[54:57], v[150:153], v[166:169], v[54:57]
	v_mfma_f32_16x16x32_bf16 v[50:53], v[158:161], v[166:169], v[50:53]
	v_mfma_f32_16x16x32_bf16 v[34:37], v[158:161], v[174:177], v[34:37]
	v_mfma_f32_16x16x32_bf16 v[38:41], v[150:153], v[174:177], v[38:41]
	v_mfma_f32_16x16x32_bf16 v[22:25], v[150:153], v[182:185], v[22:25]
	v_mfma_f32_16x16x32_bf16 v[18:21], v[158:161], v[182:185], v[18:21]
	v_mfma_f32_16x16x32_bf16 v[2:5], v[158:161], v[190:193], v[2:5]
	v_mfma_f32_16x16x32_bf16 v[6:9], v[150:153], v[190:193], v[6:9]
	s_barrier
	s_setprio 0
	s_add_i32 s23, s23, 2
	s_add_u32 s20, s20, 0x100
	s_addc_u32 s21, s21, 0
	s_cmp_gt_u32 s23, 29
	s_mov_b64 s[12:13], s[16:17]
	s_cmpk_lt_u32 s59, 0x100
	s_cbranch_scc0 .Lyng_loop0
.LBB0_312:
	v_add_u32_e32 v0, 0x10000, v237
	ds_read_b128 v[130:133], v0
	ds_read_b128 v[134:137], v0 offset:1024
	ds_read_b128 v[138:141], v0 offset:2048
	ds_read_b128 v[142:145], v0 offset:3072
	v_add_u32_e32 v0, 0x14000, v237
	ds_read_b128 v[146:149], v0
	ds_read_b128 v[150:153], v0 offset:1024
	ds_read_b128 v[154:157], v0 offset:2048
	ds_read_b128 v[158:161], v0 offset:3072
	s_add_u32 s16, s12, 0x100
	s_addc_u32 s17, s13, 0
	s_sub_i32 s12, s12, s4
	s_add_i32 s12, s12, 0x80080
	s_sub_i32 s36, s12, 0x80000
	s_cmp_eq_u32 s23, 28
	s_cselect_b32 s13, s19, s16
	s_mov_b32 m0, s69
	ds_read_b128 v[162:165], v238
	ds_read_b128 v[166:169], v238 offset:1024
	ds_read_b128 v[170:173], v238 offset:2048
	ds_read_b128 v[174:177], v238 offset:3072
	ds_read_b128 v[178:181], v238 offset:4096
	ds_read_b128 v[182:185], v238 offset:5120
	ds_read_b128 v[186:189], v238 offset:6144
	ds_read_b128 v[190:193], v238 offset:7168
	s_mov_b32 m0, s78
	s_nop 0
	buffer_load_dwordx4 v211, s[4:7], s36 offen lds
	s_mov_b32 m0, s69
	s_nop 0
	buffer_load_dwordx4 v195, s[4:7], s12 offen lds
	s_mov_b32 m0, s67
	s_nop 0
	buffer_load_dwordx4 v211, s[4:7], s12 offen lds
	s_waitcnt vmcnt(8)
	s_waitcnt lgkmcnt(0)
	s_setprio 1
	s_barrier
	v_mfma_f32_16x16x32_bf16 v[126:129], v[130:133], v[162:165], v[126:129]
	v_mfma_f32_16x16x32_bf16 v[122:125], v[138:141], v[162:165], v[122:125]
	v_mfma_f32_16x16x32_bf16 v[106:109], v[138:141], v[170:173], v[106:109]
	v_mfma_f32_16x16x32_bf16 v[110:113], v[130:133], v[170:173], v[110:113]
	v_mfma_f32_16x16x32_bf16 v[94:97], v[130:133], v[178:181], v[94:97]
	v_mfma_f32_16x16x32_bf16 v[90:93], v[138:141], v[178:181], v[90:93]
	v_mfma_f32_16x16x32_bf16 v[74:77], v[138:141], v[186:189], v[74:77]
	v_mfma_f32_16x16x32_bf16 v[78:81], v[130:133], v[186:189], v[78:81]
	v_mfma_f32_16x16x32_bf16 v[126:129], v[134:137], v[166:169], v[126:129]
	v_mfma_f32_16x16x32_bf16 v[122:125], v[142:145], v[166:169], v[122:125]
	v_mfma_f32_16x16x32_bf16 v[106:109], v[142:145], v[174:177], v[106:109]
	v_mfma_f32_16x16x32_bf16 v[110:113], v[134:137], v[174:177], v[110:113]
	v_mfma_f32_16x16x32_bf16 v[94:97], v[134:137], v[182:185], v[94:97]
	v_mfma_f32_16x16x32_bf16 v[90:93], v[142:145], v[182:185], v[90:93]
	v_mfma_f32_16x16x32_bf16 v[74:77], v[142:145], v[190:193], v[74:77]
	v_mfma_f32_16x16x32_bf16 v[78:81], v[134:137], v[190:193], v[78:81]
	v_mfma_f32_16x16x32_bf16 v[118:121], v[146:149], v[162:165], v[118:121]
	v_mfma_f32_16x16x32_bf16 v[114:117], v[154:157], v[162:165], v[114:117]
	v_mfma_f32_16x16x32_bf16 v[98:101], v[154:157], v[170:173], v[98:101]
	v_mfma_f32_16x16x32_bf16 v[102:105], v[146:149], v[170:173], v[102:105]
	v_mfma_f32_16x16x32_bf16 v[86:89], v[146:149], v[178:181], v[86:89]
	v_mfma_f32_16x16x32_bf16 v[82:85], v[154:157], v[178:181], v[82:85]
	v_mfma_f32_16x16x32_bf16 v[66:69], v[154:157], v[186:189], v[66:69]
	v_mfma_f32_16x16x32_bf16 v[70:73], v[146:149], v[186:189], v[70:73]
	v_mfma_f32_16x16x32_bf16 v[118:121], v[150:153], v[166:169], v[118:121]
	v_mfma_f32_16x16x32_bf16 v[114:117], v[158:161], v[166:169], v[114:117]
	v_mfma_f32_16x16x32_bf16 v[98:101], v[158:161], v[174:177], v[98:101]
	v_mfma_f32_16x16x32_bf16 v[102:105], v[150:153], v[174:177], v[102:105]
	v_mfma_f32_16x16x32_bf16 v[86:89], v[150:153], v[182:185], v[86:89]
	v_mfma_f32_16x16x32_bf16 v[82:85], v[158:161], v[182:185], v[82:85]
	v_mfma_f32_16x16x32_bf16 v[66:69], v[158:161], v[190:193], v[66:69]
	v_mfma_f32_16x16x32_bf16 v[70:73], v[150:153], v[190:193], v[70:73]
	s_barrier
; #define PG8_STAGE(bufoff, gbase, voff) do { const int so_ = (int)(unsigned)((const char*)(gbase) - base_##voff); _Pragma("unroll") for (int _i = 0; _i < 2; ++_i) \
;         __builtin_amdgcn_raw_ptr_buffer_load_lds(rs_##voff, (PG8_LAS unsigned*)(lds + (bufoff) + ldsw + _i * 8192), 16, (int)(voff)[_i], so_, 0, 0); } while (0)
; #define PG8_LDA(dst, b, h) do { _Pragma("unroll") for (int m = 0; m < 4; ++m) _Pragma("unroll") for (int k = 0; k < 2; ++k) dst[m][k] = *(const PG8_LAS bf16x8*)(lds + PG8_SA(b, h) + aoff + m * 2048 + k * 1024); } while (0)
; #define PG8_LDB(dst, b, h) do { _Pragma("unroll") for (int n = 0; n < 2; ++n) _Pragma("unroll") for (int k = 0; k < 2; ++k) dst[n][k] = *(const PG8_LAS bf16x8*)(lds + PG8_SB(b, h) + boff + n * 2048 + k * 1024); } while (0)
; #define PG8_MMA(ai, bj, At, Bt) do { __builtin_amdgcn_s_setprio(1); _Pragma("unroll") for (int m = 0; m < 4; ++m) _Pragma("unroll") for (int n = 0; n < 2; ++n) _Pragma("unroll") for (int k = 0; k < 2; ++k) \
;         acc[ai][bj][m][n] = __builtin_amdgcn_mfma_f32_16x16x32_bf16(Bt[n][k], At[m][k], acc[ai][bj][m][n], 0, 0, 0); __builtin_amdgcn_s_setprio(0); } while (0)
; #define PG8_WAIT_V(n) asm volatile("s_waitcnt vmcnt(" #n ")" ::: "memory")
; #define PG8_WAIT_L(n) asm volatile("s_waitcnt lgkmcnt(" #n ")" ::: "memory")
; #define PG8_BAR __builtin_amdgcn_s_barrier()
; #define PG8_SCHED __builtin_amdgcn_sched_barrier(0)
; template <class Epi, class Sched, bool ALIGN_EPI = false, bool SP2 = false>
; __device__ __forceinline__ void gemm_phase(PG8_LAS unsigned char* lds, const Gemm g, const Sched& S, const Epi& E, int tid_in) {
;     ...
;             PG8_LDA(At, 0, 1); PG8_STAGE(PG8_SB(0, 0), b2, voffB); PG8_STAGE(PG8_SB(0, 1), b2 + hstepB, voffB); PG8_STAGE(PG8_SA(0, 0), a2, voffA);
;             PG8_WAIT_V(8); PG8_WAIT_L(0); PG8_BAR; PG8_MMA(1, 0, At, B0); PG8_MMA(1, 1, At, B1); PG8_BAR; PG8_SCHED;
;             PG8_LDB(B0, 1, 0); PG8_LDB(B1, 1, 1); PG8_SCHED; PG8_LDA(At, 1, 0); PG8_STAGE(PG8_SA(0, 1), a2 + hstepA, voffA);
;             PG8_WAIT_V(8); PG8_WAIT_L(0); PG8_BAR; PG8_MMA(0, 0, At, B0); PG8_MMA(0, 1, At, B1); PG8_BAR; PG8_SCHED;
	s_setprio 0
	s_cselect_b32 s12, s15, s20
	s_mov_b32 m0, s61
	s_mov_b32 s42, s6
	s_mov_b32 s43, s7
	s_sub_i32 s12, s12, s40
	ds_read_b128 v[162:165], v238 offset:16384
	ds_read_b128 v[166:169], v238 offset:17408
	ds_read_b128 v[170:173], v238 offset:18432
	ds_read_b128 v[174:177], v238 offset:19456
	ds_read_b128 v[178:181], v238 offset:20480
	ds_read_b128 v[182:185], v238 offset:21504
	ds_read_b128 v[186:189], v238 offset:22528
	ds_read_b128 v[190:193], v238 offset:23552
	buffer_load_dwordx4 v207, s[40:43], s12 offen lds
	s_mov_b32 m0, s62
	s_add_i32 s36, s12, 0x80000
	buffer_load_dwordx4 v224, s[40:43], s12 offen lds
	s_mov_b32 m0, s63
	s_sub_i32 s13, s13, s4
	buffer_load_dwordx4 v207, s[40:43], s36 offen lds
	s_mov_b32 m0, s71
	s_nop 0
	buffer_load_dwordx4 v224, s[40:43], s36 offen lds
	s_mov_b32 m0, s53
	s_nop 0
	buffer_load_dwordx4 v195, s[4:7], s13 offen lds
	s_waitcnt vmcnt(7)
	s_waitcnt lgkmcnt(0)
	s_setprio 1
	s_barrier
	v_mfma_f32_16x16x32_bf16 v[62:65], v[130:133], v[162:165], v[62:65]
	v_mfma_f32_16x16x32_bf16 v[58:61], v[138:141], v[162:165], v[58:61]
	v_mfma_f32_16x16x32_bf16 v[42:45], v[138:141], v[170:173], v[42:45]
	v_mfma_f32_16x16x32_bf16 v[46:49], v[130:133], v[170:173], v[46:49]
	v_mfma_f32_16x16x32_bf16 v[30:33], v[130:133], v[178:181], v[30:33]
	v_mfma_f32_16x16x32_bf16 v[26:29], v[138:141], v[178:181], v[26:29]
	v_mfma_f32_16x16x32_bf16 v[10:13], v[138:141], v[186:189], v[10:13]
	v_mfma_f32_16x16x32_bf16 v[14:17], v[130:133], v[186:189], v[14:17]
	v_mfma_f32_16x16x32_bf16 v[62:65], v[134:137], v[166:169], v[62:65]
	v_mfma_f32_16x16x32_bf16 v[58:61], v[142:145], v[166:169], v[58:61]
	v_mfma_f32_16x16x32_bf16 v[42:45], v[142:145], v[174:177], v[42:45]
	v_mfma_f32_16x16x32_bf16 v[46:49], v[134:137], v[174:177], v[46:49]
	v_mfma_f32_16x16x32_bf16 v[30:33], v[134:137], v[182:185], v[30:33]
	v_mfma_f32_16x16x32_bf16 v[26:29], v[142:145], v[182:185], v[26:29]
	v_mfma_f32_16x16x32_bf16 v[10:13], v[142:145], v[190:193], v[10:13]
	v_mfma_f32_16x16x32_bf16 v[14:17], v[134:137], v[190:193], v[14:17]
	v_mfma_f32_16x16x32_bf16 v[54:57], v[146:149], v[162:165], v[54:57]
	v_mfma_f32_16x16x32_bf16 v[50:53], v[154:157], v[162:165], v[50:53]
	v_mfma_f32_16x16x32_bf16 v[34:37], v[154:157], v[170:173], v[34:37]
	v_mfma_f32_16x16x32_bf16 v[38:41], v[146:149], v[170:173], v[38:41]
	v_mfma_f32_16x16x32_bf16 v[22:25], v[146:149], v[178:181], v[22:25]
	v_mfma_f32_16x16x32_bf16 v[18:21], v[154:157], v[178:181], v[18:21]
	v_mfma_f32_16x16x32_bf16 v[2:5], v[154:157], v[186:189], v[2:5]
	v_mfma_f32_16x16x32_bf16 v[6:9], v[146:149], v[186:189], v[6:9]
	v_mfma_f32_16x16x32_bf16 v[54:57], v[150:153], v[166:169], v[54:57]
	v_mfma_f32_16x16x32_bf16 v[50:53], v[158:161], v[166:169], v[50:53]
	v_mfma_f32_16x16x32_bf16 v[34:37], v[158:161], v[174:177], v[34:37]
	v_mfma_f32_16x16x32_bf16 v[38:41], v[150:153], v[174:177], v[38:41]
	v_mfma_f32_16x16x32_bf16 v[22:25], v[150:153], v[182:185], v[22:25]
	v_mfma_f32_16x16x32_bf16 v[18:21], v[158:161], v[182:185], v[18:21]
	v_mfma_f32_16x16x32_bf16 v[2:5], v[158:161], v[190:193], v[2:5]
	v_mfma_f32_16x16x32_bf16 v[6:9], v[150:153], v[190:193], v[6:9]
	s_barrier
	s_setprio 0
	v_add_u32_e32 v0, 0x18000, v237
	ds_read_b128 v[130:133], v0
	ds_read_b128 v[134:137], v0 offset:1024
	ds_read_b128 v[138:141], v0 offset:2048
	ds_read_b128 v[142:145], v0 offset:3072
	v_add_u32_e32 v0, 0x1c000, v237
	ds_read_b128 v[146:149], v0
	ds_read_b128 v[150:153], v0 offset:1024
	ds_read_b128 v[154:157], v0 offset:2048
	ds_read_b128 v[158:161], v0 offset:3072
	s_add_i32 s36, s13, 0x80000
	s_mov_b32 m0, s73
	ds_read_b128 v[162:165], v238 offset:32768
	ds_read_b128 v[166:169], v238 offset:33792
	ds_read_b128 v[170:173], v238 offset:34816
	ds_read_b128 v[174:177], v238 offset:35840
	ds_read_b128 v[178:181], v238 offset:36864
	ds_read_b128 v[182:185], v238 offset:37888
	ds_read_b128 v[186:189], v238 offset:38912
	ds_read_b128 v[190:193], v238 offset:39936
	s_mov_b32 m0, s72
	s_nop 0
	buffer_load_dwordx4 v211, s[4:7], s13 offen lds
	s_mov_b32 m0, s73
	s_nop 0
	buffer_load_dwordx4 v195, s[4:7], s36 offen lds
	s_mov_b32 m0, s74
	s_nop 0
	buffer_load_dwordx4 v211, s[4:7], s36 offen lds
	s_waitcnt vmcnt(8)
	s_waitcnt lgkmcnt(0)
	s_setprio 1
	s_barrier
	v_mfma_f32_16x16x32_bf16 v[126:129], v[130:133], v[162:165], v[126:129]
	v_mfma_f32_16x16x32_bf16 v[122:125], v[138:141], v[162:165], v[122:125]
	v_mfma_f32_16x16x32_bf16 v[106:109], v[138:141], v[170:173], v[106:109]
	v_mfma_f32_16x16x32_bf16 v[110:113], v[130:133], v[170:173], v[110:113]
	v_mfma_f32_16x16x32_bf16 v[94:97], v[130:133], v[178:181], v[94:97]
	v_mfma_f32_16x16x32_bf16 v[90:93], v[138:141], v[178:181], v[90:93]
	v_mfma_f32_16x16x32_bf16 v[74:77], v[138:141], v[186:189], v[74:77]
	v_mfma_f32_16x16x32_bf16 v[78:81], v[130:133], v[186:189], v[78:81]
	v_mfma_f32_16x16x32_bf16 v[126:129], v[134:137], v[166:169], v[126:129]
	v_mfma_f32_16x16x32_bf16 v[122:125], v[142:145], v[166:169], v[122:125]
	v_mfma_f32_16x16x32_bf16 v[106:109], v[142:145], v[174:177], v[106:109]
	v_mfma_f32_16x16x32_bf16 v[110:113], v[134:137], v[174:177], v[110:113]
	v_mfma_f32_16x16x32_bf16 v[94:97], v[134:137], v[182:185], v[94:97]
	v_mfma_f32_16x16x32_bf16 v[90:93], v[142:145], v[182:185], v[90:93]
	v_mfma_f32_16x16x32_bf16 v[74:77], v[142:145], v[190:193], v[74:77]
	v_mfma_f32_16x16x32_bf16 v[78:81], v[134:137], v[190:193], v[78:81]
	v_mfma_f32_16x16x32_bf16 v[118:121], v[146:149], v[162:165], v[118:121]
	v_mfma_f32_16x16x32_bf16 v[114:117], v[154:157], v[162:165], v[114:117]
	v_mfma_f32_16x16x32_bf16 v[98:101], v[154:157], v[170:173], v[98:101]
	v_mfma_f32_16x16x32_bf16 v[102:105], v[146:149], v[170:173], v[102:105]
	v_mfma_f32_16x16x32_bf16 v[86:89], v[146:149], v[178:181], v[86:89]
	v_mfma_f32_16x16x32_bf16 v[82:85], v[154:157], v[178:181], v[82:85]
	v_mfma_f32_16x16x32_bf16 v[66:69], v[154:157], v[186:189], v[66:69]
	v_mfma_f32_16x16x32_bf16 v[70:73], v[146:149], v[186:189], v[70:73]
	v_mfma_f32_16x16x32_bf16 v[118:121], v[150:153], v[166:169], v[118:121]
	v_mfma_f32_16x16x32_bf16 v[114:117], v[158:161], v[166:169], v[114:117]
	v_mfma_f32_16x16x32_bf16 v[98:101], v[158:161], v[174:177], v[98:101]
	v_mfma_f32_16x16x32_bf16 v[102:105], v[150:153], v[174:177], v[102:105]
	v_mfma_f32_16x16x32_bf16 v[86:89], v[150:153], v[182:185], v[86:89]
	v_mfma_f32_16x16x32_bf16 v[82:85], v[158:161], v[182:185], v[82:85]
	v_mfma_f32_16x16x32_bf16 v[66:69], v[158:161], v[190:193], v[66:69]
	v_mfma_f32_16x16x32_bf16 v[70:73], v[150:153], v[190:193], v[70:73]
	s_barrier
; #define PG8_STAGE(bufoff, gbase, voff) do { const int so_ = (int)(unsigned)((const char*)(gbase) - base_##voff); _Pragma("unroll") for (int _i = 0; _i < 2; ++_i) \
;         __builtin_amdgcn_raw_ptr_buffer_load_lds(rs_##voff, (PG8_LAS unsigned*)(lds + (bufoff) + ldsw + _i * 8192), 16, (int)(voff)[_i], so_, 0, 0); } while (0)
; #define PG8_LDA(dst, b, h) do { _Pragma("unroll") for (int m = 0; m < 4; ++m) _Pragma("unroll") for (int k = 0; k < 2; ++k) dst[m][k] = *(const PG8_LAS bf16x8*)(lds + PG8_SA(b, h) + aoff + m * 2048 + k * 1024); } while (0)
; #define PG8_LDB(dst, b, h) do { _Pragma("unroll") for (int n = 0; n < 2; ++n) _Pragma("unroll") for (int k = 0; k < 2; ++k) dst[n][k] = *(const PG8_LAS bf16x8*)(lds + PG8_SB(b, h) + boff + n * 2048 + k * 1024); } while (0)
; #define PG8_MMA(ai, bj, At, Bt) do { __builtin_amdgcn_s_setprio(1); _Pragma("unroll") for (int m = 0; m < 4; ++m) _Pragma("unroll") for (int n = 0; n < 2; ++n) _Pragma("unroll") for (int k = 0; k < 2; ++k) \
;         acc[ai][bj][m][n] = __builtin_amdgcn_mfma_f32_16x16x32_bf16(Bt[n][k], At[m][k], acc[ai][bj][m][n], 0, 0, 0); __builtin_amdgcn_s_setprio(0); } while (0)
; template <class Epi, class Sched, bool ALIGN_EPI = false, bool SP2 = false>
; __device__ __forceinline__ void gemm_phase(PG8_LAS unsigned char* lds, const Gemm g, const Sched& S, const Epi& E, int tid_in) {
;     ...
;             PG8_LDB(B0, 0, 0); PG8_LDB(B1, 0, 1); PG8_SCHED; PG8_LDA(At, 0, 0); PG8_STAGE(PG8_SA(1, 1), a1 + hstepA, voffA);
;             PG8_WAIT_V(8); PG8_WAIT_L(0); PG8_BAR; PG8_MMA(0, 0, At, B0); PG8_MMA(0, 1, At, B1); PG8_BAR; PG8_SCHED;
;             PG8_LDA(At, 0, 1); PG8_STAGE(PG8_SB(0, 0), b2, voffB); PG8_STAGE(PG8_SB(0, 1), b2 + hstepB, voffB); PG8_STAGE(PG8_SA(0, 0), a2, voffA);
;             PG8_WAIT_V(8); PG8_WAIT_L(0); PG8_BAR; PG8_MMA(1, 0, At, B0); PG8_MMA(1, 1, At, B1); PG8_BAR; PG8_SCHED;
;             PG8_LDB(B0, 1, 0); PG8_LDB(B1, 1, 1); PG8_SCHED; PG8_LDA(At, 1, 0); PG8_STAGE(PG8_SA(0, 1), a2 + hstepA, voffA);
;             PG8_WAIT_V(8); PG8_WAIT_L(0); PG8_BAR; PG8_MMA(0, 0, At, B0); PG8_MMA(0, 1, At, B1); PG8_BAR; PG8_SCHED;
;             PG8_LDA(At, 1, 1); PG8_STAGE(PG8_SB(1, 0), b3, voffB); PG8_STAGE(PG8_SB(1, 1), b3 + hstepB, voffB); PG8_STAGE(PG8_SA(1, 0), a3, voffA);
;             PG8_WAIT_V(8); PG8_WAIT_L(0); PG8_BAR; PG8_MMA(1, 0, At, B0); PG8_MMA(1, 1, At, B1); PG8_BAR; PG8_SCHED;
	s_setprio 0
	s_mov_b32 m0, s75
	s_add_i32 s36, s12, 0x80
	ds_read_b128 v[162:165], v238 offset:49152
	ds_read_b128 v[166:169], v238 offset:50176
	ds_read_b128 v[170:173], v238 offset:51200
	ds_read_b128 v[174:177], v238 offset:52224
	ds_read_b128 v[178:181], v238 offset:53248
	ds_read_b128 v[182:185], v238 offset:54272
	ds_read_b128 v[186:189], v238 offset:55296
	ds_read_b128 v[190:193], v238 offset:56320
	buffer_load_dwordx4 v207, s[40:43], s36 offen lds
	s_mov_b32 m0, s76
	s_add_i32 s12, s12, 0x80080
	buffer_load_dwordx4 v224, s[40:43], s36 offen lds
	s_mov_b32 m0, s79
	s_addk_i32 s13, 0x80
	buffer_load_dwordx4 v207, s[40:43], s12 offen lds
	s_mov_b32 m0, s68
	s_nop 0
	buffer_load_dwordx4 v224, s[40:43], s12 offen lds
	s_mov_b32 m0, s77
	s_nop 0
	buffer_load_dwordx4 v195, s[4:7], s13 offen lds
	s_waitcnt vmcnt(7)
	s_waitcnt lgkmcnt(0)
	s_setprio 1
	s_barrier
	v_mfma_f32_16x16x32_bf16 v[62:65], v[130:133], v[162:165], v[62:65]
	v_mfma_f32_16x16x32_bf16 v[58:61], v[138:141], v[162:165], v[58:61]
	v_mfma_f32_16x16x32_bf16 v[42:45], v[138:141], v[170:173], v[42:45]
	v_mfma_f32_16x16x32_bf16 v[46:49], v[130:133], v[170:173], v[46:49]
	v_mfma_f32_16x16x32_bf16 v[30:33], v[130:133], v[178:181], v[30:33]
	v_mfma_f32_16x16x32_bf16 v[26:29], v[138:141], v[178:181], v[26:29]
	v_mfma_f32_16x16x32_bf16 v[10:13], v[138:141], v[186:189], v[10:13]
	v_mfma_f32_16x16x32_bf16 v[14:17], v[130:133], v[186:189], v[14:17]
	v_mfma_f32_16x16x32_bf16 v[62:65], v[134:137], v[166:169], v[62:65]
	v_mfma_f32_16x16x32_bf16 v[58:61], v[142:145], v[166:169], v[58:61]
	v_mfma_f32_16x16x32_bf16 v[42:45], v[142:145], v[174:177], v[42:45]
	v_mfma_f32_16x16x32_bf16 v[46:49], v[134:137], v[174:177], v[46:49]
	v_mfma_f32_16x16x32_bf16 v[30:33], v[134:137], v[182:185], v[30:33]
	v_mfma_f32_16x16x32_bf16 v[26:29], v[142:145], v[182:185], v[26:29]
	v_mfma_f32_16x16x32_bf16 v[10:13], v[142:145], v[190:193], v[10:13]
	v_mfma_f32_16x16x32_bf16 v[14:17], v[134:137], v[190:193], v[14:17]
	v_mfma_f32_16x16x32_bf16 v[54:57], v[146:149], v[162:165], v[54:57]
	v_mfma_f32_16x16x32_bf16 v[50:53], v[154:157], v[162:165], v[50:53]
	v_mfma_f32_16x16x32_bf16 v[34:37], v[154:157], v[170:173], v[34:37]
	v_mfma_f32_16x16x32_bf16 v[38:41], v[146:149], v[170:173], v[38:41]
	v_mfma_f32_16x16x32_bf16 v[22:25], v[146:149], v[178:181], v[22:25]
	v_mfma_f32_16x16x32_bf16 v[18:21], v[154:157], v[178:181], v[18:21]
	v_mfma_f32_16x16x32_bf16 v[2:5], v[154:157], v[186:189], v[2:5]
	v_mfma_f32_16x16x32_bf16 v[6:9], v[146:149], v[186:189], v[6:9]
	v_mfma_f32_16x16x32_bf16 v[54:57], v[150:153], v[166:169], v[54:57]
	v_mfma_f32_16x16x32_bf16 v[50:53], v[158:161], v[166:169], v[50:53]
	v_mfma_f32_16x16x32_bf16 v[34:37], v[158:161], v[174:177], v[34:37]
	v_mfma_f32_16x16x32_bf16 v[38:41], v[150:153], v[174:177], v[38:41]
	v_mfma_f32_16x16x32_bf16 v[22:25], v[150:153], v[182:185], v[22:25]
	v_mfma_f32_16x16x32_bf16 v[18:21], v[158:161], v[182:185], v[18:21]
	v_mfma_f32_16x16x32_bf16 v[2:5], v[158:161], v[190:193], v[2:5]
	v_mfma_f32_16x16x32_bf16 v[6:9], v[150:153], v[190:193], v[6:9]
	s_barrier
	s_setprio 0
	s_add_i32 s23, s23, 2
	s_add_u32 s20, s20, 0x100
	s_addc_u32 s21, s21, 0
	s_cmp_gt_u32 s23, 29
	s_mov_b64 s[12:13], s[16:17]
	s_cbranch_scc0 .LBB0_312
	s_branch .Lyng_after0
.Lyng_loop0:
	v_add_u32_e32 v0, 0x10000, v237
	ds_read_b128 v[130:133], v0
	ds_read_b128 v[134:137], v0 offset:1024
	ds_read_b128 v[138:141], v0 offset:2048
	ds_read_b128 v[142:145], v0 offset:3072
	v_add_u32_e32 v0, 0x14000, v237
	ds_read_b128 v[146:149], v0
	ds_read_b128 v[150:153], v0 offset:1024
	ds_read_b128 v[154:157], v0 offset:2048
	ds_read_b128 v[158:161], v0 offset:3072
	s_add_u32 s16, s12, 0x100
	s_addc_u32 s17, s13, 0
	s_sub_i32 s12, s12, s4
	s_add_i32 s12, s12, 0x80080
	s_sub_i32 s36, s12, 0x80000
	s_cmp_eq_u32 s23, 28
	s_cselect_b32 s13, s19, s16
	s_mov_b32 m0, s69
	ds_read_b128 v[162:165], v238
	ds_read_b128 v[166:169], v238 offset:1024
	ds_read_b128 v[170:173], v238 offset:2048
	ds_read_b128 v[174:177], v238 offset:3072
	ds_read_b128 v[178:181], v238 offset:4096
	ds_read_b128 v[182:185], v238 offset:5120
	ds_read_b128 v[186:189], v238 offset:6144
	ds_read_b128 v[190:193], v238 offset:7168
	s_mov_b32 m0, s78
	s_nop 0
	buffer_load_dwordx4 v211, s[4:7], s36 offen lds
	s_mov_b32 m0, s69
	s_nop 0
	buffer_load_dwordx4 v195, s[4:7], s12 offen lds
	s_mov_b32 m0, s67
	s_nop 0
	buffer_load_dwordx4 v211, s[4:7], s12 offen lds
	s_waitcnt vmcnt(8)
	s_waitcnt lgkmcnt(0)
	s_setprio 2
	s_barrier
	v_mfma_f32_16x16x32_bf16 v[126:129], v[130:133], v[162:165], v[126:129]
	v_mfma_f32_16x16x32_bf16 v[122:125], v[138:141], v[162:165], v[122:125]
	v_mfma_f32_16x16x32_bf16 v[106:109], v[138:141], v[170:173], v[106:109]
	v_mfma_f32_16x16x32_bf16 v[110:113], v[130:133], v[170:173], v[110:113]
	v_mfma_f32_16x16x32_bf16 v[94:97], v[130:133], v[178:181], v[94:97]
	v_mfma_f32_16x16x32_bf16 v[90:93], v[138:141], v[178:181], v[90:93]
	v_mfma_f32_16x16x32_bf16 v[74:77], v[138:141], v[186:189], v[74:77]
	v_mfma_f32_16x16x32_bf16 v[78:81], v[130:133], v[186:189], v[78:81]
	v_mfma_f32_16x16x32_bf16 v[126:129], v[134:137], v[166:169], v[126:129]
	v_mfma_f32_16x16x32_bf16 v[122:125], v[142:145], v[166:169], v[122:125]
	v_mfma_f32_16x16x32_bf16 v[106:109], v[142:145], v[174:177], v[106:109]
	v_mfma_f32_16x16x32_bf16 v[110:113], v[134:137], v[174:177], v[110:113]
	v_mfma_f32_16x16x32_bf16 v[94:97], v[134:137], v[182:185], v[94:97]
	v_mfma_f32_16x16x32_bf16 v[90:93], v[142:145], v[182:185], v[90:93]
	v_mfma_f32_16x16x32_bf16 v[74:77], v[142:145], v[190:193], v[74:77]
	v_mfma_f32_16x16x32_bf16 v[78:81], v[134:137], v[190:193], v[78:81]
	v_mfma_f32_16x16x32_bf16 v[118:121], v[146:149], v[162:165], v[118:121]
	v_mfma_f32_16x16x32_bf16 v[114:117], v[154:157], v[162:165], v[114:117]
	v_mfma_f32_16x16x32_bf16 v[98:101], v[154:157], v[170:173], v[98:101]
	v_mfma_f32_16x16x32_bf16 v[102:105], v[146:149], v[170:173], v[102:105]
	v_mfma_f32_16x16x32_bf16 v[86:89], v[146:149], v[178:181], v[86:89]
	v_mfma_f32_16x16x32_bf16 v[82:85], v[154:157], v[178:181], v[82:85]
	v_mfma_f32_16x16x32_bf16 v[66:69], v[154:157], v[186:189], v[66:69]
	v_mfma_f32_16x16x32_bf16 v[70:73], v[146:149], v[186:189], v[70:73]
	v_mfma_f32_16x16x32_bf16 v[118:121], v[150:153], v[166:169], v[118:121]
	v_mfma_f32_16x16x32_bf16 v[114:117], v[158:161], v[166:169], v[114:117]
	v_mfma_f32_16x16x32_bf16 v[98:101], v[158:161], v[174:177], v[98:101]
	v_mfma_f32_16x16x32_bf16 v[102:105], v[150:153], v[174:177], v[102:105]
	v_mfma_f32_16x16x32_bf16 v[86:89], v[150:153], v[182:185], v[86:89]
	v_mfma_f32_16x16x32_bf16 v[82:85], v[158:161], v[182:185], v[82:85]
	v_mfma_f32_16x16x32_bf16 v[66:69], v[158:161], v[190:193], v[66:69]
	v_mfma_f32_16x16x32_bf16 v[70:73], v[150:153], v[190:193], v[70:73]
	s_barrier
; #define PG8_STAGE(bufoff, gbase, voff) do { const int so_ = (int)(unsigned)((const char*)(gbase) - base_##voff); _Pragma("unroll") for (int _i = 0; _i < 2; ++_i) \
;         __builtin_amdgcn_raw_ptr_buffer_load_lds(rs_##voff, (PG8_LAS unsigned*)(lds + (bufoff) + ldsw + _i * 8192), 16, (int)(voff)[_i], so_, 0, 0); } while (0)
; #define PG8_LDA(dst, b, h) do { _Pragma("unroll") for (int m = 0; m < 4; ++m) _Pragma("unroll") for (int k = 0; k < 2; ++k) dst[m][k] = *(const PG8_LAS bf16x8*)(lds + PG8_SA(b, h) + aoff + m * 2048 + k * 1024); } while (0)
; #define PG8_LDB(dst, b, h) do { _Pragma("unroll") for (int n = 0; n < 2; ++n) _Pragma("unroll") for (int k = 0; k < 2; ++k) dst[n][k] = *(const PG8_LAS bf16x8*)(lds + PG8_SB(b, h) + boff + n * 2048 + k * 1024); } while (0)
; #define PG8_MMA(ai, bj, At, Bt) do { __builtin_amdgcn_s_setprio(1); _Pragma("unroll") for (int m = 0; m < 4; ++m) _Pragma("unroll") for (int n = 0; n < 2; ++n) _Pragma("unroll") for (int k = 0; k < 2; ++k) \
;         acc[ai][bj][m][n] = __builtin_amdgcn_mfma_f32_16x16x32_bf16(Bt[n][k], At[m][k], acc[ai][bj][m][n], 0, 0, 0); __builtin_amdgcn_s_setprio(0); } while (0)
; #define PG8_WAIT_V(n) asm volatile("s_waitcnt vmcnt(" #n ")" ::: "memory")
; #define PG8_WAIT_L(n) asm volatile("s_waitcnt lgkmcnt(" #n ")" ::: "memory")
; #define PG8_BAR __builtin_amdgcn_s_barrier()
; #define PG8_SCHED __builtin_amdgcn_sched_barrier(0)
; template <class Epi, class Sched, bool ALIGN_EPI = false, bool SP2 = false>
; __device__ __forceinline__ void gemm_phase(PG8_LAS unsigned char* lds, const Gemm g, const Sched& S, const Epi& E, int tid_in) {
;     ...
;             PG8_LDA(At, 0, 1); PG8_STAGE(PG8_SB(0, 0), b2, voffB); PG8_STAGE(PG8_SB(0, 1), b2 + hstepB, voffB); PG8_STAGE(PG8_SA(0, 0), a2, voffA);
;             PG8_WAIT_V(8); PG8_WAIT_L(0); PG8_BAR; PG8_MMA(1, 0, At, B0); PG8_MMA(1, 1, At, B1); PG8_BAR; PG8_SCHED;
;             PG8_LDB(B0, 1, 0); PG8_LDB(B1, 1, 1); PG8_SCHED; PG8_LDA(At, 1, 0); PG8_STAGE(PG8_SA(0, 1), a2 + hstepA, voffA);
;             PG8_WAIT_V(8); PG8_WAIT_L(0); PG8_BAR; PG8_MMA(0, 0, At, B0); PG8_MMA(0, 1, At, B1); PG8_BAR; PG8_SCHED;
	s_setprio 1
	s_cselect_b32 s12, s15, s20
	s_mov_b32 m0, s61
	s_mov_b32 s42, s6
	s_mov_b32 s43, s7
	s_sub_i32 s12, s12, s40
	ds_read_b128 v[162:165], v238 offset:16384
	ds_read_b128 v[166:169], v238 offset:17408
	ds_read_b128 v[170:173], v238 offset:18432
	ds_read_b128 v[174:177], v238 offset:19456
	ds_read_b128 v[178:181], v238 offset:20480
	ds_read_b128 v[182:185], v238 offset:21504
	ds_read_b128 v[186:189], v238 offset:22528
	ds_read_b128 v[190:193], v238 offset:23552
	buffer_load_dwordx4 v207, s[40:43], s12 offen lds
	s_mov_b32 m0, s62
	s_add_i32 s36, s12, 0x80000
	buffer_load_dwordx4 v224, s[40:43], s12 offen lds
	s_mov_b32 m0, s63
	s_sub_i32 s13, s13, s4
	buffer_load_dwordx4 v207, s[40:43], s36 offen lds
	s_mov_b32 m0, s71
	s_nop 0
	buffer_load_dwordx4 v224, s[40:43], s36 offen lds
	s_mov_b32 m0, s53
	s_nop 0
	buffer_load_dwordx4 v195, s[4:7], s13 offen lds
	s_waitcnt vmcnt(7)
	s_waitcnt lgkmcnt(0)
	s_setprio 2
	s_barrier
	v_mfma_f32_16x16x32_bf16 v[62:65], v[130:133], v[162:165], v[62:65]
	v_mfma_f32_16x16x32_bf16 v[58:61], v[138:141], v[162:165], v[58:61]
	v_mfma_f32_16x16x32_bf16 v[42:45], v[138:141], v[170:173], v[42:45]
	v_mfma_f32_16x16x32_bf16 v[46:49], v[130:133], v[170:173], v[46:49]
	v_mfma_f32_16x16x32_bf16 v[30:33], v[130:133], v[178:181], v[30:33]
	v_mfma_f32_16x16x32_bf16 v[26:29], v[138:141], v[178:181], v[26:29]
	v_mfma_f32_16x16x32_bf16 v[10:13], v[138:141], v[186:189], v[10:13]
	v_mfma_f32_16x16x32_bf16 v[14:17], v[130:133], v[186:189], v[14:17]
	v_mfma_f32_16x16x32_bf16 v[62:65], v[134:137], v[166:169], v[62:65]
	v_mfma_f32_16x16x32_bf16 v[58:61], v[142:145], v[166:169], v[58:61]
	v_mfma_f32_16x16x32_bf16 v[42:45], v[142:145], v[174:177], v[42:45]
	v_mfma_f32_16x16x32_bf16 v[46:49], v[134:137], v[174:177], v[46:49]
	v_mfma_f32_16x16x32_bf16 v[30:33], v[134:137], v[182:185], v[30:33]
	v_mfma_f32_16x16x32_bf16 v[26:29], v[142:145], v[182:185], v[26:29]
	v_mfma_f32_16x16x32_bf16 v[10:13], v[142:145], v[190:193], v[10:13]
	v_mfma_f32_16x16x32_bf16 v[14:17], v[134:137], v[190:193], v[14:17]
	v_mfma_f32_16x16x32_bf16 v[54:57], v[146:149], v[162:165], v[54:57]
	v_mfma_f32_16x16x32_bf16 v[50:53], v[154:157], v[162:165], v[50:53]
	v_mfma_f32_16x16x32_bf16 v[34:37], v[154:157], v[170:173], v[34:37]
	v_mfma_f32_16x16x32_bf16 v[38:41], v[146:149], v[170:173], v[38:41]
	v_mfma_f32_16x16x32_bf16 v[22:25], v[146:149], v[178:181], v[22:25]
	v_mfma_f32_16x16x32_bf16 v[18:21], v[154:157], v[178:181], v[18:21]
	v_mfma_f32_16x16x32_bf16 v[2:5], v[154:157], v[186:189], v[2:5]
	v_mfma_f32_16x16x32_bf16 v[6:9], v[146:149], v[186:189], v[6:9]
	v_mfma_f32_16x16x32_bf16 v[54:57], v[150:153], v[166:169], v[54:57]
	v_mfma_f32_16x16x32_bf16 v[50:53], v[158:161], v[166:169], v[50:53]
	v_mfma_f32_16x16x32_bf16 v[34:37], v[158:161], v[174:177], v[34:37]
	v_mfma_f32_16x16x32_bf16 v[38:41], v[150:153], v[174:177], v[38:41]
	v_mfma_f32_16x16x32_bf16 v[22:25], v[150:153], v[182:185], v[22:25]
	v_mfma_f32_16x16x32_bf16 v[18:21], v[158:161], v[182:185], v[18:21]
	v_mfma_f32_16x16x32_bf16 v[2:5], v[158:161], v[190:193], v[2:5]
	v_mfma_f32_16x16x32_bf16 v[6:9], v[150:153], v[190:193], v[6:9]
	s_barrier
	s_setprio 1
	v_add_u32_e32 v0, 0x18000, v237
	ds_read_b128 v[130:133], v0
	ds_read_b128 v[134:137], v0 offset:1024
	ds_read_b128 v[138:141], v0 offset:2048
	ds_read_b128 v[142:145], v0 offset:3072
	v_add_u32_e32 v0, 0x1c000, v237
	ds_read_b128 v[146:149], v0
	ds_read_b128 v[150:153], v0 offset:1024
	ds_read_b128 v[154:157], v0 offset:2048
	ds_read_b128 v[158:161], v0 offset:3072
	s_add_i32 s36, s13, 0x80000
	s_mov_b32 m0, s73
	ds_read_b128 v[162:165], v238 offset:32768
	ds_read_b128 v[166:169], v238 offset:33792
	ds_read_b128 v[170:173], v238 offset:34816
	ds_read_b128 v[174:177], v238 offset:35840
	ds_read_b128 v[178:181], v238 offset:36864
	ds_read_b128 v[182:185], v238 offset:37888
	ds_read_b128 v[186:189], v238 offset:38912
	ds_read_b128 v[190:193], v238 offset:39936
	s_mov_b32 m0, s72
	s_nop 0
	buffer_load_dwordx4 v211, s[4:7], s13 offen lds
	s_mov_b32 m0, s73
	s_nop 0
	buffer_load_dwordx4 v195, s[4:7], s36 offen lds
	s_mov_b32 m0, s74
	s_nop 0
	buffer_load_dwordx4 v211, s[4:7], s36 offen lds
	s_waitcnt vmcnt(8)
	s_waitcnt lgkmcnt(0)
	s_setprio 2
	s_barrier
; #define PG8_STAGE(bufoff, gbase, voff) do { const int so_ = (int)(unsigned)((const char*)(gbase) - base_##voff); _Pragma("unroll") for (int _i = 0; _i < 2; ++_i) \
;         __builtin_amdgcn_raw_ptr_buffer_load_lds(rs_##voff, (PG8_LAS unsigned*)(lds + (bufoff) + ldsw + _i * 8192), 16, (int)(voff)[_i], so_, 0, 0); } while (0)
; #define PG8_WAIT_V(n) asm volatile("s_waitcnt vmcnt(" #n ")" ::: "memory")
; template <class Epi, class Sched, bool ALIGN_EPI = false, bool SP2 = false>
; __device__ __forceinline__ void gemm_phase(PG8_LAS unsigned char* lds, const Gemm g, const Sched& S, const Epi& E, int tid_in) {
;     ...
;             PG8_WAIT_V(8); PG8_WAIT_L(0); PG8_BAR; PG8_MMA(0, 0, At, B0); PG8_MMA(0, 1, At, B1); PG8_BAR; PG8_SCHED;
;             PG8_LDA(At, 1, 1); PG8_STAGE(PG8_SB(1, 0), b3, voffB); PG8_STAGE(PG8_SB(1, 1), b3 + hstepB, voffB); PG8_STAGE(PG8_SA(1, 0), a3, voffA);
;             PG8_WAIT_V(8); PG8_WAIT_L(0); PG8_BAR; PG8_MMA(1, 0, At, B0); PG8_MMA(1, 1, At, B1); PG8_BAR; PG8_SCHED;
;             } else {
;             PG8_LDB(B0, 0, 0); PG8_SCHED; PG8_LDA(At, 0, 0); PG8_STAGE(PG8_SA(1, 1), a1 + hstepA, voffA);
;             PG8_WAIT_L(8); PG8_BAR; PG8_WAIT_L(0); PG8_MMA(0, 0, At, B0); PG8_BAR; PG8_SCHED;
;             PG8_LDB(B1, 0, 1); PG8_STAGE(PG8_SB(0, 0), b2, voffB);
;             PG8_BAR; PG8_WAIT_L(0); PG8_MMA(0, 1, At, B1); PG8_BAR;
;             PG8_LDA(At, 0, 1); PG8_STAGE(PG8_SA(0, 0), a2, voffA);
;             PG8_BAR; PG8_WAIT_L(0); PG8_MMA(1, 0, At, B0); PG8_BAR; PG8_SCHED;
;             PG8_STAGE(PG8_SB(0, 1), b2 + hstepB, voffB);
;             PG8_WAIT_V(6); PG8_BAR; PG8_MMA(1, 1, At, B1); PG8_BAR;
;             PG8_LDB(B0, 1, 0); PG8_SCHED; PG8_LDA(At, 1, 0); PG8_STAGE(PG8_SA(0, 1), a2 + hstepA, voffA);
;             PG8_WAIT_L(8); PG8_BAR; PG8_WAIT_L(0); PG8_MMA(0, 0, At, B0); PG8_BAR; PG8_SCHED;
;             PG8_LDB(B1, 1, 1); PG8_STAGE(PG8_SB(1, 0), b3, voffB);
;             PG8_BAR; PG8_WAIT_L(0); PG8_MMA(0, 1, At, B1); PG8_BAR;
;             PG8_LDA(At, 1, 1); PG8_STAGE(PG8_SA(1, 0), a3, voffA);
;             PG8_BAR; PG8_WAIT_L(0); PG8_MMA(1, 0, At, B0); PG8_BAR; PG8_SCHED;
;             PG8_STAGE(PG8_SB(1, 1), b3 + hstepB, voffB);
;             PG8_WAIT_V(6); PG8_BAR; PG8_MMA(1, 1, At, B1); PG8_BAR;
;             }
;         }
;         if constexpr (ALIGN_EPI) { if (wr == 0) PG8_BAR; }
	v_mfma_f32_16x16x32_bf16 v[126:129], v[130:133], v[162:165], v[126:129]
	v_mfma_f32_16x16x32_bf16 v[122:125], v[138:141], v[162:165], v[122:125]
	v_mfma_f32_16x16x32_bf16 v[106:109], v[138:141], v[170:173], v[106:109]
	v_mfma_f32_16x16x32_bf16 v[110:113], v[130:133], v[170:173], v[110:113]
	v_mfma_f32_16x16x32_bf16 v[94:97], v[130:133], v[178:181], v[94:97]
	v_mfma_f32_16x16x32_bf16 v[90:93], v[138:141], v[178:181], v[90:93]
	v_mfma_f32_16x16x32_bf16 v[74:77], v[138:141], v[186:189], v[74:77]
	v_mfma_f32_16x16x32_bf16 v[78:81], v[130:133], v[186:189], v[78:81]
	v_mfma_f32_16x16x32_bf16 v[126:129], v[134:137], v[166:169], v[126:129]
	v_mfma_f32_16x16x32_bf16 v[122:125], v[142:145], v[166:169], v[122:125]
	v_mfma_f32_16x16x32_bf16 v[106:109], v[142:145], v[174:177], v[106:109]
	v_mfma_f32_16x16x32_bf16 v[110:113], v[134:137], v[174:177], v[110:113]
	v_mfma_f32_16x16x32_bf16 v[94:97], v[134:137], v[182:185], v[94:97]
	v_mfma_f32_16x16x32_bf16 v[90:93], v[142:145], v[182:185], v[90:93]
	v_mfma_f32_16x16x32_bf16 v[74:77], v[142:145], v[190:193], v[74:77]
	v_mfma_f32_16x16x32_bf16 v[78:81], v[134:137], v[190:193], v[78:81]
	v_mfma_f32_16x16x32_bf16 v[118:121], v[146:149], v[162:165], v[118:121]
	v_mfma_f32_16x16x32_bf16 v[114:117], v[154:157], v[162:165], v[114:117]
	v_mfma_f32_16x16x32_bf16 v[98:101], v[154:157], v[170:173], v[98:101]
	v_mfma_f32_16x16x32_bf16 v[102:105], v[146:149], v[170:173], v[102:105]
	v_mfma_f32_16x16x32_bf16 v[86:89], v[146:149], v[178:181], v[86:89]
	v_mfma_f32_16x16x32_bf16 v[82:85], v[154:157], v[178:181], v[82:85]
	v_mfma_f32_16x16x32_bf16 v[66:69], v[154:157], v[186:189], v[66:69]
	v_mfma_f32_16x16x32_bf16 v[70:73], v[146:149], v[186:189], v[70:73]
	v_mfma_f32_16x16x32_bf16 v[118:121], v[150:153], v[166:169], v[118:121]
	v_mfma_f32_16x16x32_bf16 v[114:117], v[158:161], v[166:169], v[114:117]
	v_mfma_f32_16x16x32_bf16 v[98:101], v[158:161], v[174:177], v[98:101]
	v_mfma_f32_16x16x32_bf16 v[102:105], v[150:153], v[174:177], v[102:105]
	v_mfma_f32_16x16x32_bf16 v[86:89], v[150:153], v[182:185], v[86:89]
	v_mfma_f32_16x16x32_bf16 v[82:85], v[158:161], v[182:185], v[82:85]
	v_mfma_f32_16x16x32_bf16 v[66:69], v[158:161], v[190:193], v[66:69]
	v_mfma_f32_16x16x32_bf16 v[70:73], v[150:153], v[190:193], v[70:73]
	s_barrier
	s_setprio 1
	s_mov_b32 m0, s75
	s_add_i32 s36, s12, 0x80
	ds_read_b128 v[162:165], v238 offset:49152
	ds_read_b128 v[166:169], v238 offset:50176
	ds_read_b128 v[170:173], v238 offset:51200
	ds_read_b128 v[174:177], v238 offset:52224
	ds_read_b128 v[178:181], v238 offset:53248
	ds_read_b128 v[182:185], v238 offset:54272
	ds_read_b128 v[186:189], v238 offset:55296
	ds_read_b128 v[190:193], v238 offset:56320
	buffer_load_dwordx4 v207, s[40:43], s36 offen lds
	s_mov_b32 m0, s76
	s_add_i32 s12, s12, 0x80080
	buffer_load_dwordx4 v224, s[40:43], s36 offen lds
	s_mov_b32 m0, s79
	s_addk_i32 s13, 0x80
	buffer_load_dwordx4 v207, s[40:43], s12 offen lds
	s_mov_b32 m0, s68
	s_nop 0
	buffer_load_dwordx4 v224, s[40:43], s12 offen lds
	s_mov_b32 m0, s77
	s_nop 0
	buffer_load_dwordx4 v195, s[4:7], s13 offen lds
	s_waitcnt vmcnt(7)
	s_waitcnt lgkmcnt(0)
	s_setprio 2
	s_barrier
	v_mfma_f32_16x16x32_bf16 v[62:65], v[130:133], v[162:165], v[62:65]
	v_mfma_f32_16x16x32_bf16 v[58:61], v[138:141], v[162:165], v[58:61]
	v_mfma_f32_16x16x32_bf16 v[42:45], v[138:141], v[170:173], v[42:45]
	v_mfma_f32_16x16x32_bf16 v[46:49], v[130:133], v[170:173], v[46:49]
	v_mfma_f32_16x16x32_bf16 v[30:33], v[130:133], v[178:181], v[30:33]
	v_mfma_f32_16x16x32_bf16 v[26:29], v[138:141], v[178:181], v[26:29]
	v_mfma_f32_16x16x32_bf16 v[10:13], v[138:141], v[186:189], v[10:13]
	v_mfma_f32_16x16x32_bf16 v[14:17], v[130:133], v[186:189], v[14:17]
	v_mfma_f32_16x16x32_bf16 v[62:65], v[134:137], v[166:169], v[62:65]
	v_mfma_f32_16x16x32_bf16 v[58:61], v[142:145], v[166:169], v[58:61]
	v_mfma_f32_16x16x32_bf16 v[42:45], v[142:145], v[174:177], v[42:45]
	v_mfma_f32_16x16x32_bf16 v[46:49], v[134:137], v[174:177], v[46:49]
	v_mfma_f32_16x16x32_bf16 v[30:33], v[134:137], v[182:185], v[30:33]
	v_mfma_f32_16x16x32_bf16 v[26:29], v[142:145], v[182:185], v[26:29]
	v_mfma_f32_16x16x32_bf16 v[10:13], v[142:145], v[190:193], v[10:13]
	v_mfma_f32_16x16x32_bf16 v[14:17], v[134:137], v[190:193], v[14:17]
	v_mfma_f32_16x16x32_bf16 v[54:57], v[146:149], v[162:165], v[54:57]
	v_mfma_f32_16x16x32_bf16 v[50:53], v[154:157], v[162:165], v[50:53]
	v_mfma_f32_16x16x32_bf16 v[34:37], v[154:157], v[170:173], v[34:37]
	v_mfma_f32_16x16x32_bf16 v[38:41], v[146:149], v[170:173], v[38:41]
	v_mfma_f32_16x16x32_bf16 v[22:25], v[146:149], v[178:181], v[22:25]
	v_mfma_f32_16x16x32_bf16 v[18:21], v[154:157], v[178:181], v[18:21]
	v_mfma_f32_16x16x32_bf16 v[2:5], v[154:157], v[186:189], v[2:5]
	v_mfma_f32_16x16x32_bf16 v[6:9], v[146:149], v[186:189], v[6:9]
	v_mfma_f32_16x16x32_bf16 v[54:57], v[150:153], v[166:169], v[54:57]
	v_mfma_f32_16x16x32_bf16 v[50:53], v[158:161], v[166:169], v[50:53]
	v_mfma_f32_16x16x32_bf16 v[34:37], v[158:161], v[174:177], v[34:37]
	v_mfma_f32_16x16x32_bf16 v[38:41], v[150:153], v[174:177], v[38:41]
	v_mfma_f32_16x16x32_bf16 v[22:25], v[150:153], v[182:185], v[22:25]
	v_mfma_f32_16x16x32_bf16 v[18:21], v[158:161], v[182:185], v[18:21]
	v_mfma_f32_16x16x32_bf16 v[2:5], v[158:161], v[190:193], v[2:5]
	v_mfma_f32_16x16x32_bf16 v[6:9], v[150:153], v[190:193], v[6:9]
	s_barrier
	s_setprio 1
	s_add_i32 s23, s23, 2
	s_add_u32 s20, s20, 0x100
	s_addc_u32 s21, s21, 0
	s_cmp_gt_u32 s23, 29
	s_mov_b64 s[12:13], s[16:17]
	s_cbranch_scc0 .Lyng_loop0
	s_setprio 0
.Lyng_after0:
	s_and_b64 vcc, exec, s[48:49]
	s_cbranch_vccz .LBB0_315
	s_barrier

;     __host__ __device__ bool next(int i, Unit& u) const { const int t = i / 3, b = i - 3 * t; Unit v; if (!StaticOrder::next(t, v)) return false; u.pm = v.pm; u.pn = 8 * b + v.pn; return true; }
; #define PG8_STAGE(bufoff, gbase, voff) do { const int so_ = (int)(unsigned)((const char*)(gbase) - base_##voff); _Pragma("unroll") for (int _i = 0; _i < 2; ++_i) \
;         __builtin_amdgcn_raw_ptr_buffer_load_lds(rs_##voff, (PG8_LAS unsigned*)(lds + (bufoff) + ldsw + _i * 8192), 16, (int)(voff)[_i], so_, 0, 0); } while (0)
; #define PG8_LDA(dst, b, h) do { _Pragma("unroll") for (int m = 0; m < 4; ++m) _Pragma("unroll") for (int k = 0; k < 2; ++k) dst[m][k] = *(const PG8_LAS bf16x8*)(lds + PG8_SA(b, h) + aoff + m * 2048 + k * 1024); } while (0)
; #define PG8_WAIT_V(n) asm volatile("s_waitcnt vmcnt(" #n ")" ::: "memory")
; #define PG8_WAIT_L(n) asm volatile("s_waitcnt lgkmcnt(" #n ")" ::: "memory")
; #define PG8_BAR __builtin_amdgcn_s_barrier()
; template <class Epi, class Sched, bool ALIGN_EPI = false, bool SP2 = false>
; __device__ __forceinline__ void gemm_phase(PG8_LAS unsigned char* lds, const Gemm g, const Sched& S, const Epi& E, int tid_in) {
;     ...
;         const bool has_next = S.next(ui + 1, nxt);
;         const char* nA = has_next ? (const char*)g.A + (size_t)nxt.pm * tstepA + (g.grp ? (size_t)(nxt.pn / g.grp) * g.agrp : (size_t)0) : cA; const char* nB = has_next ? (const char*)g.Bt + (size_t)nxt.pn * tstepB : cB;
;         for (int t = 0; t < nt; t += 2) {
;             const bool last = (t == nt - 2);
;             const char* a1 = cA + (size_t)(t + 1) * kstep;
;             const char* a2 = last ? nA : cA + (size_t)(t + 2) * kstep; const char* b2 = last ? nB : cB + (size_t)(t + 2) * kstep;
;             const char* a3 = a2 + kstep; const char* b3 = b2 + kstep;
;             if (last && has_next) S.a_ready(nxt);
;             if constexpr (SP2) {
;             PG8_LDB(B0, 0, 0); PG8_LDB(B1, 0, 1); PG8_SCHED; PG8_LDA(At, 0, 0); PG8_STAGE(PG8_SA(1, 1), a1 + hstepA, voffA);
;             PG8_WAIT_V(8); PG8_WAIT_L(0); PG8_BAR; PG8_MMA(0, 0, At, B0); PG8_MMA(0, 1, At, B1); PG8_BAR; PG8_SCHED;
;             PG8_LDA(At, 0, 1); PG8_STAGE(PG8_SB(0, 0), b2, voffB); PG8_STAGE(PG8_SB(0, 1), b2 + hstepB, voffB); PG8_STAGE(PG8_SA(0, 0), a2, voffA);
;             PG8_WAIT_V(8); PG8_WAIT_L(0); PG8_BAR; PG8_MMA(1, 0, At, B0); PG8_MMA(1, 1, At, B1); PG8_BAR; PG8_SCHED;
.LBB0_1036:
	s_ashr_i32 s23, s22, 31
	s_lshl_b64 s[18:19], s[22:23], 19
	s_add_u32 s48, s44, s18
	s_addc_u32 s49, s20, s19
	s_and_b64 s[18:19], s[38:39], exec
	s_cselect_b32 s18, s48, s16
	s_add_u32 s19, s16, 0x100
	s_addc_u32 s23, s17, 0
	s_mov_b32 s38, -2
	s_cmpk_lt_u32 s59, 0x100
	s_cbranch_scc0 .Lyng_loop1
.LBB0_1037:
	v_add_u32_e32 v0, 0x10000, v236
	ds_read_b128 v[132:135], v0
	ds_read_b128 v[136:139], v0 offset:1024
	ds_read_b128 v[140:143], v0 offset:2048
	ds_read_b128 v[144:147], v0 offset:3072
	v_add_u32_e32 v0, 0x14000, v236
	ds_read_b128 v[148:151], v0
	ds_read_b128 v[152:155], v0 offset:1024
	ds_read_b128 v[156:159], v0 offset:2048
	ds_read_b128 v[160:163], v0 offset:3072
	s_add_u32 s16, s12, 0x100
	s_addc_u32 s17, s13, 0
	s_sub_i32 s12, s12, s4
	s_add_i32 s12, s12, 0xc0080
	s_sub_i32 s39, s12, 0xc0000
	s_cmp_eq_u32 s38, 12
	s_cselect_b32 s13, s24, s16
	s_mov_b32 m0, s76
	ds_read_b128 v[164:167], v237
	ds_read_b128 v[168:171], v237 offset:1024
	ds_read_b128 v[172:175], v237 offset:2048
	ds_read_b128 v[176:179], v237 offset:3072
	ds_read_b128 v[180:183], v237 offset:4096
	ds_read_b128 v[184:187], v237 offset:5120
	ds_read_b128 v[188:191], v237 offset:6144
	ds_read_b128 v[192:195], v237 offset:7168
	s_mov_b32 m0, s73
	s_nop 0
	buffer_load_dwordx4 v222, s[4:7], s39 offen lds
	s_mov_b32 m0, s76
	s_nop 0
	buffer_load_dwordx4 v220, s[4:7], s12 offen lds
	s_mov_b32 m0, s77
	s_nop 0
	buffer_load_dwordx4 v222, s[4:7], s12 offen lds
	s_waitcnt vmcnt(8)
	s_waitcnt lgkmcnt(0)
	s_setprio 1
	s_barrier
	v_mfma_f32_16x16x32_bf16 v[128:131], v[132:135], v[164:167], v[128:131]
	v_mfma_f32_16x16x32_bf16 v[124:127], v[140:143], v[164:167], v[124:127]
	v_mfma_f32_16x16x32_bf16 v[116:119], v[140:143], v[172:175], v[116:119]
	v_mfma_f32_16x16x32_bf16 v[120:123], v[132:135], v[172:175], v[120:123]
	v_mfma_f32_16x16x32_bf16 v[112:115], v[132:135], v[180:183], v[112:115]
	v_mfma_f32_16x16x32_bf16 v[108:111], v[140:143], v[180:183], v[108:111]
	v_mfma_f32_16x16x32_bf16 v[100:103], v[140:143], v[188:191], v[100:103]
	v_mfma_f32_16x16x32_bf16 v[104:107], v[132:135], v[188:191], v[104:107]
	v_mfma_f32_16x16x32_bf16 v[128:131], v[136:139], v[168:171], v[128:131]
	v_mfma_f32_16x16x32_bf16 v[124:127], v[144:147], v[168:171], v[124:127]
	v_mfma_f32_16x16x32_bf16 v[116:119], v[144:147], v[176:179], v[116:119]
	v_mfma_f32_16x16x32_bf16 v[120:123], v[136:139], v[176:179], v[120:123]
	v_mfma_f32_16x16x32_bf16 v[112:115], v[136:139], v[184:187], v[112:115]
	v_mfma_f32_16x16x32_bf16 v[108:111], v[144:147], v[184:187], v[108:111]
	v_mfma_f32_16x16x32_bf16 v[100:103], v[144:147], v[192:195], v[100:103]
	v_mfma_f32_16x16x32_bf16 v[104:107], v[136:139], v[192:195], v[104:107]
	v_mfma_f32_16x16x32_bf16 v[96:99], v[148:151], v[164:167], v[96:99]
	v_mfma_f32_16x16x32_bf16 v[92:95], v[156:159], v[164:167], v[92:95]
	v_mfma_f32_16x16x32_bf16 v[84:87], v[156:159], v[172:175], v[84:87]
	v_mfma_f32_16x16x32_bf16 v[88:91], v[148:151], v[172:175], v[88:91]
	v_mfma_f32_16x16x32_bf16 v[80:83], v[148:151], v[180:183], v[80:83]
	v_mfma_f32_16x16x32_bf16 v[76:79], v[156:159], v[180:183], v[76:79]
	v_mfma_f32_16x16x32_bf16 v[68:71], v[156:159], v[188:191], v[68:71]
	v_mfma_f32_16x16x32_bf16 v[72:75], v[148:151], v[188:191], v[72:75]
	v_mfma_f32_16x16x32_bf16 v[96:99], v[152:155], v[168:171], v[96:99]
	v_mfma_f32_16x16x32_bf16 v[92:95], v[160:163], v[168:171], v[92:95]
	v_mfma_f32_16x16x32_bf16 v[84:87], v[160:163], v[176:179], v[84:87]
	v_mfma_f32_16x16x32_bf16 v[88:91], v[152:155], v[176:179], v[88:91]
	v_mfma_f32_16x16x32_bf16 v[80:83], v[152:155], v[184:187], v[80:83]
	v_mfma_f32_16x16x32_bf16 v[76:79], v[160:163], v[184:187], v[76:79]
	v_mfma_f32_16x16x32_bf16 v[68:71], v[160:163], v[192:195], v[68:71]
	v_mfma_f32_16x16x32_bf16 v[72:75], v[152:155], v[192:195], v[72:75]
	s_barrier
	s_setprio 0
	s_cselect_b32 s12, s18, s19
	s_mov_b32 m0, s26
	s_mov_b32 s46, s6
	s_mov_b32 s47, s7
	s_sub_i32 s12, s12, s44
	ds_read_b128 v[164:167], v237 offset:16384
	ds_read_b128 v[168:171], v237 offset:17408
	ds_read_b128 v[172:175], v237 offset:18432
	ds_read_b128 v[176:179], v237 offset:19456
	ds_read_b128 v[180:183], v237 offset:20480
	ds_read_b128 v[184:187], v237 offset:21504
	ds_read_b128 v[188:191], v237 offset:22528
	ds_read_b128 v[192:195], v237 offset:23552
	buffer_load_dwordx4 v221, s[44:47], s12 offen lds
	s_mov_b32 m0, s53
	s_add_i32 s39, s12, 0x40000
	buffer_load_dwordx4 v223, s[44:47], s12 offen lds
	s_mov_b32 m0, s60
	s_sub_i32 s13, s13, s4
	buffer_load_dwordx4 v221, s[44:47], s39 offen lds
	s_mov_b32 m0, s61
	s_nop 0
	buffer_load_dwordx4 v223, s[44:47], s39 offen lds
	s_mov_b32 m0, s21
	s_nop 0
	buffer_load_dwordx4 v220, s[4:7], s13 offen lds
	s_waitcnt vmcnt(7)
	s_waitcnt lgkmcnt(0)
	s_setprio 1
	s_barrier
; #define PG8_STAGE(bufoff, gbase, voff) do { const int so_ = (int)(unsigned)((const char*)(gbase) - base_##voff); _Pragma("unroll") for (int _i = 0; _i < 2; ++_i) \
;         __builtin_amdgcn_raw_ptr_buffer_load_lds(rs_##voff, (PG8_LAS unsigned*)(lds + (bufoff) + ldsw + _i * 8192), 16, (int)(voff)[_i], so_, 0, 0); } while (0)
; #define PG8_LDA(dst, b, h) do { _Pragma("unroll") for (int m = 0; m < 4; ++m) _Pragma("unroll") for (int k = 0; k < 2; ++k) dst[m][k] = *(const PG8_LAS bf16x8*)(lds + PG8_SA(b, h) + aoff + m * 2048 + k * 1024); } while (0)
; #define PG8_LDB(dst, b, h) do { _Pragma("unroll") for (int n = 0; n < 2; ++n) _Pragma("unroll") for (int k = 0; k < 2; ++k) dst[n][k] = *(const PG8_LAS bf16x8*)(lds + PG8_SB(b, h) + boff + n * 2048 + k * 1024); } while (0)
; #define PG8_MMA(ai, bj, At, Bt) do { __builtin_amdgcn_s_setprio(1); _Pragma("unroll") for (int m = 0; m < 4; ++m) _Pragma("unroll") for (int n = 0; n < 2; ++n) _Pragma("unroll") for (int k = 0; k < 2; ++k) \
;         acc[ai][bj][m][n] = __builtin_amdgcn_mfma_f32_16x16x32_bf16(Bt[n][k], At[m][k], acc[ai][bj][m][n], 0, 0, 0); __builtin_amdgcn_s_setprio(0); } while (0)
; #define PG8_WAIT_V(n) asm volatile("s_waitcnt vmcnt(" #n ")" ::: "memory")
; #define PG8_WAIT_L(n) asm volatile("s_waitcnt lgkmcnt(" #n ")" ::: "memory")
; #define PG8_BAR __builtin_amdgcn_s_barrier()
; #define PG8_SCHED __builtin_amdgcn_sched_barrier(0)
; template <class Epi, class Sched, bool ALIGN_EPI = false, bool SP2 = false>
; __device__ __forceinline__ void gemm_phase(PG8_LAS unsigned char* lds, const Gemm g, const Sched& S, const Epi& E, int tid_in) {
;     ...
;             PG8_WAIT_V(8); PG8_WAIT_L(0); PG8_BAR; PG8_MMA(1, 0, At, B0); PG8_MMA(1, 1, At, B1); PG8_BAR; PG8_SCHED;
;             PG8_LDB(B0, 1, 0); PG8_LDB(B1, 1, 1); PG8_SCHED; PG8_LDA(At, 1, 0); PG8_STAGE(PG8_SA(0, 1), a2 + hstepA, voffA);
;             PG8_WAIT_V(8); PG8_WAIT_L(0); PG8_BAR; PG8_MMA(0, 0, At, B0); PG8_MMA(0, 1, At, B1); PG8_BAR; PG8_SCHED;
	v_mfma_f32_16x16x32_bf16 v[64:67], v[132:135], v[164:167], v[64:67]
	v_mfma_f32_16x16x32_bf16 v[60:63], v[140:143], v[164:167], v[60:63]
	v_mfma_f32_16x16x32_bf16 v[52:55], v[140:143], v[172:175], v[52:55]
	v_mfma_f32_16x16x32_bf16 v[56:59], v[132:135], v[172:175], v[56:59]
	v_mfma_f32_16x16x32_bf16 v[48:51], v[132:135], v[180:183], v[48:51]
	v_mfma_f32_16x16x32_bf16 v[44:47], v[140:143], v[180:183], v[44:47]
	v_mfma_f32_16x16x32_bf16 v[36:39], v[140:143], v[188:191], v[36:39]
	v_mfma_f32_16x16x32_bf16 v[40:43], v[132:135], v[188:191], v[40:43]
	v_mfma_f32_16x16x32_bf16 v[64:67], v[136:139], v[168:171], v[64:67]
	v_mfma_f32_16x16x32_bf16 v[60:63], v[144:147], v[168:171], v[60:63]
	v_mfma_f32_16x16x32_bf16 v[52:55], v[144:147], v[176:179], v[52:55]
	v_mfma_f32_16x16x32_bf16 v[56:59], v[136:139], v[176:179], v[56:59]
	v_mfma_f32_16x16x32_bf16 v[48:51], v[136:139], v[184:187], v[48:51]
	v_mfma_f32_16x16x32_bf16 v[44:47], v[144:147], v[184:187], v[44:47]
	v_mfma_f32_16x16x32_bf16 v[36:39], v[144:147], v[192:195], v[36:39]
	v_mfma_f32_16x16x32_bf16 v[40:43], v[136:139], v[192:195], v[40:43]
	v_mfma_f32_16x16x32_bf16 v[32:35], v[148:151], v[164:167], v[32:35]
	v_mfma_f32_16x16x32_bf16 v[28:31], v[156:159], v[164:167], v[28:31]
	v_mfma_f32_16x16x32_bf16 v[20:23], v[156:159], v[172:175], v[20:23]
	v_mfma_f32_16x16x32_bf16 v[24:27], v[148:151], v[172:175], v[24:27]
	v_mfma_f32_16x16x32_bf16 v[16:19], v[148:151], v[180:183], v[16:19]
	v_mfma_f32_16x16x32_bf16 v[12:15], v[156:159], v[180:183], v[12:15]
	v_mfma_f32_16x16x32_bf16 v[2:5], v[156:159], v[188:191], v[4:7]
	v_mfma_f32_16x16x32_bf16 v[8:11], v[148:151], v[188:191], v[8:11]
	v_mfma_f32_16x16x32_bf16 v[32:35], v[152:155], v[168:171], v[32:35]
	v_mfma_f32_16x16x32_bf16 v[28:31], v[160:163], v[168:171], v[28:31]
	v_mfma_f32_16x16x32_bf16 v[20:23], v[160:163], v[176:179], v[20:23]
	v_mfma_f32_16x16x32_bf16 v[24:27], v[152:155], v[176:179], v[24:27]
	v_mfma_f32_16x16x32_bf16 v[16:19], v[152:155], v[184:187], v[16:19]
	v_mfma_f32_16x16x32_bf16 v[12:15], v[160:163], v[184:187], v[12:15]
	v_mfma_f32_16x16x32_bf16 v[2:5], v[160:163], v[192:195], v[2:5]
	v_mfma_f32_16x16x32_bf16 v[8:11], v[152:155], v[192:195], v[8:11]
	s_barrier
	s_setprio 0
	v_add_u32_e32 v0, 0x18000, v236
	ds_read_b128 v[132:135], v0
	ds_read_b128 v[136:139], v0 offset:1024
	ds_read_b128 v[140:143], v0 offset:2048
	ds_read_b128 v[144:147], v0 offset:3072
	v_add_u32_e32 v0, 0x1c000, v236
	ds_read_b128 v[148:151], v0
	ds_read_b128 v[152:155], v0 offset:1024
	ds_read_b128 v[156:159], v0 offset:2048
	ds_read_b128 v[160:163], v0 offset:3072
	s_add_i32 s39, s13, 0xc0000
	s_mov_b32 m0, s63
	ds_read_b128 v[164:167], v237 offset:32768
	ds_read_b128 v[168:171], v237 offset:33792
	ds_read_b128 v[172:175], v237 offset:34816
	ds_read_b128 v[176:179], v237 offset:35840
	ds_read_b128 v[180:183], v237 offset:36864
	ds_read_b128 v[184:187], v237 offset:37888
	ds_read_b128 v[188:191], v237 offset:38912
	ds_read_b128 v[192:195], v237 offset:39936
	s_mov_b32 m0, s62
	s_nop 0
	buffer_load_dwordx4 v222, s[4:7], s13 offen lds
	s_mov_b32 m0, s63
	s_nop 0
	buffer_load_dwordx4 v220, s[4:7], s39 offen lds
	s_mov_b32 m0, s66
	s_nop 0
	buffer_load_dwordx4 v222, s[4:7], s39 offen lds
	s_waitcnt vmcnt(8)
	s_waitcnt lgkmcnt(0)
	s_setprio 1
	s_barrier
	v_mfma_f32_16x16x32_bf16 v[128:131], v[132:135], v[164:167], v[128:131]
	v_mfma_f32_16x16x32_bf16 v[124:127], v[140:143], v[164:167], v[124:127]
	v_mfma_f32_16x16x32_bf16 v[116:119], v[140:143], v[172:175], v[116:119]
	v_mfma_f32_16x16x32_bf16 v[120:123], v[132:135], v[172:175], v[120:123]
	v_mfma_f32_16x16x32_bf16 v[112:115], v[132:135], v[180:183], v[112:115]
	v_mfma_f32_16x16x32_bf16 v[108:111], v[140:143], v[180:183], v[108:111]
	v_mfma_f32_16x16x32_bf16 v[100:103], v[140:143], v[188:191], v[100:103]
	v_mfma_f32_16x16x32_bf16 v[104:107], v[132:135], v[188:191], v[104:107]
	v_mfma_f32_16x16x32_bf16 v[128:131], v[136:139], v[168:171], v[128:131]
	v_mfma_f32_16x16x32_bf16 v[124:127], v[144:147], v[168:171], v[124:127]
	v_mfma_f32_16x16x32_bf16 v[116:119], v[144:147], v[176:179], v[116:119]
	v_mfma_f32_16x16x32_bf16 v[120:123], v[136:139], v[176:179], v[120:123]
	v_mfma_f32_16x16x32_bf16 v[112:115], v[136:139], v[184:187], v[112:115]
	v_mfma_f32_16x16x32_bf16 v[108:111], v[144:147], v[184:187], v[108:111]
	v_mfma_f32_16x16x32_bf16 v[100:103], v[144:147], v[192:195], v[100:103]
	v_mfma_f32_16x16x32_bf16 v[104:107], v[136:139], v[192:195], v[104:107]
	v_mfma_f32_16x16x32_bf16 v[96:99], v[148:151], v[164:167], v[96:99]
	v_mfma_f32_16x16x32_bf16 v[92:95], v[156:159], v[164:167], v[92:95]
	v_mfma_f32_16x16x32_bf16 v[84:87], v[156:159], v[172:175], v[84:87]
	v_mfma_f32_16x16x32_bf16 v[88:91], v[148:151], v[172:175], v[88:91]
	v_mfma_f32_16x16x32_bf16 v[80:83], v[148:151], v[180:183], v[80:83]
	v_mfma_f32_16x16x32_bf16 v[76:79], v[156:159], v[180:183], v[76:79]
	v_mfma_f32_16x16x32_bf16 v[68:71], v[156:159], v[188:191], v[68:71]
	v_mfma_f32_16x16x32_bf16 v[72:75], v[148:151], v[188:191], v[72:75]
	v_mfma_f32_16x16x32_bf16 v[96:99], v[152:155], v[168:171], v[96:99]
	v_mfma_f32_16x16x32_bf16 v[92:95], v[160:163], v[168:171], v[92:95]
	v_mfma_f32_16x16x32_bf16 v[84:87], v[160:163], v[176:179], v[84:87]
	v_mfma_f32_16x16x32_bf16 v[88:91], v[152:155], v[176:179], v[88:91]
	v_mfma_f32_16x16x32_bf16 v[80:83], v[152:155], v[184:187], v[80:83]
	v_mfma_f32_16x16x32_bf16 v[76:79], v[160:163], v[184:187], v[76:79]
	v_mfma_f32_16x16x32_bf16 v[68:71], v[160:163], v[192:195], v[68:71]
	v_mfma_f32_16x16x32_bf16 v[72:75], v[152:155], v[192:195], v[72:75]
	s_barrier
; #define PG8_STAGE(bufoff, gbase, voff) do { const int so_ = (int)(unsigned)((const char*)(gbase) - base_##voff); _Pragma("unroll") for (int _i = 0; _i < 2; ++_i) \
;         __builtin_amdgcn_raw_ptr_buffer_load_lds(rs_##voff, (PG8_LAS unsigned*)(lds + (bufoff) + ldsw + _i * 8192), 16, (int)(voff)[_i], so_, 0, 0); } while (0)
; #define PG8_LDA(dst, b, h) do { _Pragma("unroll") for (int m = 0; m < 4; ++m) _Pragma("unroll") for (int k = 0; k < 2; ++k) dst[m][k] = *(const PG8_LAS bf16x8*)(lds + PG8_SA(b, h) + aoff + m * 2048 + k * 1024); } while (0)
; #define PG8_LDB(dst, b, h) do { _Pragma("unroll") for (int n = 0; n < 2; ++n) _Pragma("unroll") for (int k = 0; k < 2; ++k) dst[n][k] = *(const PG8_LAS bf16x8*)(lds + PG8_SB(b, h) + boff + n * 2048 + k * 1024); } while (0)
; #define PG8_MMA(ai, bj, At, Bt) do { __builtin_amdgcn_s_setprio(1); _Pragma("unroll") for (int m = 0; m < 4; ++m) _Pragma("unroll") for (int n = 0; n < 2; ++n) _Pragma("unroll") for (int k = 0; k < 2; ++k) \
;         acc[ai][bj][m][n] = __builtin_amdgcn_mfma_f32_16x16x32_bf16(Bt[n][k], At[m][k], acc[ai][bj][m][n], 0, 0, 0); __builtin_amdgcn_s_setprio(0); } while (0)
; template <class Epi, class Sched, bool ALIGN_EPI = false, bool SP2 = false>
; __device__ __forceinline__ void gemm_phase(PG8_LAS unsigned char* lds, const Gemm g, const Sched& S, const Epi& E, int tid_in) {
;     ...
;             PG8_LDB(B0, 0, 0); PG8_LDB(B1, 0, 1); PG8_SCHED; PG8_LDA(At, 0, 0); PG8_STAGE(PG8_SA(1, 1), a1 + hstepA, voffA);
;             PG8_WAIT_V(8); PG8_WAIT_L(0); PG8_BAR; PG8_MMA(0, 0, At, B0); PG8_MMA(0, 1, At, B1); PG8_BAR; PG8_SCHED;
;             PG8_LDA(At, 0, 1); PG8_STAGE(PG8_SB(0, 0), b2, voffB); PG8_STAGE(PG8_SB(0, 1), b2 + hstepB, voffB); PG8_STAGE(PG8_SA(0, 0), a2, voffA);
;             PG8_WAIT_V(8); PG8_WAIT_L(0); PG8_BAR; PG8_MMA(1, 0, At, B0); PG8_MMA(1, 1, At, B1); PG8_BAR; PG8_SCHED;
;             PG8_LDB(B0, 1, 0); PG8_LDB(B1, 1, 1); PG8_SCHED; PG8_LDA(At, 1, 0); PG8_STAGE(PG8_SA(0, 1), a2 + hstepA, voffA);
;             PG8_WAIT_V(8); PG8_WAIT_L(0); PG8_BAR; PG8_MMA(0, 0, At, B0); PG8_MMA(0, 1, At, B1); PG8_BAR; PG8_SCHED;
;             PG8_LDA(At, 1, 1); PG8_STAGE(PG8_SB(1, 0), b3, voffB); PG8_STAGE(PG8_SB(1, 1), b3 + hstepB, voffB); PG8_STAGE(PG8_SA(1, 0), a3, voffA);
;             PG8_WAIT_V(8); PG8_WAIT_L(0); PG8_BAR; PG8_MMA(1, 0, At, B0); PG8_MMA(1, 1, At, B1); PG8_BAR; PG8_SCHED;
	s_setprio 0
	s_mov_b32 m0, s69
	s_add_i32 s39, s12, 0x80
	ds_read_b128 v[164:167], v237 offset:49152
	ds_read_b128 v[168:171], v237 offset:50176
	ds_read_b128 v[172:175], v237 offset:51200
	ds_read_b128 v[176:179], v237 offset:52224
	ds_read_b128 v[180:183], v237 offset:53248
	ds_read_b128 v[184:187], v237 offset:54272
	ds_read_b128 v[188:191], v237 offset:55296
	ds_read_b128 v[192:195], v237 offset:56320
	buffer_load_dwordx4 v221, s[44:47], s39 offen lds
	s_mov_b32 m0, s71
	s_add_i32 s12, s12, 0x40080
	buffer_load_dwordx4 v223, s[44:47], s39 offen lds
	s_mov_b32 m0, s74
	s_addk_i32 s13, 0x80
	buffer_load_dwordx4 v221, s[44:47], s12 offen lds
	s_mov_b32 m0, s75
	s_nop 0
	buffer_load_dwordx4 v223, s[44:47], s12 offen lds
	s_mov_b32 m0, s72
	s_nop 0
	buffer_load_dwordx4 v220, s[4:7], s13 offen lds
	s_waitcnt vmcnt(7)
	s_waitcnt lgkmcnt(0)
	s_setprio 1
	s_barrier
	v_mfma_f32_16x16x32_bf16 v[64:67], v[132:135], v[164:167], v[64:67]
	v_mfma_f32_16x16x32_bf16 v[60:63], v[140:143], v[164:167], v[60:63]
	v_mfma_f32_16x16x32_bf16 v[52:55], v[140:143], v[172:175], v[52:55]
	v_mfma_f32_16x16x32_bf16 v[56:59], v[132:135], v[172:175], v[56:59]
	v_mfma_f32_16x16x32_bf16 v[48:51], v[132:135], v[180:183], v[48:51]
	v_mfma_f32_16x16x32_bf16 v[44:47], v[140:143], v[180:183], v[44:47]
	v_mfma_f32_16x16x32_bf16 v[36:39], v[140:143], v[188:191], v[36:39]
	v_mfma_f32_16x16x32_bf16 v[40:43], v[132:135], v[188:191], v[40:43]
	v_mfma_f32_16x16x32_bf16 v[64:67], v[136:139], v[168:171], v[64:67]
	v_mfma_f32_16x16x32_bf16 v[60:63], v[144:147], v[168:171], v[60:63]
	v_mfma_f32_16x16x32_bf16 v[52:55], v[144:147], v[176:179], v[52:55]
	v_mfma_f32_16x16x32_bf16 v[56:59], v[136:139], v[176:179], v[56:59]
	v_mfma_f32_16x16x32_bf16 v[48:51], v[136:139], v[184:187], v[48:51]
	v_mfma_f32_16x16x32_bf16 v[44:47], v[144:147], v[184:187], v[44:47]
	v_mfma_f32_16x16x32_bf16 v[36:39], v[144:147], v[192:195], v[36:39]
	v_mfma_f32_16x16x32_bf16 v[40:43], v[136:139], v[192:195], v[40:43]
	v_mfma_f32_16x16x32_bf16 v[32:35], v[148:151], v[164:167], v[32:35]
	v_mfma_f32_16x16x32_bf16 v[28:31], v[156:159], v[164:167], v[28:31]
	v_mfma_f32_16x16x32_bf16 v[20:23], v[156:159], v[172:175], v[20:23]
	v_mfma_f32_16x16x32_bf16 v[24:27], v[148:151], v[172:175], v[24:27]
	v_mfma_f32_16x16x32_bf16 v[16:19], v[148:151], v[180:183], v[16:19]
	v_mfma_f32_16x16x32_bf16 v[12:15], v[156:159], v[180:183], v[12:15]
	v_mfma_f32_16x16x32_bf16 v[2:5], v[156:159], v[188:191], v[2:5]
	v_mfma_f32_16x16x32_bf16 v[6:9], v[148:151], v[188:191], v[8:11]
	v_mfma_f32_16x16x32_bf16 v[32:35], v[152:155], v[168:171], v[32:35]
	v_mfma_f32_16x16x32_bf16 v[28:31], v[160:163], v[168:171], v[28:31]
	v_mfma_f32_16x16x32_bf16 v[20:23], v[160:163], v[176:179], v[20:23]
	v_mfma_f32_16x16x32_bf16 v[24:27], v[152:155], v[176:179], v[24:27]
	v_mfma_f32_16x16x32_bf16 v[16:19], v[152:155], v[184:187], v[16:19]
	v_mfma_f32_16x16x32_bf16 v[12:15], v[160:163], v[184:187], v[12:15]
	v_mfma_f32_16x16x32_bf16 v[8:11], v[152:155], v[192:195], v[6:9]
	v_mfma_f32_16x16x32_bf16 v[4:7], v[160:163], v[192:195], v[2:5]
	s_barrier
	s_setprio 0
	s_add_i32 s38, s38, 2
	s_add_u32 s19, s19, 0x100
	s_addc_u32 s23, s23, 0
	s_cmp_gt_u32 s38, 13
	s_mov_b64 s[12:13], s[16:17]
	s_cbranch_scc0 .LBB0_1037
	s_branch .Lyng_after1
.Lyng_loop1:
	v_add_u32_e32 v0, 0x10000, v236
	ds_read_b128 v[132:135], v0
	ds_read_b128 v[136:139], v0 offset:1024
	ds_read_b128 v[140:143], v0 offset:2048
	ds_read_b128 v[144:147], v0 offset:3072
	v_add_u32_e32 v0, 0x14000, v236
	ds_read_b128 v[148:151], v0
	ds_read_b128 v[152:155], v0 offset:1024
	ds_read_b128 v[156:159], v0 offset:2048
	ds_read_b128 v[160:163], v0 offset:3072
	s_add_u32 s16, s12, 0x100
	s_addc_u32 s17, s13, 0
	s_sub_i32 s12, s12, s4
	s_add_i32 s12, s12, 0xc0080
	s_sub_i32 s39, s12, 0xc0000
	s_cmp_eq_u32 s38, 12
	s_cselect_b32 s13, s24, s16
	s_mov_b32 m0, s76
	ds_read_b128 v[164:167], v237
	ds_read_b128 v[168:171], v237 offset:1024
	ds_read_b128 v[172:175], v237 offset:2048
	ds_read_b128 v[176:179], v237 offset:3072
	ds_read_b128 v[180:183], v237 offset:4096
	ds_read_b128 v[184:187], v237 offset:5120
	ds_read_b128 v[188:191], v237 offset:6144
	ds_read_b128 v[192:195], v237 offset:7168
	s_mov_b32 m0, s73
	s_nop 0
	buffer_load_dwordx4 v222, s[4:7], s39 offen lds
	s_mov_b32 m0, s76
	s_nop 0
	buffer_load_dwordx4 v220, s[4:7], s12 offen lds
	s_mov_b32 m0, s77
	s_nop 0
	buffer_load_dwordx4 v222, s[4:7], s12 offen lds
	s_waitcnt vmcnt(8)
	s_waitcnt lgkmcnt(0)
	s_setprio 2
	s_barrier
	v_mfma_f32_16x16x32_bf16 v[128:131], v[132:135], v[164:167], v[128:131]
	v_mfma_f32_16x16x32_bf16 v[124:127], v[140:143], v[164:167], v[124:127]
	v_mfma_f32_16x16x32_bf16 v[116:119], v[140:143], v[172:175], v[116:119]
	v_mfma_f32_16x16x32_bf16 v[120:123], v[132:135], v[172:175], v[120:123]
	v_mfma_f32_16x16x32_bf16 v[112:115], v[132:135], v[180:183], v[112:115]
	v_mfma_f32_16x16x32_bf16 v[108:111], v[140:143], v[180:183], v[108:111]
	v_mfma_f32_16x16x32_bf16 v[100:103], v[140:143], v[188:191], v[100:103]
	v_mfma_f32_16x16x32_bf16 v[104:107], v[132:135], v[188:191], v[104:107]
	v_mfma_f32_16x16x32_bf16 v[128:131], v[136:139], v[168:171], v[128:131]
	v_mfma_f32_16x16x32_bf16 v[124:127], v[144:147], v[168:171], v[124:127]
	v_mfma_f32_16x16x32_bf16 v[116:119], v[144:147], v[176:179], v[116:119]
	v_mfma_f32_16x16x32_bf16 v[120:123], v[136:139], v[176:179], v[120:123]
	v_mfma_f32_16x16x32_bf16 v[112:115], v[136:139], v[184:187], v[112:115]
	v_mfma_f32_16x16x32_bf16 v[108:111], v[144:147], v[184:187], v[108:111]
	v_mfma_f32_16x16x32_bf16 v[100:103], v[144:147], v[192:195], v[100:103]
	v_mfma_f32_16x16x32_bf16 v[104:107], v[136:139], v[192:195], v[104:107]
	v_mfma_f32_16x16x32_bf16 v[96:99], v[148:151], v[164:167], v[96:99]
	v_mfma_f32_16x16x32_bf16 v[92:95], v[156:159], v[164:167], v[92:95]
	v_mfma_f32_16x16x32_bf16 v[84:87], v[156:159], v[172:175], v[84:87]
	v_mfma_f32_16x16x32_bf16 v[88:91], v[148:151], v[172:175], v[88:91]
	v_mfma_f32_16x16x32_bf16 v[80:83], v[148:151], v[180:183], v[80:83]
	v_mfma_f32_16x16x32_bf16 v[76:79], v[156:159], v[180:183], v[76:79]
	v_mfma_f32_16x16x32_bf16 v[68:71], v[156:159], v[188:191], v[68:71]
	v_mfma_f32_16x16x32_bf16 v[72:75], v[148:151], v[188:191], v[72:75]
	v_mfma_f32_16x16x32_bf16 v[96:99], v[152:155], v[168:171], v[96:99]
	v_mfma_f32_16x16x32_bf16 v[92:95], v[160:163], v[168:171], v[92:95]
	v_mfma_f32_16x16x32_bf16 v[84:87], v[160:163], v[176:179], v[84:87]
	v_mfma_f32_16x16x32_bf16 v[88:91], v[152:155], v[176:179], v[88:91]
	v_mfma_f32_16x16x32_bf16 v[80:83], v[152:155], v[184:187], v[80:83]
	v_mfma_f32_16x16x32_bf16 v[76:79], v[160:163], v[184:187], v[76:79]
	v_mfma_f32_16x16x32_bf16 v[68:71], v[160:163], v[192:195], v[68:71]
	v_mfma_f32_16x16x32_bf16 v[72:75], v[152:155], v[192:195], v[72:75]
	s_barrier
; #define PG8_STAGE(bufoff, gbase, voff) do { const int so_ = (int)(unsigned)((const char*)(gbase) - base_##voff); _Pragma("unroll") for (int _i = 0; _i < 2; ++_i) \
;         __builtin_amdgcn_raw_ptr_buffer_load_lds(rs_##voff, (PG8_LAS unsigned*)(lds + (bufoff) + ldsw + _i * 8192), 16, (int)(voff)[_i], so_, 0, 0); } while (0)
; #define PG8_LDA(dst, b, h) do { _Pragma("unroll") for (int m = 0; m < 4; ++m) _Pragma("unroll") for (int k = 0; k < 2; ++k) dst[m][k] = *(const PG8_LAS bf16x8*)(lds + PG8_SA(b, h) + aoff + m * 2048 + k * 1024); } while (0)
; #define PG8_LDB(dst, b, h) do { _Pragma("unroll") for (int n = 0; n < 2; ++n) _Pragma("unroll") for (int k = 0; k < 2; ++k) dst[n][k] = *(const PG8_LAS bf16x8*)(lds + PG8_SB(b, h) + boff + n * 2048 + k * 1024); } while (0)
; #define PG8_MMA(ai, bj, At, Bt) do { __builtin_amdgcn_s_setprio(1); _Pragma("unroll") for (int m = 0; m < 4; ++m) _Pragma("unroll") for (int n = 0; n < 2; ++n) _Pragma("unroll") for (int k = 0; k < 2; ++k) \
;         acc[ai][bj][m][n] = __builtin_amdgcn_mfma_f32_16x16x32_bf16(Bt[n][k], At[m][k], acc[ai][bj][m][n], 0, 0, 0); __builtin_amdgcn_s_setprio(0); } while (0)
; #define PG8_WAIT_V(n) asm volatile("s_waitcnt vmcnt(" #n ")" ::: "memory")
; #define PG8_WAIT_L(n) asm volatile("s_waitcnt lgkmcnt(" #n ")" ::: "memory")
; #define PG8_BAR __builtin_amdgcn_s_barrier()
; #define PG8_SCHED __builtin_amdgcn_sched_barrier(0)
; template <class Epi, class Sched, bool ALIGN_EPI = false, bool SP2 = false>
; __device__ __forceinline__ void gemm_phase(PG8_LAS unsigned char* lds, const Gemm g, const Sched& S, const Epi& E, int tid_in) {
;     ...
;             PG8_LDA(At, 0, 1); PG8_STAGE(PG8_SB(0, 0), b2, voffB); PG8_STAGE(PG8_SB(0, 1), b2 + hstepB, voffB); PG8_STAGE(PG8_SA(0, 0), a2, voffA);
;             PG8_WAIT_V(8); PG8_WAIT_L(0); PG8_BAR; PG8_MMA(1, 0, At, B0); PG8_MMA(1, 1, At, B1); PG8_BAR; PG8_SCHED;
;             PG8_LDB(B0, 1, 0); PG8_LDB(B1, 1, 1); PG8_SCHED; PG8_LDA(At, 1, 0); PG8_STAGE(PG8_SA(0, 1), a2 + hstepA, voffA);
;             PG8_WAIT_V(8); PG8_WAIT_L(0); PG8_BAR; PG8_MMA(0, 0, At, B0); PG8_MMA(0, 1, At, B1); PG8_BAR; PG8_SCHED;
	s_setprio 1
	s_cselect_b32 s12, s18, s19
	s_mov_b32 m0, s26
	s_mov_b32 s46, s6
	s_mov_b32 s47, s7
	s_sub_i32 s12, s12, s44
	ds_read_b128 v[164:167], v237 offset:16384
	ds_read_b128 v[168:171], v237 offset:17408
	ds_read_b128 v[172:175], v237 offset:18432
	ds_read_b128 v[176:179], v237 offset:19456
	ds_read_b128 v[180:183], v237 offset:20480
	ds_read_b128 v[184:187], v237 offset:21504
	ds_read_b128 v[188:191], v237 offset:22528
	ds_read_b128 v[192:195], v237 offset:23552
	buffer_load_dwordx4 v221, s[44:47], s12 offen lds
	s_mov_b32 m0, s53
	s_add_i32 s39, s12, 0x40000
	buffer_load_dwordx4 v223, s[44:47], s12 offen lds
	s_mov_b32 m0, s60
	s_sub_i32 s13, s13, s4
	buffer_load_dwordx4 v221, s[44:47], s39 offen lds
	s_mov_b32 m0, s61
	s_nop 0
	buffer_load_dwordx4 v223, s[44:47], s39 offen lds
	s_mov_b32 m0, s21
	s_nop 0
	buffer_load_dwordx4 v220, s[4:7], s13 offen lds
	s_waitcnt vmcnt(7)
	s_waitcnt lgkmcnt(0)
	s_setprio 2
	s_barrier
	v_mfma_f32_16x16x32_bf16 v[64:67], v[132:135], v[164:167], v[64:67]
	v_mfma_f32_16x16x32_bf16 v[60:63], v[140:143], v[164:167], v[60:63]
	v_mfma_f32_16x16x32_bf16 v[52:55], v[140:143], v[172:175], v[52:55]
	v_mfma_f32_16x16x32_bf16 v[56:59], v[132:135], v[172:175], v[56:59]
	v_mfma_f32_16x16x32_bf16 v[48:51], v[132:135], v[180:183], v[48:51]
	v_mfma_f32_16x16x32_bf16 v[44:47], v[140:143], v[180:183], v[44:47]
	v_mfma_f32_16x16x32_bf16 v[36:39], v[140:143], v[188:191], v[36:39]
	v_mfma_f32_16x16x32_bf16 v[40:43], v[132:135], v[188:191], v[40:43]
	v_mfma_f32_16x16x32_bf16 v[64:67], v[136:139], v[168:171], v[64:67]
	v_mfma_f32_16x16x32_bf16 v[60:63], v[144:147], v[168:171], v[60:63]
	v_mfma_f32_16x16x32_bf16 v[52:55], v[144:147], v[176:179], v[52:55]
	v_mfma_f32_16x16x32_bf16 v[56:59], v[136:139], v[176:179], v[56:59]
	v_mfma_f32_16x16x32_bf16 v[48:51], v[136:139], v[184:187], v[48:51]
	v_mfma_f32_16x16x32_bf16 v[44:47], v[144:147], v[184:187], v[44:47]
	v_mfma_f32_16x16x32_bf16 v[36:39], v[144:147], v[192:195], v[36:39]
	v_mfma_f32_16x16x32_bf16 v[40:43], v[136:139], v[192:195], v[40:43]
	v_mfma_f32_16x16x32_bf16 v[32:35], v[148:151], v[164:167], v[32:35]
	v_mfma_f32_16x16x32_bf16 v[28:31], v[156:159], v[164:167], v[28:31]
	v_mfma_f32_16x16x32_bf16 v[20:23], v[156:159], v[172:175], v[20:23]
	v_mfma_f32_16x16x32_bf16 v[24:27], v[148:151], v[172:175], v[24:27]
	v_mfma_f32_16x16x32_bf16 v[16:19], v[148:151], v[180:183], v[16:19]
	v_mfma_f32_16x16x32_bf16 v[12:15], v[156:159], v[180:183], v[12:15]
	v_mfma_f32_16x16x32_bf16 v[2:5], v[156:159], v[188:191], v[4:7]
	v_mfma_f32_16x16x32_bf16 v[8:11], v[148:151], v[188:191], v[8:11]
	v_mfma_f32_16x16x32_bf16 v[32:35], v[152:155], v[168:171], v[32:35]
	v_mfma_f32_16x16x32_bf16 v[28:31], v[160:163], v[168:171], v[28:31]
	v_mfma_f32_16x16x32_bf16 v[20:23], v[160:163], v[176:179], v[20:23]
	v_mfma_f32_16x16x32_bf16 v[24:27], v[152:155], v[176:179], v[24:27]
	v_mfma_f32_16x16x32_bf16 v[16:19], v[152:155], v[184:187], v[16:19]
	v_mfma_f32_16x16x32_bf16 v[12:15], v[160:163], v[184:187], v[12:15]
	v_mfma_f32_16x16x32_bf16 v[2:5], v[160:163], v[192:195], v[2:5]
	v_mfma_f32_16x16x32_bf16 v[8:11], v[152:155], v[192:195], v[8:11]
	s_barrier
	s_setprio 1
	v_add_u32_e32 v0, 0x18000, v236
	ds_read_b128 v[132:135], v0
	ds_read_b128 v[136:139], v0 offset:1024
	ds_read_b128 v[140:143], v0 offset:2048
	ds_read_b128 v[144:147], v0 offset:3072
	v_add_u32_e32 v0, 0x1c000, v236
	ds_read_b128 v[148:151], v0
	ds_read_b128 v[152:155], v0 offset:1024
	ds_read_b128 v[156:159], v0 offset:2048
	ds_read_b128 v[160:163], v0 offset:3072
	s_add_i32 s39, s13, 0xc0000
	s_mov_b32 m0, s63
	ds_read_b128 v[164:167], v237 offset:32768
	ds_read_b128 v[168:171], v237 offset:33792
	ds_read_b128 v[172:175], v237 offset:34816
	ds_read_b128 v[176:179], v237 offset:35840
	ds_read_b128 v[180:183], v237 offset:36864
	ds_read_b128 v[184:187], v237 offset:37888
	ds_read_b128 v[188:191], v237 offset:38912
	ds_read_b128 v[192:195], v237 offset:39936
	s_mov_b32 m0, s62
	s_nop 0
	buffer_load_dwordx4 v222, s[4:7], s13 offen lds
	s_mov_b32 m0, s63
	s_nop 0
	buffer_load_dwordx4 v220, s[4:7], s39 offen lds
	s_mov_b32 m0, s66
	s_nop 0
	buffer_load_dwordx4 v222, s[4:7], s39 offen lds
	s_waitcnt vmcnt(8)
	s_waitcnt lgkmcnt(0)
	s_setprio 2
	s_barrier
; #define PG8_STAGE(bufoff, gbase, voff) do { const int so_ = (int)(unsigned)((const char*)(gbase) - base_##voff); _Pragma("unroll") for (int _i = 0; _i < 2; ++_i) \
;         __builtin_amdgcn_raw_ptr_buffer_load_lds(rs_##voff, (PG8_LAS unsigned*)(lds + (bufoff) + ldsw + _i * 8192), 16, (int)(voff)[_i], so_, 0, 0); } while (0)
; #define PG8_WAIT_V(n) asm volatile("s_waitcnt vmcnt(" #n ")" ::: "memory")
; template <class Epi, class Sched, bool ALIGN_EPI = false, bool SP2 = false>
; __device__ __forceinline__ void gemm_phase(PG8_LAS unsigned char* lds, const Gemm g, const Sched& S, const Epi& E, int tid_in) {
;     ...
;             PG8_WAIT_V(8); PG8_WAIT_L(0); PG8_BAR; PG8_MMA(0, 0, At, B0); PG8_MMA(0, 1, At, B1); PG8_BAR; PG8_SCHED;
;             PG8_LDA(At, 1, 1); PG8_STAGE(PG8_SB(1, 0), b3, voffB); PG8_STAGE(PG8_SB(1, 1), b3 + hstepB, voffB); PG8_STAGE(PG8_SA(1, 0), a3, voffA);
;             PG8_WAIT_V(8); PG8_WAIT_L(0); PG8_BAR; PG8_MMA(1, 0, At, B0); PG8_MMA(1, 1, At, B1); PG8_BAR; PG8_SCHED;
;             } else {
;             PG8_LDB(B0, 0, 0); PG8_SCHED; PG8_LDA(At, 0, 0); PG8_STAGE(PG8_SA(1, 1), a1 + hstepA, voffA);
;             PG8_WAIT_L(8); PG8_BAR; PG8_WAIT_L(0); PG8_MMA(0, 0, At, B0); PG8_BAR; PG8_SCHED;
;             PG8_LDB(B1, 0, 1); PG8_STAGE(PG8_SB(0, 0), b2, voffB);
;             PG8_BAR; PG8_WAIT_L(0); PG8_MMA(0, 1, At, B1); PG8_BAR;
;             PG8_LDA(At, 0, 1); PG8_STAGE(PG8_SA(0, 0), a2, voffA);
;             PG8_BAR; PG8_WAIT_L(0); PG8_MMA(1, 0, At, B0); PG8_BAR; PG8_SCHED;
;             PG8_STAGE(PG8_SB(0, 1), b2 + hstepB, voffB);
;             PG8_WAIT_V(6); PG8_BAR; PG8_MMA(1, 1, At, B1); PG8_BAR;
;             PG8_LDB(B0, 1, 0); PG8_SCHED; PG8_LDA(At, 1, 0); PG8_STAGE(PG8_SA(0, 1), a2 + hstepA, voffA);
;             PG8_WAIT_L(8); PG8_BAR; PG8_WAIT_L(0); PG8_MMA(0, 0, At, B0); PG8_BAR; PG8_SCHED;
;             PG8_LDB(B1, 1, 1); PG8_STAGE(PG8_SB(1, 0), b3, voffB);
;             PG8_BAR; PG8_WAIT_L(0); PG8_MMA(0, 1, At, B1); PG8_BAR;
;             PG8_LDA(At, 1, 1); PG8_STAGE(PG8_SA(1, 0), a3, voffA);
;             PG8_BAR; PG8_WAIT_L(0); PG8_MMA(1, 0, At, B0); PG8_BAR; PG8_SCHED;
;             PG8_STAGE(PG8_SB(1, 1), b3 + hstepB, voffB);
;             PG8_WAIT_V(6); PG8_BAR; PG8_MMA(1, 1, At, B1); PG8_BAR;
;             }
;         }
;         if constexpr (ALIGN_EPI) { if (wr == 0) PG8_BAR; }
	v_mfma_f32_16x16x32_bf16 v[128:131], v[132:135], v[164:167], v[128:131]
	v_mfma_f32_16x16x32_bf16 v[124:127], v[140:143], v[164:167], v[124:127]
	v_mfma_f32_16x16x32_bf16 v[116:119], v[140:143], v[172:175], v[116:119]
	v_mfma_f32_16x16x32_bf16 v[120:123], v[132:135], v[172:175], v[120:123]
	v_mfma_f32_16x16x32_bf16 v[112:115], v[132:135], v[180:183], v[112:115]
	v_mfma_f32_16x16x32_bf16 v[108:111], v[140:143], v[180:183], v[108:111]
	v_mfma_f32_16x16x32_bf16 v[100:103], v[140:143], v[188:191], v[100:103]
	v_mfma_f32_16x16x32_bf16 v[104:107], v[132:135], v[188:191], v[104:107]
	v_mfma_f32_16x16x32_bf16 v[128:131], v[136:139], v[168:171], v[128:131]
	v_mfma_f32_16x16x32_bf16 v[124:127], v[144:147], v[168:171], v[124:127]
	v_mfma_f32_16x16x32_bf16 v[116:119], v[144:147], v[176:179], v[116:119]
	v_mfma_f32_16x16x32_bf16 v[120:123], v[136:139], v[176:179], v[120:123]
	v_mfma_f32_16x16x32_bf16 v[112:115], v[136:139], v[184:187], v[112:115]
	v_mfma_f32_16x16x32_bf16 v[108:111], v[144:147], v[184:187], v[108:111]
	v_mfma_f32_16x16x32_bf16 v[100:103], v[144:147], v[192:195], v[100:103]
	v_mfma_f32_16x16x32_bf16 v[104:107], v[136:139], v[192:195], v[104:107]
	v_mfma_f32_16x16x32_bf16 v[96:99], v[148:151], v[164:167], v[96:99]
	v_mfma_f32_16x16x32_bf16 v[92:95], v[156:159], v[164:167], v[92:95]
	v_mfma_f32_16x16x32_bf16 v[84:87], v[156:159], v[172:175], v[84:87]
	v_mfma_f32_16x16x32_bf16 v[88:91], v[148:151], v[172:175], v[88:91]
	v_mfma_f32_16x16x32_bf16 v[80:83], v[148:151], v[180:183], v[80:83]
	v_mfma_f32_16x16x32_bf16 v[76:79], v[156:159], v[180:183], v[76:79]
	v_mfma_f32_16x16x32_bf16 v[68:71], v[156:159], v[188:191], v[68:71]
	v_mfma_f32_16x16x32_bf16 v[72:75], v[148:151], v[188:191], v[72:75]
	v_mfma_f32_16x16x32_bf16 v[96:99], v[152:155], v[168:171], v[96:99]
	v_mfma_f32_16x16x32_bf16 v[92:95], v[160:163], v[168:171], v[92:95]
	v_mfma_f32_16x16x32_bf16 v[84:87], v[160:163], v[176:179], v[84:87]
	v_mfma_f32_16x16x32_bf16 v[88:91], v[152:155], v[176:179], v[88:91]
	v_mfma_f32_16x16x32_bf16 v[80:83], v[152:155], v[184:187], v[80:83]
	v_mfma_f32_16x16x32_bf16 v[76:79], v[160:163], v[184:187], v[76:79]
	v_mfma_f32_16x16x32_bf16 v[68:71], v[160:163], v[192:195], v[68:71]
	v_mfma_f32_16x16x32_bf16 v[72:75], v[152:155], v[192:195], v[72:75]
	s_barrier
	s_setprio 1
	s_mov_b32 m0, s69
	s_add_i32 s39, s12, 0x80
	ds_read_b128 v[164:167], v237 offset:49152
	ds_read_b128 v[168:171], v237 offset:50176
	ds_read_b128 v[172:175], v237 offset:51200
	ds_read_b128 v[176:179], v237 offset:52224
	ds_read_b128 v[180:183], v237 offset:53248
	ds_read_b128 v[184:187], v237 offset:54272
	ds_read_b128 v[188:191], v237 offset:55296
	ds_read_b128 v[192:195], v237 offset:56320
	buffer_load_dwordx4 v221, s[44:47], s39 offen lds
	s_mov_b32 m0, s71
	s_add_i32 s12, s12, 0x40080
	buffer_load_dwordx4 v223, s[44:47], s39 offen lds
	s_mov_b32 m0, s74
	s_addk_i32 s13, 0x80
	buffer_load_dwordx4 v221, s[44:47], s12 offen lds
	s_mov_b32 m0, s75
	s_nop 0
	buffer_load_dwordx4 v223, s[44:47], s12 offen lds
	s_mov_b32 m0, s72
	s_nop 0
	buffer_load_dwordx4 v220, s[4:7], s13 offen lds
	s_waitcnt vmcnt(7)
	s_waitcnt lgkmcnt(0)
	s_setprio 2
	s_barrier
	v_mfma_f32_16x16x32_bf16 v[64:67], v[132:135], v[164:167], v[64:67]
	v_mfma_f32_16x16x32_bf16 v[60:63], v[140:143], v[164:167], v[60:63]
	v_mfma_f32_16x16x32_bf16 v[52:55], v[140:143], v[172:175], v[52:55]
	v_mfma_f32_16x16x32_bf16 v[56:59], v[132:135], v[172:175], v[56:59]
	v_mfma_f32_16x16x32_bf16 v[48:51], v[132:135], v[180:183], v[48:51]
	v_mfma_f32_16x16x32_bf16 v[44:47], v[140:143], v[180:183], v[44:47]
	v_mfma_f32_16x16x32_bf16 v[36:39], v[140:143], v[188:191], v[36:39]
	v_mfma_f32_16x16x32_bf16 v[40:43], v[132:135], v[188:191], v[40:43]
	v_mfma_f32_16x16x32_bf16 v[64:67], v[136:139], v[168:171], v[64:67]
	v_mfma_f32_16x16x32_bf16 v[60:63], v[144:147], v[168:171], v[60:63]
	v_mfma_f32_16x16x32_bf16 v[52:55], v[144:147], v[176:179], v[52:55]
	v_mfma_f32_16x16x32_bf16 v[56:59], v[136:139], v[176:179], v[56:59]
	v_mfma_f32_16x16x32_bf16 v[48:51], v[136:139], v[184:187], v[48:51]
	v_mfma_f32_16x16x32_bf16 v[44:47], v[144:147], v[184:187], v[44:47]
	v_mfma_f32_16x16x32_bf16 v[36:39], v[144:147], v[192:195], v[36:39]
	v_mfma_f32_16x16x32_bf16 v[40:43], v[136:139], v[192:195], v[40:43]
	v_mfma_f32_16x16x32_bf16 v[32:35], v[148:151], v[164:167], v[32:35]
	v_mfma_f32_16x16x32_bf16 v[28:31], v[156:159], v[164:167], v[28:31]
	v_mfma_f32_16x16x32_bf16 v[20:23], v[156:159], v[172:175], v[20:23]
	v_mfma_f32_16x16x32_bf16 v[24:27], v[148:151], v[172:175], v[24:27]
	v_mfma_f32_16x16x32_bf16 v[16:19], v[148:151], v[180:183], v[16:19]
	v_mfma_f32_16x16x32_bf16 v[12:15], v[156:159], v[180:183], v[12:15]
	v_mfma_f32_16x16x32_bf16 v[2:5], v[156:159], v[188:191], v[2:5]
	v_mfma_f32_16x16x32_bf16 v[6:9], v[148:151], v[188:191], v[8:11]
	v_mfma_f32_16x16x32_bf16 v[32:35], v[152:155], v[168:171], v[32:35]
	v_mfma_f32_16x16x32_bf16 v[28:31], v[160:163], v[168:171], v[28:31]
	v_mfma_f32_16x16x32_bf16 v[20:23], v[160:163], v[176:179], v[20:23]
	v_mfma_f32_16x16x32_bf16 v[24:27], v[152:155], v[176:179], v[24:27]
	v_mfma_f32_16x16x32_bf16 v[16:19], v[152:155], v[184:187], v[16:19]
	v_mfma_f32_16x16x32_bf16 v[12:15], v[160:163], v[184:187], v[12:15]
	v_mfma_f32_16x16x32_bf16 v[8:11], v[152:155], v[192:195], v[6:9]
	v_mfma_f32_16x16x32_bf16 v[4:7], v[160:163], v[192:195], v[2:5]
	s_barrier
	s_setprio 1
	s_add_i32 s38, s38, 2
	s_add_u32 s19, s19, 0x100
	s_addc_u32 s23, s23, 0
	s_cmp_gt_u32 s38, 13
	s_mov_b64 s[12:13], s[16:17]
	s_cbranch_scc0 .Lyng_loop1
	s_setprio 0
.Lyng_after1:
	s_and_b64 vcc, exec, s[14:15]
	s_cbranch_vccz .LBB0_1040
	s_barrier

;     __host__ __device__ bool next(int i, Unit& u) const { const int t = i / 3, b = i - 3 * t; Unit v; if (!StaticOrder::next(t, v)) return false; u.pm = v.pm; u.pn = 8 * b + v.pn; return true; }
; #define PG8_STAGE(bufoff, gbase, voff) do { const int so_ = (int)(unsigned)((const char*)(gbase) - base_##voff); _Pragma("unroll") for (int _i = 0; _i < 2; ++_i) \
;         __builtin_amdgcn_raw_ptr_buffer_load_lds(rs_##voff, (PG8_LAS unsigned*)(lds + (bufoff) + ldsw + _i * 8192), 16, (int)(voff)[_i], so_, 0, 0); } while (0)
; #define PG8_LDA(dst, b, h) do { _Pragma("unroll") for (int m = 0; m < 4; ++m) _Pragma("unroll") for (int k = 0; k < 2; ++k) dst[m][k] = *(const PG8_LAS bf16x8*)(lds + PG8_SA(b, h) + aoff + m * 2048 + k * 1024); } while (0)
; #define PG8_WAIT_V(n) asm volatile("s_waitcnt vmcnt(" #n ")" ::: "memory")
; #define PG8_WAIT_L(n) asm volatile("s_waitcnt lgkmcnt(" #n ")" ::: "memory")
; #define PG8_BAR __builtin_amdgcn_s_barrier()
; template <class Epi, class Sched, bool ALIGN_EPI = false, bool SP2 = false>
; __device__ __forceinline__ void gemm_phase(PG8_LAS unsigned char* lds, const Gemm g, const Sched& S, const Epi& E, int tid_in) {
;     ...
;         const bool has_next = S.next(ui + 1, nxt);
;         const char* nA = has_next ? (const char*)g.A + (size_t)nxt.pm * tstepA + (g.grp ? (size_t)(nxt.pn / g.grp) * g.agrp : (size_t)0) : cA; const char* nB = has_next ? (const char*)g.Bt + (size_t)nxt.pn * tstepB : cB;
;         for (int t = 0; t < nt; t += 2) {
;             const bool last = (t == nt - 2);
;             const char* a1 = cA + (size_t)(t + 1) * kstep;
;             const char* a2 = last ? nA : cA + (size_t)(t + 2) * kstep; const char* b2 = last ? nB : cB + (size_t)(t + 2) * kstep;
;             const char* a3 = a2 + kstep; const char* b3 = b2 + kstep;
;             if (last && has_next) S.a_ready(nxt);
;             if constexpr (SP2) {
;             PG8_LDB(B0, 0, 0); PG8_LDB(B1, 0, 1); PG8_SCHED; PG8_LDA(At, 0, 0); PG8_STAGE(PG8_SA(1, 1), a1 + hstepA, voffA);
;             PG8_WAIT_V(8); PG8_WAIT_L(0); PG8_BAR; PG8_MMA(0, 0, At, B0); PG8_MMA(0, 1, At, B1); PG8_BAR; PG8_SCHED;
;             PG8_LDA(At, 0, 1); PG8_STAGE(PG8_SB(0, 0), b2, voffB); PG8_STAGE(PG8_SB(0, 1), b2 + hstepB, voffB); PG8_STAGE(PG8_SA(0, 0), a2, voffA);
;             PG8_WAIT_V(8); PG8_WAIT_L(0); PG8_BAR; PG8_MMA(1, 0, At, B0); PG8_MMA(1, 1, At, B1); PG8_BAR; PG8_SCHED;
.LBB0_1264:
	s_ashr_i32 s21, s20, 31
	s_lshl_b64 s[18:19], s[20:21], 20
	s_add_u32 s22, s4, s18
	s_addc_u32 s23, s9, s19
	s_and_b64 s[18:19], s[38:39], exec
	s_cselect_b32 s15, s22, s14
	s_ashr_i32 s17, s16, 31
	s_lshl_b64 s[18:19], s[16:17], 20
	s_add_u32 s24, s40, s18
	s_addc_u32 s25, s34, s19
	s_and_b64 s[18:19], s[38:39], exec
	s_cselect_b32 s17, s24, s12
	s_add_i32 s18, s14, s77
	s_add_i32 s18, s18, 0x80000
	s_mov_b32 s19, -2
	s_mov_b64 s[44:45], 0x100
	s_cmpk_lt_u32 s59, 0x100
	s_cbranch_scc0 .Lyng_loop2
.LBB0_1265:
	v_add_u32_e32 v133, 0x10000, v131
	ds_read_b128 v[134:137], v133
	ds_read_b128 v[138:141], v133 offset:1024
	ds_read_b128 v[142:145], v133 offset:2048
	ds_read_b128 v[146:149], v133 offset:3072
	v_add_u32_e32 v133, 0x14000, v131
	ds_read_b128 v[150:153], v133
	ds_read_b128 v[154:157], v133 offset:1024
	ds_read_b128 v[158:161], v133 offset:2048
	ds_read_b128 v[166:169], v133 offset:3072
	s_add_i32 s42, s18, s44
	s_add_i32 s21, s14, s44
	s_add_i32 s79, s12, s44
	s_addk_i32 s42, 0xff80
	s_sub_i32 vcc_lo, s42, 0x80000
	s_cmp_eq_u32 s19, 28
	s_cselect_b32 s21, s15, s21
	s_mov_b32 m0, s75
	ds_read_b128 v[170:173], v132
	ds_read_b128 v[174:177], v132 offset:1024
	ds_read_b128 v[178:181], v132 offset:2048
	ds_read_b128 v[182:185], v132 offset:3072
	ds_read_b128 v[186:189], v132 offset:4096
	ds_read_b128 v[190:193], v132 offset:5120
	ds_read_b128 v[200:203], v132 offset:6144
	ds_read_b128 v[206:209], v132 offset:7168
	s_mov_b32 m0, s72
	s_nop 0
	buffer_load_dwordx4 v130, s[4:7], vcc_lo offen lds
	s_mov_b32 m0, s75
	s_nop 0
	buffer_load_dwordx4 v0, s[4:7], s42 offen lds
	s_mov_b32 m0, s76
	s_nop 0
	buffer_load_dwordx4 v130, s[4:7], s42 offen lds
	s_waitcnt vmcnt(8)
	s_waitcnt lgkmcnt(0)
	s_setprio 1
	s_barrier
	v_mfma_f32_16x16x32_bf16 v[34:37], v[134:137], v[170:173], v[34:37]
	v_mfma_f32_16x16x32_bf16 v[18:21], v[142:145], v[170:173], v[18:21]
	v_mfma_f32_16x16x32_bf16 v[78:81], v[142:145], v[178:181], v[78:81]
	v_mfma_f32_16x16x32_bf16 v[86:89], v[134:137], v[178:181], v[86:89]
	v_mfma_f32_16x16x32_bf16 v[106:109], v[134:137], v[186:189], v[106:109]
	v_mfma_f32_16x16x32_bf16 v[102:105], v[142:145], v[186:189], v[102:105]
	v_mfma_f32_16x16x32_bf16 v[122:125], v[142:145], v[200:203], v[122:125]
	v_mfma_f32_16x16x32_bf16 v[126:129], v[134:137], v[200:203], v[126:129]
	v_mfma_f32_16x16x32_bf16 v[34:37], v[138:141], v[174:177], v[34:37]
	v_mfma_f32_16x16x32_bf16 v[18:21], v[146:149], v[174:177], v[18:21]
	v_mfma_f32_16x16x32_bf16 v[78:81], v[146:149], v[182:185], v[78:81]
	v_mfma_f32_16x16x32_bf16 v[86:89], v[138:141], v[182:185], v[86:89]
	v_mfma_f32_16x16x32_bf16 v[106:109], v[138:141], v[190:193], v[106:109]
	v_mfma_f32_16x16x32_bf16 v[102:105], v[146:149], v[190:193], v[102:105]
	v_mfma_f32_16x16x32_bf16 v[122:125], v[146:149], v[206:209], v[122:125]
	v_mfma_f32_16x16x32_bf16 v[126:129], v[138:141], v[206:209], v[126:129]
	v_mfma_f32_16x16x32_bf16 v[14:17], v[150:153], v[170:173], v[14:17]
	v_mfma_f32_16x16x32_bf16 v[38:41], v[158:161], v[170:173], v[38:41]
	v_mfma_f32_16x16x32_bf16 v[90:93], v[158:161], v[178:181], v[90:93]
	v_mfma_f32_16x16x32_bf16 v[74:77], v[150:153], v[178:181], v[74:77]
	v_mfma_f32_16x16x32_bf16 v[98:101], v[150:153], v[186:189], v[98:101]
	v_mfma_f32_16x16x32_bf16 v[110:113], v[158:161], v[186:189], v[110:113]
	v_mfma_f32_16x16x32_bf16 v[114:117], v[158:161], v[200:203], v[114:117]
	v_mfma_f32_16x16x32_bf16 v[118:121], v[150:153], v[200:203], v[118:121]
	v_mfma_f32_16x16x32_bf16 v[14:17], v[154:157], v[174:177], v[14:17]
	v_mfma_f32_16x16x32_bf16 v[38:41], v[166:169], v[174:177], v[38:41]
	v_mfma_f32_16x16x32_bf16 v[90:93], v[166:169], v[182:185], v[90:93]
	v_mfma_f32_16x16x32_bf16 v[74:77], v[154:157], v[182:185], v[74:77]
	v_mfma_f32_16x16x32_bf16 v[98:101], v[154:157], v[190:193], v[98:101]
	v_mfma_f32_16x16x32_bf16 v[110:113], v[166:169], v[190:193], v[110:113]
	v_mfma_f32_16x16x32_bf16 v[114:117], v[166:169], v[206:209], v[114:117]
	v_mfma_f32_16x16x32_bf16 v[118:121], v[154:157], v[206:209], v[118:121]
	s_barrier
	s_setprio 0
	s_cselect_b32 s79, s17, s79
	s_mov_b32 m0, s49
	s_mov_b32 s42, s6
	s_mov_b32 s43, s7
	s_sub_i32 s79, s79, s40
	ds_read_b128 v[170:173], v132 offset:16384
	ds_read_b128 v[174:177], v132 offset:17408
	ds_read_b128 v[178:181], v132 offset:18432
	ds_read_b128 v[182:185], v132 offset:19456
	ds_read_b128 v[186:189], v132 offset:20480
	ds_read_b128 v[190:193], v132 offset:21504
	ds_read_b128 v[200:203], v132 offset:22528
	ds_read_b128 v[206:209], v132 offset:23552
	buffer_load_dwordx4 v0, s[40:43], s79 offen lds
	s_mov_b32 m0, s60
	s_add_i32 vcc_lo, s79, 0x80000
	buffer_load_dwordx4 v130, s[40:43], s79 offen lds
	s_mov_b32 m0, s61
	s_sub_i32 s21, s21, s4
	buffer_load_dwordx4 v0, s[40:43], vcc_lo offen lds
	s_mov_b32 m0, s62
	s_nop 0
	buffer_load_dwordx4 v130, s[40:43], vcc_lo offen lds
	s_mov_b32 m0, s35
	s_nop 0
	buffer_load_dwordx4 v0, s[4:7], s21 offen lds
	s_waitcnt vmcnt(7)
	s_waitcnt lgkmcnt(0)
	s_setprio 1
	s_barrier
; #define PG8_STAGE(bufoff, gbase, voff) do { const int so_ = (int)(unsigned)((const char*)(gbase) - base_##voff); _Pragma("unroll") for (int _i = 0; _i < 2; ++_i) \
;         __builtin_amdgcn_raw_ptr_buffer_load_lds(rs_##voff, (PG8_LAS unsigned*)(lds + (bufoff) + ldsw + _i * 8192), 16, (int)(voff)[_i], so_, 0, 0); } while (0)
; #define PG8_LDA(dst, b, h) do { _Pragma("unroll") for (int m = 0; m < 4; ++m) _Pragma("unroll") for (int k = 0; k < 2; ++k) dst[m][k] = *(const PG8_LAS bf16x8*)(lds + PG8_SA(b, h) + aoff + m * 2048 + k * 1024); } while (0)
; #define PG8_LDB(dst, b, h) do { _Pragma("unroll") for (int n = 0; n < 2; ++n) _Pragma("unroll") for (int k = 0; k < 2; ++k) dst[n][k] = *(const PG8_LAS bf16x8*)(lds + PG8_SB(b, h) + boff + n * 2048 + k * 1024); } while (0)
; #define PG8_MMA(ai, bj, At, Bt) do { __builtin_amdgcn_s_setprio(1); _Pragma("unroll") for (int m = 0; m < 4; ++m) _Pragma("unroll") for (int n = 0; n < 2; ++n) _Pragma("unroll") for (int k = 0; k < 2; ++k) \
;         acc[ai][bj][m][n] = __builtin_amdgcn_mfma_f32_16x16x32_bf16(Bt[n][k], At[m][k], acc[ai][bj][m][n], 0, 0, 0); __builtin_amdgcn_s_setprio(0); } while (0)
; template <class Epi, class Sched, bool ALIGN_EPI = false, bool SP2 = false>
; __device__ __forceinline__ void gemm_phase(PG8_LAS unsigned char* lds, const Gemm g, const Sched& S, const Epi& E, int tid_in) {
;     ...
;             PG8_LDB(B0, 0, 0); PG8_LDB(B1, 0, 1); PG8_SCHED; PG8_LDA(At, 0, 0); PG8_STAGE(PG8_SA(1, 1), a1 + hstepA, voffA);
;             PG8_WAIT_V(8); PG8_WAIT_L(0); PG8_BAR; PG8_MMA(0, 0, At, B0); PG8_MMA(0, 1, At, B1); PG8_BAR; PG8_SCHED;
;             PG8_LDA(At, 0, 1); PG8_STAGE(PG8_SB(0, 0), b2, voffB); PG8_STAGE(PG8_SB(0, 1), b2 + hstepB, voffB); PG8_STAGE(PG8_SA(0, 0), a2, voffA);
;             PG8_WAIT_V(8); PG8_WAIT_L(0); PG8_BAR; PG8_MMA(1, 0, At, B0); PG8_MMA(1, 1, At, B1); PG8_BAR; PG8_SCHED;
;             PG8_LDB(B0, 1, 0); PG8_LDB(B1, 1, 1); PG8_SCHED; PG8_LDA(At, 1, 0); PG8_STAGE(PG8_SA(0, 1), a2 + hstepA, voffA);
;             PG8_WAIT_V(8); PG8_WAIT_L(0); PG8_BAR; PG8_MMA(0, 0, At, B0); PG8_MMA(0, 1, At, B1); PG8_BAR; PG8_SCHED;
;             PG8_LDA(At, 1, 1); PG8_STAGE(PG8_SB(1, 0), b3, voffB); PG8_STAGE(PG8_SB(1, 1), b3 + hstepB, voffB); PG8_STAGE(PG8_SA(1, 0), a3, voffA);
;             PG8_WAIT_V(8); PG8_WAIT_L(0); PG8_BAR; PG8_MMA(1, 0, At, B0); PG8_MMA(1, 1, At, B1); PG8_BAR; PG8_SCHED;
	v_mfma_f32_16x16x32_bf16 v[50:53], v[134:137], v[170:173], v[50:53]
	v_mfma_f32_16x16x32_bf16 v[30:33], v[142:145], v[170:173], v[30:33]
	v_mfma_f32_16x16x32_bf16 v[58:61], v[142:145], v[178:181], v[58:61]
	v_mfma_f32_16x16x32_bf16 v[62:65], v[134:137], v[178:181], v[62:65]
	v_mfma_f32_16x16x32_bf16 v[94:97], v[134:137], v[186:189], v[94:97]
	v_mfma_f32_16x16x32_bf16 v[82:85], v[142:145], v[186:189], v[82:85]
	v_mfma_f32_16x16x32_bf16 v[26:29], v[142:145], v[200:203], v[26:29]
	v_mfma_f32_16x16x32_bf16 v[46:49], v[134:137], v[200:203], v[46:49]
	v_mfma_f32_16x16x32_bf16 v[50:53], v[138:141], v[174:177], v[50:53]
	v_mfma_f32_16x16x32_bf16 v[30:33], v[146:149], v[174:177], v[30:33]
	v_mfma_f32_16x16x32_bf16 v[58:61], v[146:149], v[182:185], v[58:61]
	v_mfma_f32_16x16x32_bf16 v[62:65], v[138:141], v[182:185], v[62:65]
	v_mfma_f32_16x16x32_bf16 v[94:97], v[138:141], v[190:193], v[94:97]
	v_mfma_f32_16x16x32_bf16 v[82:85], v[146:149], v[190:193], v[82:85]
	v_mfma_f32_16x16x32_bf16 v[26:29], v[146:149], v[206:209], v[26:29]
	v_mfma_f32_16x16x32_bf16 v[46:49], v[138:141], v[206:209], v[46:49]
	v_mfma_f32_16x16x32_bf16 v[22:25], v[150:153], v[170:173], v[22:25]
	v_mfma_f32_16x16x32_bf16 v[10:13], v[158:161], v[170:173], v[10:13]
	v_mfma_f32_16x16x32_bf16 v[66:69], v[158:161], v[178:181], v[66:69]
	v_mfma_f32_16x16x32_bf16 v[54:57], v[150:153], v[178:181], v[54:57]
	v_mfma_f32_16x16x32_bf16 v[70:73], v[150:153], v[186:189], v[70:73]
	v_mfma_f32_16x16x32_bf16 v[42:45], v[158:161], v[186:189], v[42:45]
	v_mfma_f32_16x16x32_bf16 v[2:5], v[158:161], v[200:203], v[2:5]
	v_mfma_f32_16x16x32_bf16 v[6:9], v[150:153], v[200:203], v[6:9]
	v_mfma_f32_16x16x32_bf16 v[22:25], v[154:157], v[174:177], v[22:25]
	v_mfma_f32_16x16x32_bf16 v[10:13], v[166:169], v[174:177], v[10:13]
	v_mfma_f32_16x16x32_bf16 v[66:69], v[166:169], v[182:185], v[66:69]
	v_mfma_f32_16x16x32_bf16 v[54:57], v[154:157], v[182:185], v[54:57]
	v_mfma_f32_16x16x32_bf16 v[70:73], v[154:157], v[190:193], v[70:73]
	v_mfma_f32_16x16x32_bf16 v[42:45], v[166:169], v[190:193], v[42:45]
	v_mfma_f32_16x16x32_bf16 v[2:5], v[166:169], v[206:209], v[2:5]
	v_mfma_f32_16x16x32_bf16 v[6:9], v[154:157], v[206:209], v[6:9]
	s_barrier
	s_setprio 0
	v_add_u32_e32 v133, 0x18000, v131
	ds_read_b128 v[134:137], v133
	ds_read_b128 v[138:141], v133 offset:1024
	ds_read_b128 v[142:145], v133 offset:2048
	ds_read_b128 v[146:149], v133 offset:3072
	v_add_u32_e32 v133, 0x1c000, v131
	ds_read_b128 v[150:153], v133
	ds_read_b128 v[154:157], v133 offset:1024
	ds_read_b128 v[158:161], v133 offset:2048
	ds_read_b128 v[166:169], v133 offset:3072
	s_add_i32 vcc_lo, s21, 0x80000
	s_mov_b32 m0, s66
	ds_read_b128 v[170:173], v132 offset:32768
	ds_read_b128 v[174:177], v132 offset:33792
	ds_read_b128 v[178:181], v132 offset:34816
	ds_read_b128 v[182:185], v132 offset:35840
	ds_read_b128 v[186:189], v132 offset:36864
	ds_read_b128 v[190:193], v132 offset:37888
	ds_read_b128 v[200:203], v132 offset:38912
	ds_read_b128 v[206:209], v132 offset:39936
	s_mov_b32 m0, s63
	s_nop 0
	buffer_load_dwordx4 v130, s[4:7], s21 offen lds
	s_mov_b32 m0, s66
	s_nop 0
	buffer_load_dwordx4 v0, s[4:7], vcc_lo offen lds
	s_mov_b32 m0, s67
	s_nop 0
	buffer_load_dwordx4 v130, s[4:7], vcc_lo offen lds
	s_waitcnt vmcnt(8)
	s_waitcnt lgkmcnt(0)
	s_setprio 1
	s_barrier
	v_mfma_f32_16x16x32_bf16 v[34:37], v[134:137], v[170:173], v[34:37]
	v_mfma_f32_16x16x32_bf16 v[18:21], v[142:145], v[170:173], v[18:21]
	v_mfma_f32_16x16x32_bf16 v[78:81], v[142:145], v[178:181], v[78:81]
	v_mfma_f32_16x16x32_bf16 v[86:89], v[134:137], v[178:181], v[86:89]
	v_mfma_f32_16x16x32_bf16 v[106:109], v[134:137], v[186:189], v[106:109]
	v_mfma_f32_16x16x32_bf16 v[102:105], v[142:145], v[186:189], v[102:105]
	v_mfma_f32_16x16x32_bf16 v[122:125], v[142:145], v[200:203], v[122:125]
	v_mfma_f32_16x16x32_bf16 v[126:129], v[134:137], v[200:203], v[126:129]
	v_mfma_f32_16x16x32_bf16 v[34:37], v[138:141], v[174:177], v[34:37]
	v_mfma_f32_16x16x32_bf16 v[18:21], v[146:149], v[174:177], v[18:21]
	v_mfma_f32_16x16x32_bf16 v[78:81], v[146:149], v[182:185], v[78:81]
	v_mfma_f32_16x16x32_bf16 v[86:89], v[138:141], v[182:185], v[86:89]
	v_mfma_f32_16x16x32_bf16 v[106:109], v[138:141], v[190:193], v[106:109]
	v_mfma_f32_16x16x32_bf16 v[102:105], v[146:149], v[190:193], v[102:105]
	v_mfma_f32_16x16x32_bf16 v[122:125], v[146:149], v[206:209], v[122:125]
	v_mfma_f32_16x16x32_bf16 v[126:129], v[138:141], v[206:209], v[126:129]
	v_mfma_f32_16x16x32_bf16 v[14:17], v[150:153], v[170:173], v[14:17]
	v_mfma_f32_16x16x32_bf16 v[38:41], v[158:161], v[170:173], v[38:41]
	v_mfma_f32_16x16x32_bf16 v[90:93], v[158:161], v[178:181], v[90:93]
	v_mfma_f32_16x16x32_bf16 v[74:77], v[150:153], v[178:181], v[74:77]
	v_mfma_f32_16x16x32_bf16 v[98:101], v[150:153], v[186:189], v[98:101]
	v_mfma_f32_16x16x32_bf16 v[110:113], v[158:161], v[186:189], v[110:113]
	v_mfma_f32_16x16x32_bf16 v[114:117], v[158:161], v[200:203], v[114:117]
	v_mfma_f32_16x16x32_bf16 v[118:121], v[150:153], v[200:203], v[118:121]
	v_mfma_f32_16x16x32_bf16 v[14:17], v[154:157], v[174:177], v[14:17]
	v_mfma_f32_16x16x32_bf16 v[38:41], v[166:169], v[174:177], v[38:41]
	v_mfma_f32_16x16x32_bf16 v[90:93], v[166:169], v[182:185], v[90:93]
	v_mfma_f32_16x16x32_bf16 v[74:77], v[154:157], v[182:185], v[74:77]
	v_mfma_f32_16x16x32_bf16 v[98:101], v[154:157], v[190:193], v[98:101]
	v_mfma_f32_16x16x32_bf16 v[110:113], v[166:169], v[190:193], v[110:113]
	v_mfma_f32_16x16x32_bf16 v[114:117], v[166:169], v[206:209], v[114:117]
	v_mfma_f32_16x16x32_bf16 v[118:121], v[154:157], v[206:209], v[118:121]
	s_barrier
; #define PG8_STAGE(bufoff, gbase, voff) do { const int so_ = (int)(unsigned)((const char*)(gbase) - base_##voff); _Pragma("unroll") for (int _i = 0; _i < 2; ++_i) \
;         __builtin_amdgcn_raw_ptr_buffer_load_lds(rs_##voff, (PG8_LAS unsigned*)(lds + (bufoff) + ldsw + _i * 8192), 16, (int)(voff)[_i], so_, 0, 0); } while (0)
; #define PG8_LDA(dst, b, h) do { _Pragma("unroll") for (int m = 0; m < 4; ++m) _Pragma("unroll") for (int k = 0; k < 2; ++k) dst[m][k] = *(const PG8_LAS bf16x8*)(lds + PG8_SA(b, h) + aoff + m * 2048 + k * 1024); } while (0)
; #define PG8_WAIT_V(n) asm volatile("s_waitcnt vmcnt(" #n ")" ::: "memory")
; #define PG8_WAIT_L(n) asm volatile("s_waitcnt lgkmcnt(" #n ")" ::: "memory")
; template <class Epi, class Sched, bool ALIGN_EPI = false, bool SP2 = false>
; __device__ __forceinline__ void gemm_phase(PG8_LAS unsigned char* lds, const Gemm g, const Sched& S, const Epi& E, int tid_in) {
;     ...
;         for (int t = 0; t < nt; t += 2) {
;             const bool last = (t == nt - 2);
;             const char* a1 = cA + (size_t)(t + 1) * kstep;
;             const char* a2 = last ? nA : cA + (size_t)(t + 2) * kstep; const char* b2 = last ? nB : cB + (size_t)(t + 2) * kstep;
;             const char* a3 = a2 + kstep; const char* b3 = b2 + kstep;
;             if (last && has_next) S.a_ready(nxt);
;     ...
;             PG8_LDB(B0, 0, 0); PG8_LDB(B1, 0, 1); PG8_SCHED; PG8_LDA(At, 0, 0); PG8_STAGE(PG8_SA(1, 1), a1 + hstepA, voffA);
;             PG8_WAIT_V(8); PG8_WAIT_L(0); PG8_BAR; PG8_MMA(0, 0, At, B0); PG8_MMA(0, 1, At, B1); PG8_BAR; PG8_SCHED;
;             PG8_LDA(At, 0, 1); PG8_STAGE(PG8_SB(0, 0), b2, voffB); PG8_STAGE(PG8_SB(0, 1), b2 + hstepB, voffB); PG8_STAGE(PG8_SA(0, 0), a2, voffA);
;             PG8_WAIT_V(8); PG8_WAIT_L(0); PG8_BAR; PG8_MMA(1, 0, At, B0); PG8_MMA(1, 1, At, B1); PG8_BAR; PG8_SCHED;
;             PG8_LDB(B0, 1, 0); PG8_LDB(B1, 1, 1); PG8_SCHED; PG8_LDA(At, 1, 0); PG8_STAGE(PG8_SA(0, 1), a2 + hstepA, voffA);
;             PG8_WAIT_V(8); PG8_WAIT_L(0); PG8_BAR; PG8_MMA(0, 0, At, B0); PG8_MMA(0, 1, At, B1); PG8_BAR; PG8_SCHED;
;             PG8_LDA(At, 1, 1); PG8_STAGE(PG8_SB(1, 0), b3, voffB); PG8_STAGE(PG8_SB(1, 1), b3 + hstepB, voffB); PG8_STAGE(PG8_SA(1, 0), a3, voffA);
;             PG8_WAIT_V(8); PG8_WAIT_L(0); PG8_BAR; PG8_MMA(1, 0, At, B0); PG8_MMA(1, 1, At, B1); PG8_BAR; PG8_SCHED;
	s_setprio 0
	s_mov_b32 m0, s68
	s_add_i32 vcc_lo, s79, 0x80
	ds_read_b128 v[170:173], v132 offset:49152
	ds_read_b128 v[174:177], v132 offset:50176
	ds_read_b128 v[178:181], v132 offset:51200
	ds_read_b128 v[182:185], v132 offset:52224
	ds_read_b128 v[186:189], v132 offset:53248
	ds_read_b128 v[190:193], v132 offset:54272
	ds_read_b128 v[200:203], v132 offset:55296
	ds_read_b128 v[206:209], v132 offset:56320
	buffer_load_dwordx4 v0, s[40:43], vcc_lo offen lds
	s_mov_b32 m0, s69
	s_add_i32 s79, s79, 0x80080
	buffer_load_dwordx4 v130, s[40:43], vcc_lo offen lds
	s_mov_b32 m0, s73
	s_addk_i32 s21, 0x80
	buffer_load_dwordx4 v0, s[40:43], s79 offen lds
	s_mov_b32 m0, s74
	s_nop 0
	buffer_load_dwordx4 v130, s[40:43], s79 offen lds
	s_mov_b32 m0, s71
	s_nop 0
	buffer_load_dwordx4 v0, s[4:7], s21 offen lds
	s_waitcnt vmcnt(7)
	s_waitcnt lgkmcnt(0)
	s_setprio 1
	s_barrier
	v_mfma_f32_16x16x32_bf16 v[50:53], v[134:137], v[170:173], v[50:53]
	v_mfma_f32_16x16x32_bf16 v[30:33], v[142:145], v[170:173], v[30:33]
	v_mfma_f32_16x16x32_bf16 v[58:61], v[142:145], v[178:181], v[58:61]
	v_mfma_f32_16x16x32_bf16 v[62:65], v[134:137], v[178:181], v[62:65]
	v_mfma_f32_16x16x32_bf16 v[94:97], v[134:137], v[186:189], v[94:97]
	v_mfma_f32_16x16x32_bf16 v[82:85], v[142:145], v[186:189], v[82:85]
	v_mfma_f32_16x16x32_bf16 v[26:29], v[142:145], v[200:203], v[26:29]
	v_mfma_f32_16x16x32_bf16 v[46:49], v[134:137], v[200:203], v[46:49]
	v_mfma_f32_16x16x32_bf16 v[50:53], v[138:141], v[174:177], v[50:53]
	v_mfma_f32_16x16x32_bf16 v[30:33], v[146:149], v[174:177], v[30:33]
	v_mfma_f32_16x16x32_bf16 v[58:61], v[146:149], v[182:185], v[58:61]
	v_mfma_f32_16x16x32_bf16 v[62:65], v[138:141], v[182:185], v[62:65]
	v_mfma_f32_16x16x32_bf16 v[94:97], v[138:141], v[190:193], v[94:97]
	v_mfma_f32_16x16x32_bf16 v[82:85], v[146:149], v[190:193], v[82:85]
	v_mfma_f32_16x16x32_bf16 v[26:29], v[146:149], v[206:209], v[26:29]
	v_mfma_f32_16x16x32_bf16 v[46:49], v[138:141], v[206:209], v[46:49]
	v_mfma_f32_16x16x32_bf16 v[22:25], v[150:153], v[170:173], v[22:25]
	v_mfma_f32_16x16x32_bf16 v[10:13], v[158:161], v[170:173], v[10:13]
	v_mfma_f32_16x16x32_bf16 v[66:69], v[158:161], v[178:181], v[66:69]
	v_mfma_f32_16x16x32_bf16 v[54:57], v[150:153], v[178:181], v[54:57]
	v_mfma_f32_16x16x32_bf16 v[70:73], v[150:153], v[186:189], v[70:73]
	v_mfma_f32_16x16x32_bf16 v[42:45], v[158:161], v[186:189], v[42:45]
	v_mfma_f32_16x16x32_bf16 v[2:5], v[158:161], v[200:203], v[2:5]
	v_mfma_f32_16x16x32_bf16 v[6:9], v[150:153], v[200:203], v[6:9]
	v_mfma_f32_16x16x32_bf16 v[22:25], v[154:157], v[174:177], v[22:25]
	v_mfma_f32_16x16x32_bf16 v[10:13], v[166:169], v[174:177], v[10:13]
	v_mfma_f32_16x16x32_bf16 v[66:69], v[166:169], v[182:185], v[66:69]
	v_mfma_f32_16x16x32_bf16 v[54:57], v[154:157], v[182:185], v[54:57]
	v_mfma_f32_16x16x32_bf16 v[70:73], v[154:157], v[190:193], v[70:73]
	v_mfma_f32_16x16x32_bf16 v[42:45], v[166:169], v[190:193], v[42:45]
	v_mfma_f32_16x16x32_bf16 v[2:5], v[166:169], v[206:209], v[2:5]
	v_mfma_f32_16x16x32_bf16 v[6:9], v[154:157], v[206:209], v[6:9]
	s_barrier
	s_setprio 0
	s_add_i32 s19, s19, 2
	s_add_u32 s44, s44, 0x100
	s_addc_u32 s45, s45, 0
	s_cmp_gt_u32 s19, 29
	s_cbranch_scc0 .LBB0_1265
	s_branch .Lyng_after2
.Lyng_loop2:
	v_add_u32_e32 v133, 0x10000, v131
	ds_read_b128 v[134:137], v133
	ds_read_b128 v[138:141], v133 offset:1024
	ds_read_b128 v[142:145], v133 offset:2048
	ds_read_b128 v[146:149], v133 offset:3072
	v_add_u32_e32 v133, 0x14000, v131
	ds_read_b128 v[150:153], v133
	ds_read_b128 v[154:157], v133 offset:1024
	ds_read_b128 v[158:161], v133 offset:2048
	ds_read_b128 v[166:169], v133 offset:3072
	s_add_i32 s42, s18, s44
	s_add_i32 s21, s14, s44
	s_add_i32 s79, s12, s44
	s_addk_i32 s42, 0xff80
	s_sub_i32 vcc_lo, s42, 0x80000
	s_cmp_eq_u32 s19, 28
	s_cselect_b32 s21, s15, s21
	s_mov_b32 m0, s75
	ds_read_b128 v[170:173], v132
	ds_read_b128 v[174:177], v132 offset:1024
	ds_read_b128 v[178:181], v132 offset:2048
	ds_read_b128 v[182:185], v132 offset:3072
	ds_read_b128 v[186:189], v132 offset:4096
	ds_read_b128 v[190:193], v132 offset:5120
	ds_read_b128 v[200:203], v132 offset:6144
	ds_read_b128 v[206:209], v132 offset:7168
	s_mov_b32 m0, s72
	s_nop 0
	buffer_load_dwordx4 v130, s[4:7], vcc_lo offen lds
	s_mov_b32 m0, s75
	s_nop 0
	buffer_load_dwordx4 v0, s[4:7], s42 offen lds
	s_mov_b32 m0, s76
	s_nop 0
	buffer_load_dwordx4 v130, s[4:7], s42 offen lds
	s_waitcnt vmcnt(8)
	s_waitcnt lgkmcnt(0)
	s_setprio 2
	s_barrier
	v_mfma_f32_16x16x32_bf16 v[34:37], v[134:137], v[170:173], v[34:37]
	v_mfma_f32_16x16x32_bf16 v[18:21], v[142:145], v[170:173], v[18:21]
	v_mfma_f32_16x16x32_bf16 v[78:81], v[142:145], v[178:181], v[78:81]
	v_mfma_f32_16x16x32_bf16 v[86:89], v[134:137], v[178:181], v[86:89]
	v_mfma_f32_16x16x32_bf16 v[106:109], v[134:137], v[186:189], v[106:109]
	v_mfma_f32_16x16x32_bf16 v[102:105], v[142:145], v[186:189], v[102:105]
	v_mfma_f32_16x16x32_bf16 v[122:125], v[142:145], v[200:203], v[122:125]
	v_mfma_f32_16x16x32_bf16 v[126:129], v[134:137], v[200:203], v[126:129]
	v_mfma_f32_16x16x32_bf16 v[34:37], v[138:141], v[174:177], v[34:37]
	v_mfma_f32_16x16x32_bf16 v[18:21], v[146:149], v[174:177], v[18:21]
	v_mfma_f32_16x16x32_bf16 v[78:81], v[146:149], v[182:185], v[78:81]
	v_mfma_f32_16x16x32_bf16 v[86:89], v[138:141], v[182:185], v[86:89]
	v_mfma_f32_16x16x32_bf16 v[106:109], v[138:141], v[190:193], v[106:109]
	v_mfma_f32_16x16x32_bf16 v[102:105], v[146:149], v[190:193], v[102:105]
	v_mfma_f32_16x16x32_bf16 v[122:125], v[146:149], v[206:209], v[122:125]
	v_mfma_f32_16x16x32_bf16 v[126:129], v[138:141], v[206:209], v[126:129]
	v_mfma_f32_16x16x32_bf16 v[14:17], v[150:153], v[170:173], v[14:17]
	v_mfma_f32_16x16x32_bf16 v[38:41], v[158:161], v[170:173], v[38:41]
	v_mfma_f32_16x16x32_bf16 v[90:93], v[158:161], v[178:181], v[90:93]
	v_mfma_f32_16x16x32_bf16 v[74:77], v[150:153], v[178:181], v[74:77]
	v_mfma_f32_16x16x32_bf16 v[98:101], v[150:153], v[186:189], v[98:101]
	v_mfma_f32_16x16x32_bf16 v[110:113], v[158:161], v[186:189], v[110:113]
	v_mfma_f32_16x16x32_bf16 v[114:117], v[158:161], v[200:203], v[114:117]
	v_mfma_f32_16x16x32_bf16 v[118:121], v[150:153], v[200:203], v[118:121]
	v_mfma_f32_16x16x32_bf16 v[14:17], v[154:157], v[174:177], v[14:17]
	v_mfma_f32_16x16x32_bf16 v[38:41], v[166:169], v[174:177], v[38:41]
	v_mfma_f32_16x16x32_bf16 v[90:93], v[166:169], v[182:185], v[90:93]
	v_mfma_f32_16x16x32_bf16 v[74:77], v[154:157], v[182:185], v[74:77]
	v_mfma_f32_16x16x32_bf16 v[98:101], v[154:157], v[190:193], v[98:101]
	v_mfma_f32_16x16x32_bf16 v[110:113], v[166:169], v[190:193], v[110:113]
	v_mfma_f32_16x16x32_bf16 v[114:117], v[166:169], v[206:209], v[114:117]
	v_mfma_f32_16x16x32_bf16 v[118:121], v[154:157], v[206:209], v[118:121]
	s_barrier
; #define PG8_STAGE(bufoff, gbase, voff) do { const int so_ = (int)(unsigned)((const char*)(gbase) - base_##voff); _Pragma("unroll") for (int _i = 0; _i < 2; ++_i) \
;         __builtin_amdgcn_raw_ptr_buffer_load_lds(rs_##voff, (PG8_LAS unsigned*)(lds + (bufoff) + ldsw + _i * 8192), 16, (int)(voff)[_i], so_, 0, 0); } while (0)
; #define PG8_LDA(dst, b, h) do { _Pragma("unroll") for (int m = 0; m < 4; ++m) _Pragma("unroll") for (int k = 0; k < 2; ++k) dst[m][k] = *(const PG8_LAS bf16x8*)(lds + PG8_SA(b, h) + aoff + m * 2048 + k * 1024); } while (0)
; #define PG8_LDB(dst, b, h) do { _Pragma("unroll") for (int n = 0; n < 2; ++n) _Pragma("unroll") for (int k = 0; k < 2; ++k) dst[n][k] = *(const PG8_LAS bf16x8*)(lds + PG8_SB(b, h) + boff + n * 2048 + k * 1024); } while (0)
; #define PG8_MMA(ai, bj, At, Bt) do { __builtin_amdgcn_s_setprio(1); _Pragma("unroll") for (int m = 0; m < 4; ++m) _Pragma("unroll") for (int n = 0; n < 2; ++n) _Pragma("unroll") for (int k = 0; k < 2; ++k) \
;         acc[ai][bj][m][n] = __builtin_amdgcn_mfma_f32_16x16x32_bf16(Bt[n][k], At[m][k], acc[ai][bj][m][n], 0, 0, 0); __builtin_amdgcn_s_setprio(0); } while (0)
; template <class Epi, class Sched, bool ALIGN_EPI = false, bool SP2 = false>
; __device__ __forceinline__ void gemm_phase(PG8_LAS unsigned char* lds, const Gemm g, const Sched& S, const Epi& E, int tid_in) {
;     ...
;             PG8_LDB(B0, 0, 0); PG8_LDB(B1, 0, 1); PG8_SCHED; PG8_LDA(At, 0, 0); PG8_STAGE(PG8_SA(1, 1), a1 + hstepA, voffA);
;             PG8_WAIT_V(8); PG8_WAIT_L(0); PG8_BAR; PG8_MMA(0, 0, At, B0); PG8_MMA(0, 1, At, B1); PG8_BAR; PG8_SCHED;
;             PG8_LDA(At, 0, 1); PG8_STAGE(PG8_SB(0, 0), b2, voffB); PG8_STAGE(PG8_SB(0, 1), b2 + hstepB, voffB); PG8_STAGE(PG8_SA(0, 0), a2, voffA);
;             PG8_WAIT_V(8); PG8_WAIT_L(0); PG8_BAR; PG8_MMA(1, 0, At, B0); PG8_MMA(1, 1, At, B1); PG8_BAR; PG8_SCHED;
;             PG8_LDB(B0, 1, 0); PG8_LDB(B1, 1, 1); PG8_SCHED; PG8_LDA(At, 1, 0); PG8_STAGE(PG8_SA(0, 1), a2 + hstepA, voffA);
;             PG8_WAIT_V(8); PG8_WAIT_L(0); PG8_BAR; PG8_MMA(0, 0, At, B0); PG8_MMA(0, 1, At, B1); PG8_BAR; PG8_SCHED;
;             PG8_LDA(At, 1, 1); PG8_STAGE(PG8_SB(1, 0), b3, voffB); PG8_STAGE(PG8_SB(1, 1), b3 + hstepB, voffB); PG8_STAGE(PG8_SA(1, 0), a3, voffA);
;             PG8_WAIT_V(8); PG8_WAIT_L(0); PG8_BAR; PG8_MMA(1, 0, At, B0); PG8_MMA(1, 1, At, B1); PG8_BAR; PG8_SCHED;
	s_setprio 1
	s_cselect_b32 s79, s17, s79
	s_mov_b32 m0, s49
	s_mov_b32 s42, s6
	s_mov_b32 s43, s7
	s_sub_i32 s79, s79, s40
	ds_read_b128 v[170:173], v132 offset:16384
	ds_read_b128 v[174:177], v132 offset:17408
	ds_read_b128 v[178:181], v132 offset:18432
	ds_read_b128 v[182:185], v132 offset:19456
	ds_read_b128 v[186:189], v132 offset:20480
	ds_read_b128 v[190:193], v132 offset:21504
	ds_read_b128 v[200:203], v132 offset:22528
	ds_read_b128 v[206:209], v132 offset:23552
	buffer_load_dwordx4 v0, s[40:43], s79 offen lds
	s_mov_b32 m0, s60
	s_add_i32 vcc_lo, s79, 0x80000
	buffer_load_dwordx4 v130, s[40:43], s79 offen lds
	s_mov_b32 m0, s61
	s_sub_i32 s21, s21, s4
	buffer_load_dwordx4 v0, s[40:43], vcc_lo offen lds
	s_mov_b32 m0, s62
	s_nop 0
	buffer_load_dwordx4 v130, s[40:43], vcc_lo offen lds
	s_mov_b32 m0, s35
	s_nop 0
	buffer_load_dwordx4 v0, s[4:7], s21 offen lds
	s_waitcnt vmcnt(7)
	s_waitcnt lgkmcnt(0)
	s_setprio 2
	s_barrier
	v_mfma_f32_16x16x32_bf16 v[50:53], v[134:137], v[170:173], v[50:53]
	v_mfma_f32_16x16x32_bf16 v[30:33], v[142:145], v[170:173], v[30:33]
	v_mfma_f32_16x16x32_bf16 v[58:61], v[142:145], v[178:181], v[58:61]
	v_mfma_f32_16x16x32_bf16 v[62:65], v[134:137], v[178:181], v[62:65]
	v_mfma_f32_16x16x32_bf16 v[94:97], v[134:137], v[186:189], v[94:97]
	v_mfma_f32_16x16x32_bf16 v[82:85], v[142:145], v[186:189], v[82:85]
	v_mfma_f32_16x16x32_bf16 v[26:29], v[142:145], v[200:203], v[26:29]
	v_mfma_f32_16x16x32_bf16 v[46:49], v[134:137], v[200:203], v[46:49]
	v_mfma_f32_16x16x32_bf16 v[50:53], v[138:141], v[174:177], v[50:53]
	v_mfma_f32_16x16x32_bf16 v[30:33], v[146:149], v[174:177], v[30:33]
	v_mfma_f32_16x16x32_bf16 v[58:61], v[146:149], v[182:185], v[58:61]
	v_mfma_f32_16x16x32_bf16 v[62:65], v[138:141], v[182:185], v[62:65]
	v_mfma_f32_16x16x32_bf16 v[94:97], v[138:141], v[190:193], v[94:97]
	v_mfma_f32_16x16x32_bf16 v[82:85], v[146:149], v[190:193], v[82:85]
	v_mfma_f32_16x16x32_bf16 v[26:29], v[146:149], v[206:209], v[26:29]
	v_mfma_f32_16x16x32_bf16 v[46:49], v[138:141], v[206:209], v[46:49]
	v_mfma_f32_16x16x32_bf16 v[22:25], v[150:153], v[170:173], v[22:25]
	v_mfma_f32_16x16x32_bf16 v[10:13], v[158:161], v[170:173], v[10:13]
	v_mfma_f32_16x16x32_bf16 v[66:69], v[158:161], v[178:181], v[66:69]
	v_mfma_f32_16x16x32_bf16 v[54:57], v[150:153], v[178:181], v[54:57]
	v_mfma_f32_16x16x32_bf16 v[70:73], v[150:153], v[186:189], v[70:73]
	v_mfma_f32_16x16x32_bf16 v[42:45], v[158:161], v[186:189], v[42:45]
	v_mfma_f32_16x16x32_bf16 v[2:5], v[158:161], v[200:203], v[2:5]
	v_mfma_f32_16x16x32_bf16 v[6:9], v[150:153], v[200:203], v[6:9]
	v_mfma_f32_16x16x32_bf16 v[22:25], v[154:157], v[174:177], v[22:25]
	v_mfma_f32_16x16x32_bf16 v[10:13], v[166:169], v[174:177], v[10:13]
	v_mfma_f32_16x16x32_bf16 v[66:69], v[166:169], v[182:185], v[66:69]
	v_mfma_f32_16x16x32_bf16 v[54:57], v[154:157], v[182:185], v[54:57]
	v_mfma_f32_16x16x32_bf16 v[70:73], v[154:157], v[190:193], v[70:73]
	v_mfma_f32_16x16x32_bf16 v[42:45], v[166:169], v[190:193], v[42:45]
	v_mfma_f32_16x16x32_bf16 v[2:5], v[166:169], v[206:209], v[2:5]
	v_mfma_f32_16x16x32_bf16 v[6:9], v[154:157], v[206:209], v[6:9]
	s_barrier
	s_setprio 1
	v_add_u32_e32 v133, 0x18000, v131
	ds_read_b128 v[134:137], v133
	ds_read_b128 v[138:141], v133 offset:1024
	ds_read_b128 v[142:145], v133 offset:2048
	ds_read_b128 v[146:149], v133 offset:3072
	v_add_u32_e32 v133, 0x1c000, v131
	ds_read_b128 v[150:153], v133
	ds_read_b128 v[154:157], v133 offset:1024
	ds_read_b128 v[158:161], v133 offset:2048
	ds_read_b128 v[166:169], v133 offset:3072
	s_add_i32 vcc_lo, s21, 0x80000
	s_mov_b32 m0, s66
	ds_read_b128 v[170:173], v132 offset:32768
	ds_read_b128 v[174:177], v132 offset:33792
	ds_read_b128 v[178:181], v132 offset:34816
	ds_read_b128 v[182:185], v132 offset:35840
	ds_read_b128 v[186:189], v132 offset:36864
	ds_read_b128 v[190:193], v132 offset:37888
	ds_read_b128 v[200:203], v132 offset:38912
	ds_read_b128 v[206:209], v132 offset:39936
	s_mov_b32 m0, s63
	s_nop 0
	buffer_load_dwordx4 v130, s[4:7], s21 offen lds
	s_mov_b32 m0, s66
	s_nop 0
	buffer_load_dwordx4 v0, s[4:7], vcc_lo offen lds
	s_mov_b32 m0, s67
	s_nop 0
	buffer_load_dwordx4 v130, s[4:7], vcc_lo offen lds
	s_waitcnt vmcnt(8)
	s_waitcnt lgkmcnt(0)
	s_setprio 2
	s_barrier
	v_mfma_f32_16x16x32_bf16 v[34:37], v[134:137], v[170:173], v[34:37]
	v_mfma_f32_16x16x32_bf16 v[18:21], v[142:145], v[170:173], v[18:21]
	v_mfma_f32_16x16x32_bf16 v[78:81], v[142:145], v[178:181], v[78:81]
	v_mfma_f32_16x16x32_bf16 v[86:89], v[134:137], v[178:181], v[86:89]
	v_mfma_f32_16x16x32_bf16 v[106:109], v[134:137], v[186:189], v[106:109]
	v_mfma_f32_16x16x32_bf16 v[102:105], v[142:145], v[186:189], v[102:105]
	v_mfma_f32_16x16x32_bf16 v[122:125], v[142:145], v[200:203], v[122:125]
	v_mfma_f32_16x16x32_bf16 v[126:129], v[134:137], v[200:203], v[126:129]
	v_mfma_f32_16x16x32_bf16 v[34:37], v[138:141], v[174:177], v[34:37]
	v_mfma_f32_16x16x32_bf16 v[18:21], v[146:149], v[174:177], v[18:21]
	v_mfma_f32_16x16x32_bf16 v[78:81], v[146:149], v[182:185], v[78:81]
	v_mfma_f32_16x16x32_bf16 v[86:89], v[138:141], v[182:185], v[86:89]
	v_mfma_f32_16x16x32_bf16 v[106:109], v[138:141], v[190:193], v[106:109]
	v_mfma_f32_16x16x32_bf16 v[102:105], v[146:149], v[190:193], v[102:105]
	v_mfma_f32_16x16x32_bf16 v[122:125], v[146:149], v[206:209], v[122:125]
	v_mfma_f32_16x16x32_bf16 v[126:129], v[138:141], v[206:209], v[126:129]
	v_mfma_f32_16x16x32_bf16 v[14:17], v[150:153], v[170:173], v[14:17]
	v_mfma_f32_16x16x32_bf16 v[38:41], v[158:161], v[170:173], v[38:41]
	v_mfma_f32_16x16x32_bf16 v[90:93], v[158:161], v[178:181], v[90:93]
	v_mfma_f32_16x16x32_bf16 v[74:77], v[150:153], v[178:181], v[74:77]
	v_mfma_f32_16x16x32_bf16 v[98:101], v[150:153], v[186:189], v[98:101]
	v_mfma_f32_16x16x32_bf16 v[110:113], v[158:161], v[186:189], v[110:113]
	v_mfma_f32_16x16x32_bf16 v[114:117], v[158:161], v[200:203], v[114:117]
	v_mfma_f32_16x16x32_bf16 v[118:121], v[150:153], v[200:203], v[118:121]
	v_mfma_f32_16x16x32_bf16 v[14:17], v[154:157], v[174:177], v[14:17]
	v_mfma_f32_16x16x32_bf16 v[38:41], v[166:169], v[174:177], v[38:41]
	v_mfma_f32_16x16x32_bf16 v[90:93], v[166:169], v[182:185], v[90:93]
	v_mfma_f32_16x16x32_bf16 v[74:77], v[154:157], v[182:185], v[74:77]
	v_mfma_f32_16x16x32_bf16 v[98:101], v[154:157], v[190:193], v[98:101]
	v_mfma_f32_16x16x32_bf16 v[110:113], v[166:169], v[190:193], v[110:113]
	v_mfma_f32_16x16x32_bf16 v[114:117], v[166:169], v[206:209], v[114:117]
	v_mfma_f32_16x16x32_bf16 v[118:121], v[154:157], v[206:209], v[118:121]
	s_barrier
;     static __device__ __forceinline__ bool last_of_chain(const Unit& u) { return (u.pn >> 3) == 2; }
; #define PG8_STAGE(bufoff, gbase, voff) do { const int so_ = (int)(unsigned)((const char*)(gbase) - base_##voff); _Pragma("unroll") for (int _i = 0; _i < 2; ++_i) \
;         __builtin_amdgcn_raw_ptr_buffer_load_lds(rs_##voff, (PG8_LAS unsigned*)(lds + (bufoff) + ldsw + _i * 8192), 16, (int)(voff)[_i], so_, 0, 0); } while (0)
; #define PG8_LDA(dst, b, h) do { _Pragma("unroll") for (int m = 0; m < 4; ++m) _Pragma("unroll") for (int k = 0; k < 2; ++k) dst[m][k] = *(const PG8_LAS bf16x8*)(lds + PG8_SA(b, h) + aoff + m * 2048 + k * 1024); } while (0)
; template <class Epi, class Sched, bool ALIGN_EPI = false, bool SP2 = false>
; __device__ __forceinline__ void gemm_phase(PG8_LAS unsigned char* lds, const Gemm g, const Sched& S, const Epi& E, int tid_in) {
;     ...
;             PG8_LDB(B0, 0, 0); PG8_LDB(B1, 0, 1); PG8_SCHED; PG8_LDA(At, 0, 0); PG8_STAGE(PG8_SA(1, 1), a1 + hstepA, voffA);
;             PG8_WAIT_V(8); PG8_WAIT_L(0); PG8_BAR; PG8_MMA(0, 0, At, B0); PG8_MMA(0, 1, At, B1); PG8_BAR; PG8_SCHED;
;             PG8_LDA(At, 0, 1); PG8_STAGE(PG8_SB(0, 0), b2, voffB); PG8_STAGE(PG8_SB(0, 1), b2 + hstepB, voffB); PG8_STAGE(PG8_SA(0, 0), a2, voffA);
;             PG8_WAIT_V(8); PG8_WAIT_L(0); PG8_BAR; PG8_MMA(1, 0, At, B0); PG8_MMA(1, 1, At, B1); PG8_BAR; PG8_SCHED;
;             PG8_LDB(B0, 1, 0); PG8_LDB(B1, 1, 1); PG8_SCHED; PG8_LDA(At, 1, 0); PG8_STAGE(PG8_SA(0, 1), a2 + hstepA, voffA);
;             PG8_WAIT_V(8); PG8_WAIT_L(0); PG8_BAR; PG8_MMA(0, 0, At, B0); PG8_MMA(0, 1, At, B1); PG8_BAR; PG8_SCHED;
;             PG8_LDA(At, 1, 1); PG8_STAGE(PG8_SB(1, 0), b3, voffB); PG8_STAGE(PG8_SB(1, 1), b3 + hstepB, voffB); PG8_STAGE(PG8_SA(1, 0), a3, voffA);
;             PG8_WAIT_V(8); PG8_WAIT_L(0); PG8_BAR; PG8_MMA(1, 0, At, B0); PG8_MMA(1, 1, At, B1); PG8_BAR; PG8_SCHED;
;     ...
;         if (!has_next) break;
;         bool zero_acc = true; if constexpr (Epi::CHAIN) zero_acc = Epi::last_of_chain(cur);
;         if (zero_acc) {
; #pragma unroll
;         for (int a = 0; a < 2; ++a)
; #pragma unroll
;             for (int b = 0; b < 2; ++b)
; #pragma unroll
;                 for (int m = 0; m < 4; ++m)
; #pragma unroll
;                     for (int n = 0; n < 2; ++n) acc[a][b][m][n] = (f32x4){0.f, 0.f, 0.f, 0.f};
;         }
;         cur = nxt; cA = nA; cB = nB; ++ui;
	s_setprio 1
	s_mov_b32 m0, s68
	s_add_i32 vcc_lo, s79, 0x80
	ds_read_b128 v[170:173], v132 offset:49152
	ds_read_b128 v[174:177], v132 offset:50176
	ds_read_b128 v[178:181], v132 offset:51200
	ds_read_b128 v[182:185], v132 offset:52224
	ds_read_b128 v[186:189], v132 offset:53248
	ds_read_b128 v[190:193], v132 offset:54272
	ds_read_b128 v[200:203], v132 offset:55296
	ds_read_b128 v[206:209], v132 offset:56320
	buffer_load_dwordx4 v0, s[40:43], vcc_lo offen lds
	s_mov_b32 m0, s69
	s_add_i32 s79, s79, 0x80080
	buffer_load_dwordx4 v130, s[40:43], vcc_lo offen lds
	s_mov_b32 m0, s73
	s_addk_i32 s21, 0x80
	buffer_load_dwordx4 v0, s[40:43], s79 offen lds
	s_mov_b32 m0, s74
	s_nop 0
	buffer_load_dwordx4 v130, s[40:43], s79 offen lds
	s_mov_b32 m0, s71
	s_nop 0
	buffer_load_dwordx4 v0, s[4:7], s21 offen lds
	s_waitcnt vmcnt(7)
	s_waitcnt lgkmcnt(0)
	s_setprio 2
	s_barrier
	v_mfma_f32_16x16x32_bf16 v[50:53], v[134:137], v[170:173], v[50:53]
	v_mfma_f32_16x16x32_bf16 v[30:33], v[142:145], v[170:173], v[30:33]
	v_mfma_f32_16x16x32_bf16 v[58:61], v[142:145], v[178:181], v[58:61]
	v_mfma_f32_16x16x32_bf16 v[62:65], v[134:137], v[178:181], v[62:65]
	v_mfma_f32_16x16x32_bf16 v[94:97], v[134:137], v[186:189], v[94:97]
	v_mfma_f32_16x16x32_bf16 v[82:85], v[142:145], v[186:189], v[82:85]
	v_mfma_f32_16x16x32_bf16 v[26:29], v[142:145], v[200:203], v[26:29]
	v_mfma_f32_16x16x32_bf16 v[46:49], v[134:137], v[200:203], v[46:49]
	v_mfma_f32_16x16x32_bf16 v[50:53], v[138:141], v[174:177], v[50:53]
	v_mfma_f32_16x16x32_bf16 v[30:33], v[146:149], v[174:177], v[30:33]
	v_mfma_f32_16x16x32_bf16 v[58:61], v[146:149], v[182:185], v[58:61]
	v_mfma_f32_16x16x32_bf16 v[62:65], v[138:141], v[182:185], v[62:65]
	v_mfma_f32_16x16x32_bf16 v[94:97], v[138:141], v[190:193], v[94:97]
	v_mfma_f32_16x16x32_bf16 v[82:85], v[146:149], v[190:193], v[82:85]
	v_mfma_f32_16x16x32_bf16 v[26:29], v[146:149], v[206:209], v[26:29]
	v_mfma_f32_16x16x32_bf16 v[46:49], v[138:141], v[206:209], v[46:49]
	v_mfma_f32_16x16x32_bf16 v[22:25], v[150:153], v[170:173], v[22:25]
	v_mfma_f32_16x16x32_bf16 v[10:13], v[158:161], v[170:173], v[10:13]
	v_mfma_f32_16x16x32_bf16 v[66:69], v[158:161], v[178:181], v[66:69]
	v_mfma_f32_16x16x32_bf16 v[54:57], v[150:153], v[178:181], v[54:57]
	v_mfma_f32_16x16x32_bf16 v[70:73], v[150:153], v[186:189], v[70:73]
	v_mfma_f32_16x16x32_bf16 v[42:45], v[158:161], v[186:189], v[42:45]
	v_mfma_f32_16x16x32_bf16 v[2:5], v[158:161], v[200:203], v[2:5]
	v_mfma_f32_16x16x32_bf16 v[6:9], v[150:153], v[200:203], v[6:9]
	v_mfma_f32_16x16x32_bf16 v[22:25], v[154:157], v[174:177], v[22:25]
	v_mfma_f32_16x16x32_bf16 v[10:13], v[166:169], v[174:177], v[10:13]
	v_mfma_f32_16x16x32_bf16 v[66:69], v[166:169], v[182:185], v[66:69]
	v_mfma_f32_16x16x32_bf16 v[54:57], v[154:157], v[182:185], v[54:57]
	v_mfma_f32_16x16x32_bf16 v[70:73], v[154:157], v[190:193], v[70:73]
	v_mfma_f32_16x16x32_bf16 v[42:45], v[166:169], v[190:193], v[42:45]
	v_mfma_f32_16x16x32_bf16 v[2:5], v[166:169], v[206:209], v[2:5]
	v_mfma_f32_16x16x32_bf16 v[6:9], v[154:157], v[206:209], v[6:9]
	s_barrier
	s_setprio 1
	s_add_i32 s19, s19, 2
	s_add_u32 s44, s44, 0x100
	s_addc_u32 s45, s45, 0
	s_cmp_gt_u32 s19, 29
	s_cbranch_scc0 .Lyng_loop2
	s_setprio 0
.Lyng_after2:
	s_andn2_b64 vcc, exec, s[38:39]
	s_cbranch_vccnz .LBB0_1257
	v_mov_b32_e32 v2, 0
	s_mov_b64 s[12:13], s[24:25]
	s_mov_b32 s10, s16
	s_mov_b32 s48, s20
	s_mov_b64 s[14:15], s[22:23]
	s_mov_b32 s13, s78
	v_mov_b32_e32 v3, v2
	v_mov_b32_e32 v4, v2
	v_mov_b32_e32 v5, v2
	v_mov_b32_e32 v6, v2
	v_mov_b32_e32 v7, v2
	v_mov_b32_e32 v8, v2
	v_mov_b32_e32 v9, v2
	v_mov_b32_e32 v42, v2
	v_mov_b32_e32 v43, v2
	v_mov_b32_e32 v44, v2
	v_mov_b32_e32 v45, v2
	v_mov_b32_e32 v70, v2
	v_mov_b32_e32 v71, v2
	v_mov_b32_e32 v72, v2
	v_mov_b32_e32 v73, v2
	v_mov_b32_e32 v66, v2
	v_mov_b32_e32 v67, v2
	v_mov_b32_e32 v68, v2
	v_mov_b32_e32 v69, v2
	v_mov_b32_e32 v54, v2
	v_mov_b32_e32 v55, v2
	v_mov_b32_e32 v56, v2
	v_mov_b32_e32 v57, v2
	v_mov_b32_e32 v10, v2
	v_mov_b32_e32 v11, v2
	v_mov_b32_e32 v12, v2
	v_mov_b32_e32 v13, v2
	v_mov_b32_e32 v22, v2
	v_mov_b32_e32 v23, v2
	v_mov_b32_e32 v24, v2
	v_mov_b32_e32 v25, v2
	v_mov_b32_e32 v26, v2
	v_mov_b32_e32 v27, v2
	v_mov_b32_e32 v28, v2
	v_mov_b32_e32 v29, v2
	v_mov_b32_e32 v46, v2
	v_mov_b32_e32 v47, v2
	v_mov_b32_e32 v48, v2
	v_mov_b32_e32 v49, v2
	v_mov_b32_e32 v82, v2
	v_mov_b32_e32 v83, v2
	v_mov_b32_e32 v84, v2
	v_mov_b32_e32 v85, v2
	v_mov_b32_e32 v94, v2
	v_mov_b32_e32 v95, v2
	v_mov_b32_e32 v96, v2
	v_mov_b32_e32 v97, v2
	v_mov_b32_e32 v58, v2
	v_mov_b32_e32 v59, v2
	v_mov_b32_e32 v60, v2
	v_mov_b32_e32 v61, v2
	v_mov_b32_e32 v62, v2
	v_mov_b32_e32 v63, v2
	v_mov_b32_e32 v64, v2
	v_mov_b32_e32 v65, v2
	v_mov_b32_e32 v30, v2
	v_mov_b32_e32 v31, v2
	v_mov_b32_e32 v32, v2
	v_mov_b32_e32 v33, v2
	v_mov_b32_e32 v50, v2
	v_mov_b32_e32 v51, v2
	v_mov_b32_e32 v52, v2
	v_mov_b32_e32 v53, v2
	v_mov_b32_e32 v114, v2
	v_mov_b32_e32 v115, v2
	v_mov_b32_e32 v116, v2
	v_mov_b32_e32 v117, v2
	v_mov_b32_e32 v118, v2
	v_mov_b32_e32 v119, v2
	v_mov_b32_e32 v120, v2
	v_mov_b32_e32 v121, v2
	v_mov_b32_e32 v110, v2
	v_mov_b32_e32 v111, v2
	v_mov_b32_e32 v112, v2
	v_mov_b32_e32 v113, v2
	v_mov_b32_e32 v98, v2
	v_mov_b32_e32 v99, v2
	v_mov_b32_e32 v100, v2
	v_mov_b32_e32 v101, v2
	v_mov_b32_e32 v90, v2
	v_mov_b32_e32 v91, v2
	v_mov_b32_e32 v92, v2
	v_mov_b32_e32 v93, v2
	v_mov_b32_e32 v74, v2
	v_mov_b32_e32 v75, v2
	v_mov_b32_e32 v76, v2
	v_mov_b32_e32 v77, v2
	v_mov_b32_e32 v38, v2
	v_mov_b32_e32 v39, v2
	v_mov_b32_e32 v40, v2
	v_mov_b32_e32 v41, v2
	v_mov_b32_e32 v14, v2
	v_mov_b32_e32 v15, v2
	v_mov_b32_e32 v16, v2
	v_mov_b32_e32 v17, v2
	v_mov_b32_e32 v122, v2
	v_mov_b32_e32 v123, v2
	v_mov_b32_e32 v124, v2
	v_mov_b32_e32 v125, v2
	v_mov_b32_e32 v126, v2
	v_mov_b32_e32 v127, v2
	v_mov_b32_e32 v128, v2
	v_mov_b32_e32 v129, v2
	v_mov_b32_e32 v102, v2
	v_mov_b32_e32 v103, v2
	v_mov_b32_e32 v104, v2
	v_mov_b32_e32 v105, v2
	v_mov_b32_e32 v106, v2
	v_mov_b32_e32 v107, v2
	v_mov_b32_e32 v108, v2
	v_mov_b32_e32 v109, v2
	v_mov_b32_e32 v78, v2
	v_mov_b32_e32 v79, v2
	v_mov_b32_e32 v80, v2
	v_mov_b32_e32 v81, v2
	v_mov_b32_e32 v86, v2
	v_mov_b32_e32 v87, v2
	v_mov_b32_e32 v88, v2
	v_mov_b32_e32 v89, v2
	v_mov_b32_e32 v18, v2
	v_mov_b32_e32 v19, v2
	v_mov_b32_e32 v20, v2
	v_mov_b32_e32 v21, v2
	v_mov_b32_e32 v34, v2
	v_mov_b32_e32 v35, v2
	v_mov_b32_e32 v36, v2
	v_mov_b32_e32 v37, v2
	s_branch .LBB0_1257

;     __host__ __device__ bool next(int i, Unit& u) const { const int t = i / 3, b = i - 3 * t; Unit v; if (!StaticOrder::next(t, v)) return false; u.pm = v.pm; u.pn = 8 * b + v.pn; return true; }
; #define PG8_STAGE(bufoff, gbase, voff) do { const int so_ = (int)(unsigned)((const char*)(gbase) - base_##voff); _Pragma("unroll") for (int _i = 0; _i < 2; ++_i) \
;         __builtin_amdgcn_raw_ptr_buffer_load_lds(rs_##voff, (PG8_LAS unsigned*)(lds + (bufoff) + ldsw + _i * 8192), 16, (int)(voff)[_i], so_, 0, 0); } while (0)
; #define PG8_LDA(dst, b, h) do { _Pragma("unroll") for (int m = 0; m < 4; ++m) _Pragma("unroll") for (int k = 0; k < 2; ++k) dst[m][k] = *(const PG8_LAS bf16x8*)(lds + PG8_SA(b, h) + aoff + m * 2048 + k * 1024); } while (0)
; #define PG8_LDB(dst, b, h) do { _Pragma("unroll") for (int n = 0; n < 2; ++n) _Pragma("unroll") for (int k = 0; k < 2; ++k) dst[n][k] = *(const PG8_LAS bf16x8*)(lds + PG8_SB(b, h) + boff + n * 2048 + k * 1024); } while (0)
; template <class Epi, class Sched, bool ALIGN_EPI = false, bool SP2 = false>
; __device__ __forceinline__ void gemm_phase(PG8_LAS unsigned char* lds, const Gemm g, const Sched& S, const Epi& E, int tid_in) {
;     ...
;         const bool has_next = S.next(ui + 1, nxt);
;         const char* nA = has_next ? (const char*)g.A + (size_t)nxt.pm * tstepA + (g.grp ? (size_t)(nxt.pn / g.grp) * g.agrp : (size_t)0) : cA; const char* nB = has_next ? (const char*)g.Bt + (size_t)nxt.pn * tstepB : cB;
;         for (int t = 0; t < nt; t += 2) {
;             const bool last = (t == nt - 2);
;             const char* a1 = cA + (size_t)(t + 1) * kstep;
;             const char* a2 = last ? nA : cA + (size_t)(t + 2) * kstep; const char* b2 = last ? nB : cB + (size_t)(t + 2) * kstep;
;             const char* a3 = a2 + kstep; const char* b3 = b2 + kstep;
;             if (last && has_next) S.a_ready(nxt);
;     ...
;             PG8_LDB(B0, 0, 0); PG8_LDB(B1, 0, 1); PG8_SCHED; PG8_LDA(At, 0, 0); PG8_STAGE(PG8_SA(1, 1), a1 + hstepA, voffA);
;             PG8_WAIT_V(8); PG8_WAIT_L(0); PG8_BAR; PG8_MMA(0, 0, At, B0); PG8_MMA(0, 1, At, B1); PG8_BAR; PG8_SCHED;
;             PG8_LDA(At, 0, 1); PG8_STAGE(PG8_SB(0, 0), b2, voffB); PG8_STAGE(PG8_SB(0, 1), b2 + hstepB, voffB); PG8_STAGE(PG8_SA(0, 0), a2, voffA);
;             PG8_WAIT_V(8); PG8_WAIT_L(0); PG8_BAR; PG8_MMA(1, 0, At, B0); PG8_MMA(1, 1, At, B1); PG8_BAR; PG8_SCHED;
.LBB0_1513:
	s_ashr_i32 s21, s20, 31
	s_lshl_b64 s[18:19], s[20:21], 20
	s_add_u32 s22, s4, s18
	s_addc_u32 s23, s9, s19
	s_and_b64 s[18:19], s[36:37], exec
	s_cselect_b32 s18, s22, s16
	s_ashr_i32 s15, s14, 31
	s_lshl_b64 s[24:25], s[14:15], 20
	s_add_u32 s24, s40, s24
	s_addc_u32 s25, s26, s25
	s_and_b64 s[42:43], s[36:37], exec
	s_cselect_b32 s15, s24, s38
	s_add_u32 s19, s38, 0x100
	v_mov_b32_e32 v2, 0
	s_addc_u32 s21, s39, 0
	s_mov_b32 s73, -2
	v_add_u32_e32 v141, 0x10000, v139
	ds_read_b128 v[130:133], v141
	ds_read_b128 v[142:145], v141 offset:1024
	ds_read_b128 v[146:149], v141 offset:2048
	ds_read_b128 v[150:153], v141 offset:3072
	v_add_u32_e32 v141, 0x14000, v139
	ds_read_b128 v[154:157], v141
	ds_read_b128 v[158:161], v141 offset:1024
	ds_read_b128 v[162:165], v141 offset:2048
	ds_read_b128 v[166:169], v141 offset:3072
	s_add_u32 s38, s16, 0x100
	s_addc_u32 s39, s17, 0
	s_sub_i32 s16, s16, s4
	s_add_i32 s16, s16, 0x80080
	s_sub_i32 s74, s16, 0x80000
	s_cmp_eq_u32 s73, 28
	s_cselect_b32 s17, s18, s38
	s_mov_b32 m0, s67
	ds_read_b128 v[170:173], v140
	ds_read_b128 v[174:177], v140 offset:1024
	ds_read_b128 v[178:181], v140 offset:2048
	ds_read_b128 v[182:185], v140 offset:3072
	ds_read_b128 v[186:189], v140 offset:4096
	ds_read_b128 v[190:193], v140 offset:5120
	ds_read_b128 v[200:203], v140 offset:6144
	ds_read_b128 v[206:209], v140 offset:7168
	s_mov_b32 m0, s62
	s_nop 0
	buffer_load_dwordx4 v135, s[4:7], s74 offen lds
	s_mov_b32 m0, s67
	s_nop 0
	buffer_load_dwordx4 v0, s[4:7], s16 offen lds
	s_mov_b32 m0, s68
	s_nop 0
	buffer_load_dwordx4 v135, s[4:7], s16 offen lds
	s_waitcnt vmcnt(8)
	s_waitcnt lgkmcnt(0)
	s_setprio 1
	s_barrier
	v_mfma_f32_16x16x32_bf16 v[126:129], v[130:133], v[170:173], 0
	v_mfma_f32_16x16x32_bf16 v[122:125], v[146:149], v[170:173], 0
	v_mfma_f32_16x16x32_bf16 v[106:109], v[146:149], v[178:181], 0
	v_mfma_f32_16x16x32_bf16 v[110:113], v[130:133], v[178:181], 0
	v_mfma_f32_16x16x32_bf16 v[94:97], v[130:133], v[186:189], 0
	v_mfma_f32_16x16x32_bf16 v[90:93], v[146:149], v[186:189], 0
	v_mfma_f32_16x16x32_bf16 v[74:77], v[146:149], v[200:203], 0
	v_mfma_f32_16x16x32_bf16 v[78:81], v[130:133], v[200:203], 0
	v_mfma_f32_16x16x32_bf16 v[126:129], v[142:145], v[174:177], v[126:129]
	v_mfma_f32_16x16x32_bf16 v[122:125], v[150:153], v[174:177], v[122:125]
	v_mfma_f32_16x16x32_bf16 v[106:109], v[150:153], v[182:185], v[106:109]
	v_mfma_f32_16x16x32_bf16 v[110:113], v[142:145], v[182:185], v[110:113]
	v_mfma_f32_16x16x32_bf16 v[94:97], v[142:145], v[190:193], v[94:97]
	v_mfma_f32_16x16x32_bf16 v[90:93], v[150:153], v[190:193], v[90:93]
	v_mfma_f32_16x16x32_bf16 v[74:77], v[150:153], v[206:209], v[74:77]
	v_mfma_f32_16x16x32_bf16 v[78:81], v[142:145], v[206:209], v[78:81]
	v_mfma_f32_16x16x32_bf16 v[118:121], v[154:157], v[170:173], 0
	v_mfma_f32_16x16x32_bf16 v[114:117], v[162:165], v[170:173], 0
	v_mfma_f32_16x16x32_bf16 v[98:101], v[162:165], v[178:181], 0
	v_mfma_f32_16x16x32_bf16 v[102:105], v[154:157], v[178:181], 0
	v_mfma_f32_16x16x32_bf16 v[86:89], v[154:157], v[186:189], 0
	v_mfma_f32_16x16x32_bf16 v[82:85], v[162:165], v[186:189], 0
	v_mfma_f32_16x16x32_bf16 v[66:69], v[162:165], v[200:203], 0
	v_mfma_f32_16x16x32_bf16 v[70:73], v[154:157], v[200:203], 0
	v_mfma_f32_16x16x32_bf16 v[118:121], v[158:161], v[174:177], v[118:121]
	v_mfma_f32_16x16x32_bf16 v[114:117], v[166:169], v[174:177], v[114:117]
	v_mfma_f32_16x16x32_bf16 v[98:101], v[166:169], v[182:185], v[98:101]
	v_mfma_f32_16x16x32_bf16 v[102:105], v[158:161], v[182:185], v[102:105]
	v_mfma_f32_16x16x32_bf16 v[86:89], v[158:161], v[190:193], v[86:89]
	v_mfma_f32_16x16x32_bf16 v[82:85], v[166:169], v[190:193], v[82:85]
	v_mfma_f32_16x16x32_bf16 v[66:69], v[166:169], v[206:209], v[66:69]
	v_mfma_f32_16x16x32_bf16 v[70:73], v[158:161], v[206:209], v[70:73]
	s_barrier
	s_setprio 0
	s_cselect_b32 s16, s15, s19
	s_mov_b32 m0, s35
	s_mov_b32 s42, s6
	s_mov_b32 s43, s7
	s_sub_i32 s16, s16, s40
	ds_read_b128 v[170:173], v140 offset:16384
	ds_read_b128 v[174:177], v140 offset:17408
	ds_read_b128 v[178:181], v140 offset:18432
	ds_read_b128 v[182:185], v140 offset:19456
	ds_read_b128 v[186:189], v140 offset:20480
	ds_read_b128 v[190:193], v140 offset:21504
	ds_read_b128 v[200:203], v140 offset:22528
	ds_read_b128 v[206:209], v140 offset:23552
	buffer_load_dwordx4 v134, s[40:43], s16 offen lds
	s_mov_b32 m0, s44
	s_add_i32 s74, s16, 0x80000
	buffer_load_dwordx4 v136, s[40:43], s16 offen lds
	s_mov_b32 m0, s45
	s_sub_i32 s17, s17, s4
	buffer_load_dwordx4 v134, s[40:43], s74 offen lds
	s_mov_b32 m0, s46
	s_nop 0
	buffer_load_dwordx4 v136, s[40:43], s74 offen lds
	s_mov_b32 m0, s34
	s_nop 0
	buffer_load_dwordx4 v0, s[4:7], s17 offen lds
	s_waitcnt vmcnt(7)
	s_waitcnt lgkmcnt(0)
	s_setprio 1
	s_barrier
; #define PG8_STAGE(bufoff, gbase, voff) do { const int so_ = (int)(unsigned)((const char*)(gbase) - base_##voff); _Pragma("unroll") for (int _i = 0; _i < 2; ++_i) \
;         __builtin_amdgcn_raw_ptr_buffer_load_lds(rs_##voff, (PG8_LAS unsigned*)(lds + (bufoff) + ldsw + _i * 8192), 16, (int)(voff)[_i], so_, 0, 0); } while (0)
; #define PG8_LDA(dst, b, h) do { _Pragma("unroll") for (int m = 0; m < 4; ++m) _Pragma("unroll") for (int k = 0; k < 2; ++k) dst[m][k] = *(const PG8_LAS bf16x8*)(lds + PG8_SA(b, h) + aoff + m * 2048 + k * 1024); } while (0)
; #define PG8_LDB(dst, b, h) do { _Pragma("unroll") for (int n = 0; n < 2; ++n) _Pragma("unroll") for (int k = 0; k < 2; ++k) dst[n][k] = *(const PG8_LAS bf16x8*)(lds + PG8_SB(b, h) + boff + n * 2048 + k * 1024); } while (0)
; #define PG8_MMA(ai, bj, At, Bt) do { __builtin_amdgcn_s_setprio(1); _Pragma("unroll") for (int m = 0; m < 4; ++m) _Pragma("unroll") for (int n = 0; n < 2; ++n) _Pragma("unroll") for (int k = 0; k < 2; ++k) \
;         acc[ai][bj][m][n] = __builtin_amdgcn_mfma_f32_16x16x32_bf16(Bt[n][k], At[m][k], acc[ai][bj][m][n], 0, 0, 0); __builtin_amdgcn_s_setprio(0); } while (0)
; template <class Epi, class Sched, bool ALIGN_EPI = false, bool SP2 = false>
; __device__ __forceinline__ void gemm_phase(PG8_LAS unsigned char* lds, const Gemm g, const Sched& S, const Epi& E, int tid_in) {
;     ...
;             PG8_LDB(B0, 0, 0); PG8_LDB(B1, 0, 1); PG8_SCHED; PG8_LDA(At, 0, 0); PG8_STAGE(PG8_SA(1, 1), a1 + hstepA, voffA);
;             PG8_WAIT_V(8); PG8_WAIT_L(0); PG8_BAR; PG8_MMA(0, 0, At, B0); PG8_MMA(0, 1, At, B1); PG8_BAR; PG8_SCHED;
;             PG8_LDA(At, 0, 1); PG8_STAGE(PG8_SB(0, 0), b2, voffB); PG8_STAGE(PG8_SB(0, 1), b2 + hstepB, voffB); PG8_STAGE(PG8_SA(0, 0), a2, voffA);
;             PG8_WAIT_V(8); PG8_WAIT_L(0); PG8_BAR; PG8_MMA(1, 0, At, B0); PG8_MMA(1, 1, At, B1); PG8_BAR; PG8_SCHED;
;             PG8_LDB(B0, 1, 0); PG8_LDB(B1, 1, 1); PG8_SCHED; PG8_LDA(At, 1, 0); PG8_STAGE(PG8_SA(0, 1), a2 + hstepA, voffA);
;             PG8_WAIT_V(8); PG8_WAIT_L(0); PG8_BAR; PG8_MMA(0, 0, At, B0); PG8_MMA(0, 1, At, B1); PG8_BAR; PG8_SCHED;
;             PG8_LDA(At, 1, 1); PG8_STAGE(PG8_SB(1, 0), b3, voffB); PG8_STAGE(PG8_SB(1, 1), b3 + hstepB, voffB); PG8_STAGE(PG8_SA(1, 0), a3, voffA);
;             PG8_WAIT_V(8); PG8_WAIT_L(0); PG8_BAR; PG8_MMA(1, 0, At, B0); PG8_MMA(1, 1, At, B1); PG8_BAR; PG8_SCHED;
	v_mfma_f32_16x16x32_bf16 v[62:65], v[130:133], v[170:173], 0
	v_mfma_f32_16x16x32_bf16 v[58:61], v[146:149], v[170:173], 0
	v_mfma_f32_16x16x32_bf16 v[42:45], v[146:149], v[178:181], 0
	v_mfma_f32_16x16x32_bf16 v[46:49], v[130:133], v[178:181], 0
	v_mfma_f32_16x16x32_bf16 v[30:33], v[130:133], v[186:189], 0
	v_mfma_f32_16x16x32_bf16 v[26:29], v[146:149], v[186:189], 0
	v_mfma_f32_16x16x32_bf16 v[10:13], v[146:149], v[200:203], 0
	v_mfma_f32_16x16x32_bf16 v[14:17], v[130:133], v[200:203], 0
	v_mfma_f32_16x16x32_bf16 v[62:65], v[142:145], v[174:177], v[62:65]
	v_mfma_f32_16x16x32_bf16 v[58:61], v[150:153], v[174:177], v[58:61]
	v_mfma_f32_16x16x32_bf16 v[42:45], v[150:153], v[182:185], v[42:45]
	v_mfma_f32_16x16x32_bf16 v[46:49], v[142:145], v[182:185], v[46:49]
	v_mfma_f32_16x16x32_bf16 v[30:33], v[142:145], v[190:193], v[30:33]
	v_mfma_f32_16x16x32_bf16 v[26:29], v[150:153], v[190:193], v[26:29]
	v_mfma_f32_16x16x32_bf16 v[10:13], v[150:153], v[206:209], v[10:13]
	v_mfma_f32_16x16x32_bf16 v[14:17], v[142:145], v[206:209], v[14:17]
	v_mfma_f32_16x16x32_bf16 v[54:57], v[154:157], v[170:173], 0
	v_mfma_f32_16x16x32_bf16 v[50:53], v[162:165], v[170:173], 0
	v_mfma_f32_16x16x32_bf16 v[34:37], v[162:165], v[178:181], 0
	v_mfma_f32_16x16x32_bf16 v[38:41], v[154:157], v[178:181], 0
	v_mfma_f32_16x16x32_bf16 v[22:25], v[154:157], v[186:189], 0
	v_mfma_f32_16x16x32_bf16 v[18:21], v[162:165], v[186:189], 0
	v_mfma_f32_16x16x32_bf16 v[2:5], v[162:165], v[200:203], 0
	v_mfma_f32_16x16x32_bf16 v[6:9], v[154:157], v[200:203], 0
	v_mfma_f32_16x16x32_bf16 v[54:57], v[158:161], v[174:177], v[54:57]
	v_mfma_f32_16x16x32_bf16 v[50:53], v[166:169], v[174:177], v[50:53]
	v_mfma_f32_16x16x32_bf16 v[34:37], v[166:169], v[182:185], v[34:37]
	v_mfma_f32_16x16x32_bf16 v[38:41], v[158:161], v[182:185], v[38:41]
	v_mfma_f32_16x16x32_bf16 v[22:25], v[158:161], v[190:193], v[22:25]
	v_mfma_f32_16x16x32_bf16 v[18:21], v[166:169], v[190:193], v[18:21]
	v_mfma_f32_16x16x32_bf16 v[2:5], v[166:169], v[206:209], v[2:5]
	v_mfma_f32_16x16x32_bf16 v[6:9], v[158:161], v[206:209], v[6:9]
	s_barrier
	s_setprio 0
	v_add_u32_e32 v141, 0x18000, v139
	ds_read_b128 v[130:133], v141
	ds_read_b128 v[142:145], v141 offset:1024
	ds_read_b128 v[146:149], v141 offset:2048
	ds_read_b128 v[150:153], v141 offset:3072
	v_add_u32_e32 v141, 0x1c000, v139
	ds_read_b128 v[154:157], v141
	ds_read_b128 v[158:161], v141 offset:1024
	ds_read_b128 v[162:165], v141 offset:2048
	ds_read_b128 v[166:169], v141 offset:3072
	s_add_i32 s74, s17, 0x80000
	s_mov_b32 m0, s48
	ds_read_b128 v[170:173], v140 offset:32768
	ds_read_b128 v[174:177], v140 offset:33792
	ds_read_b128 v[178:181], v140 offset:34816
	ds_read_b128 v[182:185], v140 offset:35840
	ds_read_b128 v[186:189], v140 offset:36864
	ds_read_b128 v[190:193], v140 offset:37888
	ds_read_b128 v[200:203], v140 offset:38912
	ds_read_b128 v[206:209], v140 offset:39936
	s_mov_b32 m0, s47
	s_nop 0
	buffer_load_dwordx4 v135, s[4:7], s17 offen lds
	s_mov_b32 m0, s48
	s_nop 0
	buffer_load_dwordx4 v0, s[4:7], s74 offen lds
	s_mov_b32 m0, s49
	s_nop 0
	buffer_load_dwordx4 v135, s[4:7], s74 offen lds
	s_waitcnt vmcnt(8)
	s_waitcnt lgkmcnt(0)
	s_setprio 1
	s_barrier
	v_mfma_f32_16x16x32_bf16 v[126:129], v[130:133], v[170:173], v[126:129]
	v_mfma_f32_16x16x32_bf16 v[122:125], v[146:149], v[170:173], v[122:125]
	v_mfma_f32_16x16x32_bf16 v[106:109], v[146:149], v[178:181], v[106:109]
	v_mfma_f32_16x16x32_bf16 v[110:113], v[130:133], v[178:181], v[110:113]
	v_mfma_f32_16x16x32_bf16 v[94:97], v[130:133], v[186:189], v[94:97]
	v_mfma_f32_16x16x32_bf16 v[90:93], v[146:149], v[186:189], v[90:93]
	v_mfma_f32_16x16x32_bf16 v[74:77], v[146:149], v[200:203], v[74:77]
	v_mfma_f32_16x16x32_bf16 v[78:81], v[130:133], v[200:203], v[78:81]
	v_mfma_f32_16x16x32_bf16 v[126:129], v[142:145], v[174:177], v[126:129]
	v_mfma_f32_16x16x32_bf16 v[122:125], v[150:153], v[174:177], v[122:125]
	v_mfma_f32_16x16x32_bf16 v[106:109], v[150:153], v[182:185], v[106:109]
	v_mfma_f32_16x16x32_bf16 v[110:113], v[142:145], v[182:185], v[110:113]
	v_mfma_f32_16x16x32_bf16 v[94:97], v[142:145], v[190:193], v[94:97]
	v_mfma_f32_16x16x32_bf16 v[90:93], v[150:153], v[190:193], v[90:93]
	v_mfma_f32_16x16x32_bf16 v[74:77], v[150:153], v[206:209], v[74:77]
	v_mfma_f32_16x16x32_bf16 v[78:81], v[142:145], v[206:209], v[78:81]
	v_mfma_f32_16x16x32_bf16 v[118:121], v[154:157], v[170:173], v[118:121]
	v_mfma_f32_16x16x32_bf16 v[114:117], v[162:165], v[170:173], v[114:117]
	v_mfma_f32_16x16x32_bf16 v[98:101], v[162:165], v[178:181], v[98:101]
	v_mfma_f32_16x16x32_bf16 v[102:105], v[154:157], v[178:181], v[102:105]
	v_mfma_f32_16x16x32_bf16 v[86:89], v[154:157], v[186:189], v[86:89]
	v_mfma_f32_16x16x32_bf16 v[82:85], v[162:165], v[186:189], v[82:85]
	v_mfma_f32_16x16x32_bf16 v[66:69], v[162:165], v[200:203], v[66:69]
	v_mfma_f32_16x16x32_bf16 v[70:73], v[154:157], v[200:203], v[70:73]
	v_mfma_f32_16x16x32_bf16 v[118:121], v[158:161], v[174:177], v[118:121]
	v_mfma_f32_16x16x32_bf16 v[114:117], v[166:169], v[174:177], v[114:117]
	v_mfma_f32_16x16x32_bf16 v[98:101], v[166:169], v[182:185], v[98:101]
	v_mfma_f32_16x16x32_bf16 v[102:105], v[158:161], v[182:185], v[102:105]
	v_mfma_f32_16x16x32_bf16 v[86:89], v[158:161], v[190:193], v[86:89]
	v_mfma_f32_16x16x32_bf16 v[82:85], v[166:169], v[190:193], v[82:85]
	v_mfma_f32_16x16x32_bf16 v[66:69], v[166:169], v[206:209], v[66:69]
	v_mfma_f32_16x16x32_bf16 v[70:73], v[158:161], v[206:209], v[70:73]
	s_barrier
; #define PG8_STAGE(bufoff, gbase, voff) do { const int so_ = (int)(unsigned)((const char*)(gbase) - base_##voff); _Pragma("unroll") for (int _i = 0; _i < 2; ++_i) \
;         __builtin_amdgcn_raw_ptr_buffer_load_lds(rs_##voff, (PG8_LAS unsigned*)(lds + (bufoff) + ldsw + _i * 8192), 16, (int)(voff)[_i], so_, 0, 0); } while (0)
; #define PG8_LDA(dst, b, h) do { _Pragma("unroll") for (int m = 0; m < 4; ++m) _Pragma("unroll") for (int k = 0; k < 2; ++k) dst[m][k] = *(const PG8_LAS bf16x8*)(lds + PG8_SA(b, h) + aoff + m * 2048 + k * 1024); } while (0)
; #define PG8_LDB(dst, b, h) do { _Pragma("unroll") for (int n = 0; n < 2; ++n) _Pragma("unroll") for (int k = 0; k < 2; ++k) dst[n][k] = *(const PG8_LAS bf16x8*)(lds + PG8_SB(b, h) + boff + n * 2048 + k * 1024); } while (0)
; #define PG8_MMA(ai, bj, At, Bt) do { __builtin_amdgcn_s_setprio(1); _Pragma("unroll") for (int m = 0; m < 4; ++m) _Pragma("unroll") for (int n = 0; n < 2; ++n) _Pragma("unroll") for (int k = 0; k < 2; ++k) \
;         acc[ai][bj][m][n] = __builtin_amdgcn_mfma_f32_16x16x32_bf16(Bt[n][k], At[m][k], acc[ai][bj][m][n], 0, 0, 0); __builtin_amdgcn_s_setprio(0); } while (0)
; template <class Epi, class Sched, bool ALIGN_EPI = false, bool SP2 = false>
; __device__ __forceinline__ void gemm_phase(PG8_LAS unsigned char* lds, const Gemm g, const Sched& S, const Epi& E, int tid_in) {
;     ...
;             PG8_LDB(B0, 0, 0); PG8_LDB(B1, 0, 1); PG8_SCHED; PG8_LDA(At, 0, 0); PG8_STAGE(PG8_SA(1, 1), a1 + hstepA, voffA);
;             PG8_WAIT_V(8); PG8_WAIT_L(0); PG8_BAR; PG8_MMA(0, 0, At, B0); PG8_MMA(0, 1, At, B1); PG8_BAR; PG8_SCHED;
;             PG8_LDA(At, 0, 1); PG8_STAGE(PG8_SB(0, 0), b2, voffB); PG8_STAGE(PG8_SB(0, 1), b2 + hstepB, voffB); PG8_STAGE(PG8_SA(0, 0), a2, voffA);
;             PG8_WAIT_V(8); PG8_WAIT_L(0); PG8_BAR; PG8_MMA(1, 0, At, B0); PG8_MMA(1, 1, At, B1); PG8_BAR; PG8_SCHED;
;             PG8_LDB(B0, 1, 0); PG8_LDB(B1, 1, 1); PG8_SCHED; PG8_LDA(At, 1, 0); PG8_STAGE(PG8_SA(0, 1), a2 + hstepA, voffA);
;             PG8_WAIT_V(8); PG8_WAIT_L(0); PG8_BAR; PG8_MMA(0, 0, At, B0); PG8_MMA(0, 1, At, B1); PG8_BAR; PG8_SCHED;
;             PG8_LDA(At, 1, 1); PG8_STAGE(PG8_SB(1, 0), b3, voffB); PG8_STAGE(PG8_SB(1, 1), b3 + hstepB, voffB); PG8_STAGE(PG8_SA(1, 0), a3, voffA);
;             PG8_WAIT_V(8); PG8_WAIT_L(0); PG8_BAR; PG8_MMA(1, 0, At, B0); PG8_MMA(1, 1, At, B1); PG8_BAR; PG8_SCHED;
	s_setprio 0
	s_mov_b32 m0, s53
	s_add_i32 s74, s16, 0x80
	ds_read_b128 v[170:173], v140 offset:49152
	ds_read_b128 v[174:177], v140 offset:50176
	ds_read_b128 v[178:181], v140 offset:51200
	ds_read_b128 v[182:185], v140 offset:52224
	ds_read_b128 v[186:189], v140 offset:53248
	ds_read_b128 v[190:193], v140 offset:54272
	ds_read_b128 v[200:203], v140 offset:55296
	ds_read_b128 v[206:209], v140 offset:56320
	buffer_load_dwordx4 v134, s[40:43], s74 offen lds
	s_mov_b32 m0, s60
	s_add_i32 s16, s16, 0x80080
	buffer_load_dwordx4 v136, s[40:43], s74 offen lds
	s_mov_b32 m0, s63
	s_addk_i32 s17, 0x80
	buffer_load_dwordx4 v134, s[40:43], s16 offen lds
	s_mov_b32 m0, s66
	s_nop 0
	buffer_load_dwordx4 v136, s[40:43], s16 offen lds
	s_mov_b32 m0, s61
	s_nop 0
	buffer_load_dwordx4 v0, s[4:7], s17 offen lds
	s_waitcnt vmcnt(7)
	s_waitcnt lgkmcnt(0)
	s_setprio 1
	s_barrier
	v_mfma_f32_16x16x32_bf16 v[62:65], v[130:133], v[170:173], v[62:65]
	v_mfma_f32_16x16x32_bf16 v[58:61], v[146:149], v[170:173], v[58:61]
	v_mfma_f32_16x16x32_bf16 v[42:45], v[146:149], v[178:181], v[42:45]
	v_mfma_f32_16x16x32_bf16 v[46:49], v[130:133], v[178:181], v[46:49]
	v_mfma_f32_16x16x32_bf16 v[30:33], v[130:133], v[186:189], v[30:33]
	v_mfma_f32_16x16x32_bf16 v[26:29], v[146:149], v[186:189], v[26:29]
	v_mfma_f32_16x16x32_bf16 v[10:13], v[146:149], v[200:203], v[10:13]
	v_mfma_f32_16x16x32_bf16 v[14:17], v[130:133], v[200:203], v[14:17]
	v_mfma_f32_16x16x32_bf16 v[62:65], v[142:145], v[174:177], v[62:65]
	v_mfma_f32_16x16x32_bf16 v[58:61], v[150:153], v[174:177], v[58:61]
	v_mfma_f32_16x16x32_bf16 v[42:45], v[150:153], v[182:185], v[42:45]
	v_mfma_f32_16x16x32_bf16 v[46:49], v[142:145], v[182:185], v[46:49]
	v_mfma_f32_16x16x32_bf16 v[30:33], v[142:145], v[190:193], v[30:33]
	v_mfma_f32_16x16x32_bf16 v[26:29], v[150:153], v[190:193], v[26:29]
	v_mfma_f32_16x16x32_bf16 v[10:13], v[150:153], v[206:209], v[10:13]
	v_mfma_f32_16x16x32_bf16 v[14:17], v[142:145], v[206:209], v[14:17]
	v_mfma_f32_16x16x32_bf16 v[54:57], v[154:157], v[170:173], v[54:57]
	v_mfma_f32_16x16x32_bf16 v[50:53], v[162:165], v[170:173], v[50:53]
	v_mfma_f32_16x16x32_bf16 v[34:37], v[162:165], v[178:181], v[34:37]
	v_mfma_f32_16x16x32_bf16 v[38:41], v[154:157], v[178:181], v[38:41]
	v_mfma_f32_16x16x32_bf16 v[22:25], v[154:157], v[186:189], v[22:25]
	v_mfma_f32_16x16x32_bf16 v[18:21], v[162:165], v[186:189], v[18:21]
	v_mfma_f32_16x16x32_bf16 v[2:5], v[162:165], v[200:203], v[2:5]
	v_mfma_f32_16x16x32_bf16 v[6:9], v[154:157], v[200:203], v[6:9]
	v_mfma_f32_16x16x32_bf16 v[54:57], v[158:161], v[174:177], v[54:57]
	v_mfma_f32_16x16x32_bf16 v[50:53], v[166:169], v[174:177], v[50:53]
	v_mfma_f32_16x16x32_bf16 v[34:37], v[166:169], v[182:185], v[34:37]
	v_mfma_f32_16x16x32_bf16 v[38:41], v[158:161], v[182:185], v[38:41]
	v_mfma_f32_16x16x32_bf16 v[22:25], v[158:161], v[190:193], v[22:25]
	v_mfma_f32_16x16x32_bf16 v[18:21], v[166:169], v[190:193], v[18:21]
	v_mfma_f32_16x16x32_bf16 v[2:5], v[166:169], v[206:209], v[2:5]
	v_mfma_f32_16x16x32_bf16 v[6:9], v[158:161], v[206:209], v[6:9]
	s_barrier
	s_setprio 0
	s_add_i32 s73, s73, 2
	s_add_u32 s19, s19, 0x100
	s_addc_u32 s21, s21, 0
	s_cmp_gt_u32 s73, 29
	s_mov_b64 s[16:17], s[38:39]
	s_cmpk_lt_u32 s59, 0x100
	s_cbranch_scc0 .Lyng_loop3
.LBB0_1514:
	v_add_u32_e32 v141, 0x10000, v139
	ds_read_b128 v[130:133], v141
	ds_read_b128 v[142:145], v141 offset:1024
	ds_read_b128 v[146:149], v141 offset:2048
	ds_read_b128 v[150:153], v141 offset:3072
	v_add_u32_e32 v141, 0x14000, v139
	ds_read_b128 v[154:157], v141
	ds_read_b128 v[158:161], v141 offset:1024
	ds_read_b128 v[162:165], v141 offset:2048
	ds_read_b128 v[166:169], v141 offset:3072
	s_add_u32 s38, s16, 0x100
	s_addc_u32 s39, s17, 0
	s_sub_i32 s16, s16, s4
	s_add_i32 s16, s16, 0x80080
	s_sub_i32 s74, s16, 0x80000
	s_cmp_eq_u32 s73, 28
	s_cselect_b32 s17, s18, s38
	s_mov_b32 m0, s67
	ds_read_b128 v[170:173], v140
	ds_read_b128 v[174:177], v140 offset:1024
	ds_read_b128 v[178:181], v140 offset:2048
	ds_read_b128 v[182:185], v140 offset:3072
	ds_read_b128 v[186:189], v140 offset:4096
	ds_read_b128 v[190:193], v140 offset:5120
	ds_read_b128 v[200:203], v140 offset:6144
	ds_read_b128 v[206:209], v140 offset:7168
	s_mov_b32 m0, s62
	s_nop 0
	buffer_load_dwordx4 v135, s[4:7], s74 offen lds
	s_mov_b32 m0, s67
	s_nop 0
	buffer_load_dwordx4 v0, s[4:7], s16 offen lds
	s_mov_b32 m0, s68
	s_nop 0
	buffer_load_dwordx4 v135, s[4:7], s16 offen lds
	s_waitcnt vmcnt(8)
	s_waitcnt lgkmcnt(0)
	s_setprio 1
	s_barrier
	v_mfma_f32_16x16x32_bf16 v[126:129], v[130:133], v[170:173], v[126:129]
	v_mfma_f32_16x16x32_bf16 v[122:125], v[146:149], v[170:173], v[122:125]
	v_mfma_f32_16x16x32_bf16 v[106:109], v[146:149], v[178:181], v[106:109]
	v_mfma_f32_16x16x32_bf16 v[110:113], v[130:133], v[178:181], v[110:113]
	v_mfma_f32_16x16x32_bf16 v[94:97], v[130:133], v[186:189], v[94:97]
	v_mfma_f32_16x16x32_bf16 v[90:93], v[146:149], v[186:189], v[90:93]
	v_mfma_f32_16x16x32_bf16 v[74:77], v[146:149], v[200:203], v[74:77]
	v_mfma_f32_16x16x32_bf16 v[78:81], v[130:133], v[200:203], v[78:81]
	v_mfma_f32_16x16x32_bf16 v[126:129], v[142:145], v[174:177], v[126:129]
	v_mfma_f32_16x16x32_bf16 v[122:125], v[150:153], v[174:177], v[122:125]
	v_mfma_f32_16x16x32_bf16 v[106:109], v[150:153], v[182:185], v[106:109]
	v_mfma_f32_16x16x32_bf16 v[110:113], v[142:145], v[182:185], v[110:113]
	v_mfma_f32_16x16x32_bf16 v[94:97], v[142:145], v[190:193], v[94:97]
	v_mfma_f32_16x16x32_bf16 v[90:93], v[150:153], v[190:193], v[90:93]
	v_mfma_f32_16x16x32_bf16 v[74:77], v[150:153], v[206:209], v[74:77]
	v_mfma_f32_16x16x32_bf16 v[78:81], v[142:145], v[206:209], v[78:81]
	v_mfma_f32_16x16x32_bf16 v[118:121], v[154:157], v[170:173], v[118:121]
	v_mfma_f32_16x16x32_bf16 v[114:117], v[162:165], v[170:173], v[114:117]
	v_mfma_f32_16x16x32_bf16 v[98:101], v[162:165], v[178:181], v[98:101]
	v_mfma_f32_16x16x32_bf16 v[102:105], v[154:157], v[178:181], v[102:105]
	v_mfma_f32_16x16x32_bf16 v[86:89], v[154:157], v[186:189], v[86:89]
	v_mfma_f32_16x16x32_bf16 v[82:85], v[162:165], v[186:189], v[82:85]
	v_mfma_f32_16x16x32_bf16 v[66:69], v[162:165], v[200:203], v[66:69]
	v_mfma_f32_16x16x32_bf16 v[70:73], v[154:157], v[200:203], v[70:73]
	v_mfma_f32_16x16x32_bf16 v[118:121], v[158:161], v[174:177], v[118:121]
	v_mfma_f32_16x16x32_bf16 v[114:117], v[166:169], v[174:177], v[114:117]
	v_mfma_f32_16x16x32_bf16 v[98:101], v[166:169], v[182:185], v[98:101]
	v_mfma_f32_16x16x32_bf16 v[102:105], v[158:161], v[182:185], v[102:105]
	v_mfma_f32_16x16x32_bf16 v[86:89], v[158:161], v[190:193], v[86:89]
	v_mfma_f32_16x16x32_bf16 v[82:85], v[166:169], v[190:193], v[82:85]
	v_mfma_f32_16x16x32_bf16 v[66:69], v[166:169], v[206:209], v[66:69]
	v_mfma_f32_16x16x32_bf16 v[70:73], v[158:161], v[206:209], v[70:73]
	s_barrier
; #define PG8_STAGE(bufoff, gbase, voff) do { const int so_ = (int)(unsigned)((const char*)(gbase) - base_##voff); _Pragma("unroll") for (int _i = 0; _i < 2; ++_i) \
;         __builtin_amdgcn_raw_ptr_buffer_load_lds(rs_##voff, (PG8_LAS unsigned*)(lds + (bufoff) + ldsw + _i * 8192), 16, (int)(voff)[_i], so_, 0, 0); } while (0)
; #define PG8_LDA(dst, b, h) do { _Pragma("unroll") for (int m = 0; m < 4; ++m) _Pragma("unroll") for (int k = 0; k < 2; ++k) dst[m][k] = *(const PG8_LAS bf16x8*)(lds + PG8_SA(b, h) + aoff + m * 2048 + k * 1024); } while (0)
; #define PG8_LDB(dst, b, h) do { _Pragma("unroll") for (int n = 0; n < 2; ++n) _Pragma("unroll") for (int k = 0; k < 2; ++k) dst[n][k] = *(const PG8_LAS bf16x8*)(lds + PG8_SB(b, h) + boff + n * 2048 + k * 1024); } while (0)
; #define PG8_MMA(ai, bj, At, Bt) do { __builtin_amdgcn_s_setprio(1); _Pragma("unroll") for (int m = 0; m < 4; ++m) _Pragma("unroll") for (int n = 0; n < 2; ++n) _Pragma("unroll") for (int k = 0; k < 2; ++k) \
;         acc[ai][bj][m][n] = __builtin_amdgcn_mfma_f32_16x16x32_bf16(Bt[n][k], At[m][k], acc[ai][bj][m][n], 0, 0, 0); __builtin_amdgcn_s_setprio(0); } while (0)
; template <class Epi, class Sched, bool ALIGN_EPI = false, bool SP2 = false>
; __device__ __forceinline__ void gemm_phase(PG8_LAS unsigned char* lds, const Gemm g, const Sched& S, const Epi& E, int tid_in) {
;     ...
;             PG8_LDB(B0, 0, 0); PG8_LDB(B1, 0, 1); PG8_SCHED; PG8_LDA(At, 0, 0); PG8_STAGE(PG8_SA(1, 1), a1 + hstepA, voffA);
;             PG8_WAIT_V(8); PG8_WAIT_L(0); PG8_BAR; PG8_MMA(0, 0, At, B0); PG8_MMA(0, 1, At, B1); PG8_BAR; PG8_SCHED;
;             PG8_LDA(At, 0, 1); PG8_STAGE(PG8_SB(0, 0), b2, voffB); PG8_STAGE(PG8_SB(0, 1), b2 + hstepB, voffB); PG8_STAGE(PG8_SA(0, 0), a2, voffA);
;             PG8_WAIT_V(8); PG8_WAIT_L(0); PG8_BAR; PG8_MMA(1, 0, At, B0); PG8_MMA(1, 1, At, B1); PG8_BAR; PG8_SCHED;
;             PG8_LDB(B0, 1, 0); PG8_LDB(B1, 1, 1); PG8_SCHED; PG8_LDA(At, 1, 0); PG8_STAGE(PG8_SA(0, 1), a2 + hstepA, voffA);
;             PG8_WAIT_V(8); PG8_WAIT_L(0); PG8_BAR; PG8_MMA(0, 0, At, B0); PG8_MMA(0, 1, At, B1); PG8_BAR; PG8_SCHED;
;             PG8_LDA(At, 1, 1); PG8_STAGE(PG8_SB(1, 0), b3, voffB); PG8_STAGE(PG8_SB(1, 1), b3 + hstepB, voffB); PG8_STAGE(PG8_SA(1, 0), a3, voffA);
;             PG8_WAIT_V(8); PG8_WAIT_L(0); PG8_BAR; PG8_MMA(1, 0, At, B0); PG8_MMA(1, 1, At, B1); PG8_BAR; PG8_SCHED;
	s_setprio 0
	s_cselect_b32 s16, s15, s19
	s_mov_b32 m0, s35
	s_mov_b32 s42, s6
	s_mov_b32 s43, s7
	s_sub_i32 s16, s16, s40
	ds_read_b128 v[170:173], v140 offset:16384
	ds_read_b128 v[174:177], v140 offset:17408
	ds_read_b128 v[178:181], v140 offset:18432
	ds_read_b128 v[182:185], v140 offset:19456
	ds_read_b128 v[186:189], v140 offset:20480
	ds_read_b128 v[190:193], v140 offset:21504
	ds_read_b128 v[200:203], v140 offset:22528
	ds_read_b128 v[206:209], v140 offset:23552
	buffer_load_dwordx4 v134, s[40:43], s16 offen lds
	s_mov_b32 m0, s44
	s_add_i32 s74, s16, 0x80000
	buffer_load_dwordx4 v136, s[40:43], s16 offen lds
	s_mov_b32 m0, s45
	s_sub_i32 s17, s17, s4
	buffer_load_dwordx4 v134, s[40:43], s74 offen lds
	s_mov_b32 m0, s46
	s_nop 0
	buffer_load_dwordx4 v136, s[40:43], s74 offen lds
	s_mov_b32 m0, s34
	s_nop 0
	buffer_load_dwordx4 v0, s[4:7], s17 offen lds
	s_waitcnt vmcnt(7)
	s_waitcnt lgkmcnt(0)
	s_setprio 1
	s_barrier
	v_mfma_f32_16x16x32_bf16 v[62:65], v[130:133], v[170:173], v[62:65]
	v_mfma_f32_16x16x32_bf16 v[58:61], v[146:149], v[170:173], v[58:61]
	v_mfma_f32_16x16x32_bf16 v[42:45], v[146:149], v[178:181], v[42:45]
	v_mfma_f32_16x16x32_bf16 v[46:49], v[130:133], v[178:181], v[46:49]
	v_mfma_f32_16x16x32_bf16 v[30:33], v[130:133], v[186:189], v[30:33]
	v_mfma_f32_16x16x32_bf16 v[26:29], v[146:149], v[186:189], v[26:29]
	v_mfma_f32_16x16x32_bf16 v[10:13], v[146:149], v[200:203], v[10:13]
	v_mfma_f32_16x16x32_bf16 v[14:17], v[130:133], v[200:203], v[14:17]
	v_mfma_f32_16x16x32_bf16 v[62:65], v[142:145], v[174:177], v[62:65]
	v_mfma_f32_16x16x32_bf16 v[58:61], v[150:153], v[174:177], v[58:61]
	v_mfma_f32_16x16x32_bf16 v[42:45], v[150:153], v[182:185], v[42:45]
	v_mfma_f32_16x16x32_bf16 v[46:49], v[142:145], v[182:185], v[46:49]
	v_mfma_f32_16x16x32_bf16 v[30:33], v[142:145], v[190:193], v[30:33]
	v_mfma_f32_16x16x32_bf16 v[26:29], v[150:153], v[190:193], v[26:29]
	v_mfma_f32_16x16x32_bf16 v[10:13], v[150:153], v[206:209], v[10:13]
	v_mfma_f32_16x16x32_bf16 v[14:17], v[142:145], v[206:209], v[14:17]
	v_mfma_f32_16x16x32_bf16 v[54:57], v[154:157], v[170:173], v[54:57]
	v_mfma_f32_16x16x32_bf16 v[50:53], v[162:165], v[170:173], v[50:53]
	v_mfma_f32_16x16x32_bf16 v[34:37], v[162:165], v[178:181], v[34:37]
	v_mfma_f32_16x16x32_bf16 v[38:41], v[154:157], v[178:181], v[38:41]
	v_mfma_f32_16x16x32_bf16 v[22:25], v[154:157], v[186:189], v[22:25]
	v_mfma_f32_16x16x32_bf16 v[18:21], v[162:165], v[186:189], v[18:21]
	v_mfma_f32_16x16x32_bf16 v[2:5], v[162:165], v[200:203], v[2:5]
	v_mfma_f32_16x16x32_bf16 v[6:9], v[154:157], v[200:203], v[6:9]
	v_mfma_f32_16x16x32_bf16 v[54:57], v[158:161], v[174:177], v[54:57]
	v_mfma_f32_16x16x32_bf16 v[50:53], v[166:169], v[174:177], v[50:53]
	v_mfma_f32_16x16x32_bf16 v[34:37], v[166:169], v[182:185], v[34:37]
	v_mfma_f32_16x16x32_bf16 v[38:41], v[158:161], v[182:185], v[38:41]
	v_mfma_f32_16x16x32_bf16 v[22:25], v[158:161], v[190:193], v[22:25]
	v_mfma_f32_16x16x32_bf16 v[18:21], v[166:169], v[190:193], v[18:21]
	v_mfma_f32_16x16x32_bf16 v[2:5], v[166:169], v[206:209], v[2:5]
	v_mfma_f32_16x16x32_bf16 v[6:9], v[158:161], v[206:209], v[6:9]
	s_barrier
	s_setprio 0
	v_add_u32_e32 v141, 0x18000, v139
	ds_read_b128 v[130:133], v141
	ds_read_b128 v[142:145], v141 offset:1024
	ds_read_b128 v[146:149], v141 offset:2048
	ds_read_b128 v[150:153], v141 offset:3072
	v_add_u32_e32 v141, 0x1c000, v139
	ds_read_b128 v[154:157], v141
	ds_read_b128 v[158:161], v141 offset:1024
	ds_read_b128 v[162:165], v141 offset:2048
	ds_read_b128 v[166:169], v141 offset:3072
	s_add_i32 s74, s17, 0x80000
	s_mov_b32 m0, s48
	ds_read_b128 v[170:173], v140 offset:32768
	ds_read_b128 v[174:177], v140 offset:33792
	ds_read_b128 v[178:181], v140 offset:34816
	ds_read_b128 v[182:185], v140 offset:35840
	ds_read_b128 v[186:189], v140 offset:36864
	ds_read_b128 v[190:193], v140 offset:37888
	ds_read_b128 v[200:203], v140 offset:38912
	ds_read_b128 v[206:209], v140 offset:39936
	s_mov_b32 m0, s47
	s_nop 0
	buffer_load_dwordx4 v135, s[4:7], s17 offen lds
	s_mov_b32 m0, s48
	s_nop 0
	buffer_load_dwordx4 v0, s[4:7], s74 offen lds
	s_mov_b32 m0, s49
	s_nop 0
	buffer_load_dwordx4 v135, s[4:7], s74 offen lds
	s_waitcnt vmcnt(8)
	s_waitcnt lgkmcnt(0)
	s_setprio 1
	s_barrier
	v_mfma_f32_16x16x32_bf16 v[126:129], v[130:133], v[170:173], v[126:129]
	v_mfma_f32_16x16x32_bf16 v[122:125], v[146:149], v[170:173], v[122:125]
	v_mfma_f32_16x16x32_bf16 v[106:109], v[146:149], v[178:181], v[106:109]
	v_mfma_f32_16x16x32_bf16 v[110:113], v[130:133], v[178:181], v[110:113]
	v_mfma_f32_16x16x32_bf16 v[94:97], v[130:133], v[186:189], v[94:97]
	v_mfma_f32_16x16x32_bf16 v[90:93], v[146:149], v[186:189], v[90:93]
	v_mfma_f32_16x16x32_bf16 v[74:77], v[146:149], v[200:203], v[74:77]
	v_mfma_f32_16x16x32_bf16 v[78:81], v[130:133], v[200:203], v[78:81]
	v_mfma_f32_16x16x32_bf16 v[126:129], v[142:145], v[174:177], v[126:129]
	v_mfma_f32_16x16x32_bf16 v[122:125], v[150:153], v[174:177], v[122:125]
	v_mfma_f32_16x16x32_bf16 v[106:109], v[150:153], v[182:185], v[106:109]
	v_mfma_f32_16x16x32_bf16 v[110:113], v[142:145], v[182:185], v[110:113]
	v_mfma_f32_16x16x32_bf16 v[94:97], v[142:145], v[190:193], v[94:97]
	v_mfma_f32_16x16x32_bf16 v[90:93], v[150:153], v[190:193], v[90:93]
	v_mfma_f32_16x16x32_bf16 v[74:77], v[150:153], v[206:209], v[74:77]
	v_mfma_f32_16x16x32_bf16 v[78:81], v[142:145], v[206:209], v[78:81]
	v_mfma_f32_16x16x32_bf16 v[118:121], v[154:157], v[170:173], v[118:121]
	v_mfma_f32_16x16x32_bf16 v[114:117], v[162:165], v[170:173], v[114:117]
	v_mfma_f32_16x16x32_bf16 v[98:101], v[162:165], v[178:181], v[98:101]
	v_mfma_f32_16x16x32_bf16 v[102:105], v[154:157], v[178:181], v[102:105]
	v_mfma_f32_16x16x32_bf16 v[86:89], v[154:157], v[186:189], v[86:89]
	v_mfma_f32_16x16x32_bf16 v[82:85], v[162:165], v[186:189], v[82:85]
	v_mfma_f32_16x16x32_bf16 v[66:69], v[162:165], v[200:203], v[66:69]
	v_mfma_f32_16x16x32_bf16 v[70:73], v[154:157], v[200:203], v[70:73]
	v_mfma_f32_16x16x32_bf16 v[118:121], v[158:161], v[174:177], v[118:121]
	v_mfma_f32_16x16x32_bf16 v[114:117], v[166:169], v[174:177], v[114:117]
	v_mfma_f32_16x16x32_bf16 v[98:101], v[166:169], v[182:185], v[98:101]
	v_mfma_f32_16x16x32_bf16 v[102:105], v[158:161], v[182:185], v[102:105]
	v_mfma_f32_16x16x32_bf16 v[86:89], v[158:161], v[190:193], v[86:89]
	v_mfma_f32_16x16x32_bf16 v[82:85], v[166:169], v[190:193], v[82:85]
	v_mfma_f32_16x16x32_bf16 v[66:69], v[166:169], v[206:209], v[66:69]
	v_mfma_f32_16x16x32_bf16 v[70:73], v[158:161], v[206:209], v[70:73]
	s_barrier
; #define PG8_STAGE(bufoff, gbase, voff) do { const int so_ = (int)(unsigned)((const char*)(gbase) - base_##voff); _Pragma("unroll") for (int _i = 0; _i < 2; ++_i) \
;         __builtin_amdgcn_raw_ptr_buffer_load_lds(rs_##voff, (PG8_LAS unsigned*)(lds + (bufoff) + ldsw + _i * 8192), 16, (int)(voff)[_i], so_, 0, 0); } while (0)
; #define PG8_LDA(dst, b, h) do { _Pragma("unroll") for (int m = 0; m < 4; ++m) _Pragma("unroll") for (int k = 0; k < 2; ++k) dst[m][k] = *(const PG8_LAS bf16x8*)(lds + PG8_SA(b, h) + aoff + m * 2048 + k * 1024); } while (0)
; #define PG8_LDB(dst, b, h) do { _Pragma("unroll") for (int n = 0; n < 2; ++n) _Pragma("unroll") for (int k = 0; k < 2; ++k) dst[n][k] = *(const PG8_LAS bf16x8*)(lds + PG8_SB(b, h) + boff + n * 2048 + k * 1024); } while (0)
; #define PG8_MMA(ai, bj, At, Bt) do { __builtin_amdgcn_s_setprio(1); _Pragma("unroll") for (int m = 0; m < 4; ++m) _Pragma("unroll") for (int n = 0; n < 2; ++n) _Pragma("unroll") for (int k = 0; k < 2; ++k) \
;         acc[ai][bj][m][n] = __builtin_amdgcn_mfma_f32_16x16x32_bf16(Bt[n][k], At[m][k], acc[ai][bj][m][n], 0, 0, 0); __builtin_amdgcn_s_setprio(0); } while (0)
; template <class Epi, class Sched, bool ALIGN_EPI = false, bool SP2 = false>
; __device__ __forceinline__ void gemm_phase(PG8_LAS unsigned char* lds, const Gemm g, const Sched& S, const Epi& E, int tid_in) {
;     ...
;             PG8_LDB(B0, 0, 0); PG8_LDB(B1, 0, 1); PG8_SCHED; PG8_LDA(At, 0, 0); PG8_STAGE(PG8_SA(1, 1), a1 + hstepA, voffA);
;             PG8_WAIT_V(8); PG8_WAIT_L(0); PG8_BAR; PG8_MMA(0, 0, At, B0); PG8_MMA(0, 1, At, B1); PG8_BAR; PG8_SCHED;
;             PG8_LDA(At, 0, 1); PG8_STAGE(PG8_SB(0, 0), b2, voffB); PG8_STAGE(PG8_SB(0, 1), b2 + hstepB, voffB); PG8_STAGE(PG8_SA(0, 0), a2, voffA);
;             PG8_WAIT_V(8); PG8_WAIT_L(0); PG8_BAR; PG8_MMA(1, 0, At, B0); PG8_MMA(1, 1, At, B1); PG8_BAR; PG8_SCHED;
;             PG8_LDB(B0, 1, 0); PG8_LDB(B1, 1, 1); PG8_SCHED; PG8_LDA(At, 1, 0); PG8_STAGE(PG8_SA(0, 1), a2 + hstepA, voffA);
;             PG8_WAIT_V(8); PG8_WAIT_L(0); PG8_BAR; PG8_MMA(0, 0, At, B0); PG8_MMA(0, 1, At, B1); PG8_BAR; PG8_SCHED;
;             PG8_LDA(At, 1, 1); PG8_STAGE(PG8_SB(1, 0), b3, voffB); PG8_STAGE(PG8_SB(1, 1), b3 + hstepB, voffB); PG8_STAGE(PG8_SA(1, 0), a3, voffA);
;             PG8_WAIT_V(8); PG8_WAIT_L(0); PG8_BAR; PG8_MMA(1, 0, At, B0); PG8_MMA(1, 1, At, B1); PG8_BAR; PG8_SCHED;
	s_setprio 0
	s_mov_b32 m0, s53
	s_add_i32 s74, s16, 0x80
	ds_read_b128 v[170:173], v140 offset:49152
	ds_read_b128 v[174:177], v140 offset:50176
	ds_read_b128 v[178:181], v140 offset:51200
	ds_read_b128 v[182:185], v140 offset:52224
	ds_read_b128 v[186:189], v140 offset:53248
	ds_read_b128 v[190:193], v140 offset:54272
	ds_read_b128 v[200:203], v140 offset:55296
	ds_read_b128 v[206:209], v140 offset:56320
	buffer_load_dwordx4 v134, s[40:43], s74 offen lds
	s_mov_b32 m0, s60
	s_add_i32 s16, s16, 0x80080
	buffer_load_dwordx4 v136, s[40:43], s74 offen lds
	s_mov_b32 m0, s63
	s_addk_i32 s17, 0x80
	buffer_load_dwordx4 v134, s[40:43], s16 offen lds
	s_mov_b32 m0, s66
	s_nop 0
	buffer_load_dwordx4 v136, s[40:43], s16 offen lds
	s_mov_b32 m0, s61
	s_nop 0
	buffer_load_dwordx4 v0, s[4:7], s17 offen lds
	s_waitcnt vmcnt(7)
	s_waitcnt lgkmcnt(0)
	s_setprio 1
	s_barrier
	v_mfma_f32_16x16x32_bf16 v[62:65], v[130:133], v[170:173], v[62:65]
	v_mfma_f32_16x16x32_bf16 v[58:61], v[146:149], v[170:173], v[58:61]
	v_mfma_f32_16x16x32_bf16 v[42:45], v[146:149], v[178:181], v[42:45]
	v_mfma_f32_16x16x32_bf16 v[46:49], v[130:133], v[178:181], v[46:49]
	v_mfma_f32_16x16x32_bf16 v[30:33], v[130:133], v[186:189], v[30:33]
	v_mfma_f32_16x16x32_bf16 v[26:29], v[146:149], v[186:189], v[26:29]
	v_mfma_f32_16x16x32_bf16 v[10:13], v[146:149], v[200:203], v[10:13]
	v_mfma_f32_16x16x32_bf16 v[14:17], v[130:133], v[200:203], v[14:17]
	v_mfma_f32_16x16x32_bf16 v[62:65], v[142:145], v[174:177], v[62:65]
	v_mfma_f32_16x16x32_bf16 v[58:61], v[150:153], v[174:177], v[58:61]
	v_mfma_f32_16x16x32_bf16 v[42:45], v[150:153], v[182:185], v[42:45]
	v_mfma_f32_16x16x32_bf16 v[46:49], v[142:145], v[182:185], v[46:49]
	v_mfma_f32_16x16x32_bf16 v[30:33], v[142:145], v[190:193], v[30:33]
	v_mfma_f32_16x16x32_bf16 v[26:29], v[150:153], v[190:193], v[26:29]
	v_mfma_f32_16x16x32_bf16 v[10:13], v[150:153], v[206:209], v[10:13]
	v_mfma_f32_16x16x32_bf16 v[14:17], v[142:145], v[206:209], v[14:17]
	v_mfma_f32_16x16x32_bf16 v[54:57], v[154:157], v[170:173], v[54:57]
	v_mfma_f32_16x16x32_bf16 v[50:53], v[162:165], v[170:173], v[50:53]
	v_mfma_f32_16x16x32_bf16 v[34:37], v[162:165], v[178:181], v[34:37]
	v_mfma_f32_16x16x32_bf16 v[38:41], v[154:157], v[178:181], v[38:41]
	v_mfma_f32_16x16x32_bf16 v[22:25], v[154:157], v[186:189], v[22:25]
	v_mfma_f32_16x16x32_bf16 v[18:21], v[162:165], v[186:189], v[18:21]
	v_mfma_f32_16x16x32_bf16 v[2:5], v[162:165], v[200:203], v[2:5]
	v_mfma_f32_16x16x32_bf16 v[6:9], v[154:157], v[200:203], v[6:9]
	v_mfma_f32_16x16x32_bf16 v[54:57], v[158:161], v[174:177], v[54:57]
	v_mfma_f32_16x16x32_bf16 v[50:53], v[166:169], v[174:177], v[50:53]
	v_mfma_f32_16x16x32_bf16 v[34:37], v[166:169], v[182:185], v[34:37]
	v_mfma_f32_16x16x32_bf16 v[38:41], v[158:161], v[182:185], v[38:41]
	v_mfma_f32_16x16x32_bf16 v[22:25], v[158:161], v[190:193], v[22:25]
	v_mfma_f32_16x16x32_bf16 v[18:21], v[166:169], v[190:193], v[18:21]
	v_mfma_f32_16x16x32_bf16 v[2:5], v[166:169], v[206:209], v[2:5]
	v_mfma_f32_16x16x32_bf16 v[6:9], v[158:161], v[206:209], v[6:9]
	s_barrier
	s_setprio 0
	s_add_i32 s73, s73, 2
	s_add_u32 s19, s19, 0x100
	s_addc_u32 s21, s21, 0
	s_cmp_gt_u32 s73, 29
	s_mov_b64 s[16:17], s[38:39]
	s_cbranch_scc0 .LBB0_1514
	s_branch .Lyng_after3
.Lyng_loop3:
	v_add_u32_e32 v141, 0x10000, v139
	ds_read_b128 v[130:133], v141
	ds_read_b128 v[142:145], v141 offset:1024
	ds_read_b128 v[146:149], v141 offset:2048
	ds_read_b128 v[150:153], v141 offset:3072
	v_add_u32_e32 v141, 0x14000, v139
	ds_read_b128 v[154:157], v141
	ds_read_b128 v[158:161], v141 offset:1024
	ds_read_b128 v[162:165], v141 offset:2048
	ds_read_b128 v[166:169], v141 offset:3072
	s_add_u32 s38, s16, 0x100
	s_addc_u32 s39, s17, 0
	s_sub_i32 s16, s16, s4
	s_add_i32 s16, s16, 0x80080
	s_sub_i32 s74, s16, 0x80000
	s_cmp_eq_u32 s73, 28
	s_cselect_b32 s17, s18, s38
	s_mov_b32 m0, s67
	ds_read_b128 v[170:173], v140
	ds_read_b128 v[174:177], v140 offset:1024
	ds_read_b128 v[178:181], v140 offset:2048
	ds_read_b128 v[182:185], v140 offset:3072
	ds_read_b128 v[186:189], v140 offset:4096
	ds_read_b128 v[190:193], v140 offset:5120
	ds_read_b128 v[200:203], v140 offset:6144
	ds_read_b128 v[206:209], v140 offset:7168
	s_mov_b32 m0, s62
	s_nop 0
	buffer_load_dwordx4 v135, s[4:7], s74 offen lds
	s_mov_b32 m0, s67
	s_nop 0
	buffer_load_dwordx4 v0, s[4:7], s16 offen lds
	s_mov_b32 m0, s68
	s_nop 0
	buffer_load_dwordx4 v135, s[4:7], s16 offen lds
	s_waitcnt vmcnt(8)
	s_waitcnt lgkmcnt(0)
	s_setprio 2
	s_barrier
	v_mfma_f32_16x16x32_bf16 v[126:129], v[130:133], v[170:173], v[126:129]
	v_mfma_f32_16x16x32_bf16 v[122:125], v[146:149], v[170:173], v[122:125]
	v_mfma_f32_16x16x32_bf16 v[106:109], v[146:149], v[178:181], v[106:109]
	v_mfma_f32_16x16x32_bf16 v[110:113], v[130:133], v[178:181], v[110:113]
	v_mfma_f32_16x16x32_bf16 v[94:97], v[130:133], v[186:189], v[94:97]
	v_mfma_f32_16x16x32_bf16 v[90:93], v[146:149], v[186:189], v[90:93]
	v_mfma_f32_16x16x32_bf16 v[74:77], v[146:149], v[200:203], v[74:77]
	v_mfma_f32_16x16x32_bf16 v[78:81], v[130:133], v[200:203], v[78:81]
	v_mfma_f32_16x16x32_bf16 v[126:129], v[142:145], v[174:177], v[126:129]
	v_mfma_f32_16x16x32_bf16 v[122:125], v[150:153], v[174:177], v[122:125]
	v_mfma_f32_16x16x32_bf16 v[106:109], v[150:153], v[182:185], v[106:109]
	v_mfma_f32_16x16x32_bf16 v[110:113], v[142:145], v[182:185], v[110:113]
	v_mfma_f32_16x16x32_bf16 v[94:97], v[142:145], v[190:193], v[94:97]
	v_mfma_f32_16x16x32_bf16 v[90:93], v[150:153], v[190:193], v[90:93]
	v_mfma_f32_16x16x32_bf16 v[74:77], v[150:153], v[206:209], v[74:77]
	v_mfma_f32_16x16x32_bf16 v[78:81], v[142:145], v[206:209], v[78:81]
	v_mfma_f32_16x16x32_bf16 v[118:121], v[154:157], v[170:173], v[118:121]
	v_mfma_f32_16x16x32_bf16 v[114:117], v[162:165], v[170:173], v[114:117]
	v_mfma_f32_16x16x32_bf16 v[98:101], v[162:165], v[178:181], v[98:101]
	v_mfma_f32_16x16x32_bf16 v[102:105], v[154:157], v[178:181], v[102:105]
	v_mfma_f32_16x16x32_bf16 v[86:89], v[154:157], v[186:189], v[86:89]
	v_mfma_f32_16x16x32_bf16 v[82:85], v[162:165], v[186:189], v[82:85]
	v_mfma_f32_16x16x32_bf16 v[66:69], v[162:165], v[200:203], v[66:69]
	v_mfma_f32_16x16x32_bf16 v[70:73], v[154:157], v[200:203], v[70:73]
	v_mfma_f32_16x16x32_bf16 v[118:121], v[158:161], v[174:177], v[118:121]
	v_mfma_f32_16x16x32_bf16 v[114:117], v[166:169], v[174:177], v[114:117]
	v_mfma_f32_16x16x32_bf16 v[98:101], v[166:169], v[182:185], v[98:101]
	v_mfma_f32_16x16x32_bf16 v[102:105], v[158:161], v[182:185], v[102:105]
	v_mfma_f32_16x16x32_bf16 v[86:89], v[158:161], v[190:193], v[86:89]
	v_mfma_f32_16x16x32_bf16 v[82:85], v[166:169], v[190:193], v[82:85]
	v_mfma_f32_16x16x32_bf16 v[66:69], v[166:169], v[206:209], v[66:69]
	v_mfma_f32_16x16x32_bf16 v[70:73], v[158:161], v[206:209], v[70:73]
	s_barrier
; #define PG8_STAGE(bufoff, gbase, voff) do { const int so_ = (int)(unsigned)((const char*)(gbase) - base_##voff); _Pragma("unroll") for (int _i = 0; _i < 2; ++_i) \
;         __builtin_amdgcn_raw_ptr_buffer_load_lds(rs_##voff, (PG8_LAS unsigned*)(lds + (bufoff) + ldsw + _i * 8192), 16, (int)(voff)[_i], so_, 0, 0); } while (0)
; #define PG8_LDA(dst, b, h) do { _Pragma("unroll") for (int m = 0; m < 4; ++m) _Pragma("unroll") for (int k = 0; k < 2; ++k) dst[m][k] = *(const PG8_LAS bf16x8*)(lds + PG8_SA(b, h) + aoff + m * 2048 + k * 1024); } while (0)
; #define PG8_LDB(dst, b, h) do { _Pragma("unroll") for (int n = 0; n < 2; ++n) _Pragma("unroll") for (int k = 0; k < 2; ++k) dst[n][k] = *(const PG8_LAS bf16x8*)(lds + PG8_SB(b, h) + boff + n * 2048 + k * 1024); } while (0)
; #define PG8_MMA(ai, bj, At, Bt) do { __builtin_amdgcn_s_setprio(1); _Pragma("unroll") for (int m = 0; m < 4; ++m) _Pragma("unroll") for (int n = 0; n < 2; ++n) _Pragma("unroll") for (int k = 0; k < 2; ++k) \
;         acc[ai][bj][m][n] = __builtin_amdgcn_mfma_f32_16x16x32_bf16(Bt[n][k], At[m][k], acc[ai][bj][m][n], 0, 0, 0); __builtin_amdgcn_s_setprio(0); } while (0)
; template <class Epi, class Sched, bool ALIGN_EPI = false, bool SP2 = false>
; __device__ __forceinline__ void gemm_phase(PG8_LAS unsigned char* lds, const Gemm g, const Sched& S, const Epi& E, int tid_in) {
;     ...
;             PG8_LDB(B0, 0, 0); PG8_LDB(B1, 0, 1); PG8_SCHED; PG8_LDA(At, 0, 0); PG8_STAGE(PG8_SA(1, 1), a1 + hstepA, voffA);
;             PG8_WAIT_V(8); PG8_WAIT_L(0); PG8_BAR; PG8_MMA(0, 0, At, B0); PG8_MMA(0, 1, At, B1); PG8_BAR; PG8_SCHED;
;             PG8_LDA(At, 0, 1); PG8_STAGE(PG8_SB(0, 0), b2, voffB); PG8_STAGE(PG8_SB(0, 1), b2 + hstepB, voffB); PG8_STAGE(PG8_SA(0, 0), a2, voffA);
;             PG8_WAIT_V(8); PG8_WAIT_L(0); PG8_BAR; PG8_MMA(1, 0, At, B0); PG8_MMA(1, 1, At, B1); PG8_BAR; PG8_SCHED;
;             PG8_LDB(B0, 1, 0); PG8_LDB(B1, 1, 1); PG8_SCHED; PG8_LDA(At, 1, 0); PG8_STAGE(PG8_SA(0, 1), a2 + hstepA, voffA);
;             PG8_WAIT_V(8); PG8_WAIT_L(0); PG8_BAR; PG8_MMA(0, 0, At, B0); PG8_MMA(0, 1, At, B1); PG8_BAR; PG8_SCHED;
;             PG8_LDA(At, 1, 1); PG8_STAGE(PG8_SB(1, 0), b3, voffB); PG8_STAGE(PG8_SB(1, 1), b3 + hstepB, voffB); PG8_STAGE(PG8_SA(1, 0), a3, voffA);
;             PG8_WAIT_V(8); PG8_WAIT_L(0); PG8_BAR; PG8_MMA(1, 0, At, B0); PG8_MMA(1, 1, At, B1); PG8_BAR; PG8_SCHED;
	s_setprio 1
	s_cselect_b32 s16, s15, s19
	s_mov_b32 m0, s35
	s_mov_b32 s42, s6
	s_mov_b32 s43, s7
	s_sub_i32 s16, s16, s40
	ds_read_b128 v[170:173], v140 offset:16384
	ds_read_b128 v[174:177], v140 offset:17408
	ds_read_b128 v[178:181], v140 offset:18432
	ds_read_b128 v[182:185], v140 offset:19456
	ds_read_b128 v[186:189], v140 offset:20480
	ds_read_b128 v[190:193], v140 offset:21504
	ds_read_b128 v[200:203], v140 offset:22528
	ds_read_b128 v[206:209], v140 offset:23552
	buffer_load_dwordx4 v134, s[40:43], s16 offen lds
	s_mov_b32 m0, s44
	s_add_i32 s74, s16, 0x80000
	buffer_load_dwordx4 v136, s[40:43], s16 offen lds
	s_mov_b32 m0, s45
	s_sub_i32 s17, s17, s4
	buffer_load_dwordx4 v134, s[40:43], s74 offen lds
	s_mov_b32 m0, s46
	s_nop 0
	buffer_load_dwordx4 v136, s[40:43], s74 offen lds
	s_mov_b32 m0, s34
	s_nop 0
	buffer_load_dwordx4 v0, s[4:7], s17 offen lds
	s_waitcnt vmcnt(7)
	s_waitcnt lgkmcnt(0)
	s_setprio 2
	s_barrier
	v_mfma_f32_16x16x32_bf16 v[62:65], v[130:133], v[170:173], v[62:65]
	v_mfma_f32_16x16x32_bf16 v[58:61], v[146:149], v[170:173], v[58:61]
	v_mfma_f32_16x16x32_bf16 v[42:45], v[146:149], v[178:181], v[42:45]
	v_mfma_f32_16x16x32_bf16 v[46:49], v[130:133], v[178:181], v[46:49]
	v_mfma_f32_16x16x32_bf16 v[30:33], v[130:133], v[186:189], v[30:33]
	v_mfma_f32_16x16x32_bf16 v[26:29], v[146:149], v[186:189], v[26:29]
	v_mfma_f32_16x16x32_bf16 v[10:13], v[146:149], v[200:203], v[10:13]
	v_mfma_f32_16x16x32_bf16 v[14:17], v[130:133], v[200:203], v[14:17]
	v_mfma_f32_16x16x32_bf16 v[62:65], v[142:145], v[174:177], v[62:65]
	v_mfma_f32_16x16x32_bf16 v[58:61], v[150:153], v[174:177], v[58:61]
	v_mfma_f32_16x16x32_bf16 v[42:45], v[150:153], v[182:185], v[42:45]
	v_mfma_f32_16x16x32_bf16 v[46:49], v[142:145], v[182:185], v[46:49]
	v_mfma_f32_16x16x32_bf16 v[30:33], v[142:145], v[190:193], v[30:33]
	v_mfma_f32_16x16x32_bf16 v[26:29], v[150:153], v[190:193], v[26:29]
	v_mfma_f32_16x16x32_bf16 v[10:13], v[150:153], v[206:209], v[10:13]
	v_mfma_f32_16x16x32_bf16 v[14:17], v[142:145], v[206:209], v[14:17]
	v_mfma_f32_16x16x32_bf16 v[54:57], v[154:157], v[170:173], v[54:57]
	v_mfma_f32_16x16x32_bf16 v[50:53], v[162:165], v[170:173], v[50:53]
	v_mfma_f32_16x16x32_bf16 v[34:37], v[162:165], v[178:181], v[34:37]
	v_mfma_f32_16x16x32_bf16 v[38:41], v[154:157], v[178:181], v[38:41]
	v_mfma_f32_16x16x32_bf16 v[22:25], v[154:157], v[186:189], v[22:25]
	v_mfma_f32_16x16x32_bf16 v[18:21], v[162:165], v[186:189], v[18:21]
	v_mfma_f32_16x16x32_bf16 v[2:5], v[162:165], v[200:203], v[2:5]
	v_mfma_f32_16x16x32_bf16 v[6:9], v[154:157], v[200:203], v[6:9]
	v_mfma_f32_16x16x32_bf16 v[54:57], v[158:161], v[174:177], v[54:57]
	v_mfma_f32_16x16x32_bf16 v[50:53], v[166:169], v[174:177], v[50:53]
	v_mfma_f32_16x16x32_bf16 v[34:37], v[166:169], v[182:185], v[34:37]
	v_mfma_f32_16x16x32_bf16 v[38:41], v[158:161], v[182:185], v[38:41]
	v_mfma_f32_16x16x32_bf16 v[22:25], v[158:161], v[190:193], v[22:25]
	v_mfma_f32_16x16x32_bf16 v[18:21], v[166:169], v[190:193], v[18:21]
	v_mfma_f32_16x16x32_bf16 v[2:5], v[166:169], v[206:209], v[2:5]
	v_mfma_f32_16x16x32_bf16 v[6:9], v[158:161], v[206:209], v[6:9]
	s_barrier
	s_setprio 1
	v_add_u32_e32 v141, 0x18000, v139
	ds_read_b128 v[130:133], v141
	ds_read_b128 v[142:145], v141 offset:1024
	ds_read_b128 v[146:149], v141 offset:2048
	ds_read_b128 v[150:153], v141 offset:3072
	v_add_u32_e32 v141, 0x1c000, v139
	ds_read_b128 v[154:157], v141
	ds_read_b128 v[158:161], v141 offset:1024
	ds_read_b128 v[162:165], v141 offset:2048
	ds_read_b128 v[166:169], v141 offset:3072
	s_add_i32 s74, s17, 0x80000
	s_mov_b32 m0, s48
	ds_read_b128 v[170:173], v140 offset:32768
	ds_read_b128 v[174:177], v140 offset:33792
	ds_read_b128 v[178:181], v140 offset:34816
	ds_read_b128 v[182:185], v140 offset:35840
	ds_read_b128 v[186:189], v140 offset:36864
	ds_read_b128 v[190:193], v140 offset:37888
	ds_read_b128 v[200:203], v140 offset:38912
	ds_read_b128 v[206:209], v140 offset:39936
	s_mov_b32 m0, s47
	s_nop 0
	buffer_load_dwordx4 v135, s[4:7], s17 offen lds
	s_mov_b32 m0, s48
	s_nop 0
	buffer_load_dwordx4 v0, s[4:7], s74 offen lds
	s_mov_b32 m0, s49
	s_nop 0
	buffer_load_dwordx4 v135, s[4:7], s74 offen lds
	s_waitcnt vmcnt(8)
	s_waitcnt lgkmcnt(0)
	s_setprio 2
	s_barrier
; #define PG8_STAGE(bufoff, gbase, voff) do { const int so_ = (int)(unsigned)((const char*)(gbase) - base_##voff); _Pragma("unroll") for (int _i = 0; _i < 2; ++_i) \
;         __builtin_amdgcn_raw_ptr_buffer_load_lds(rs_##voff, (PG8_LAS unsigned*)(lds + (bufoff) + ldsw + _i * 8192), 16, (int)(voff)[_i], so_, 0, 0); } while (0)
; #define PG8_LDA(dst, b, h) do { _Pragma("unroll") for (int m = 0; m < 4; ++m) _Pragma("unroll") for (int k = 0; k < 2; ++k) dst[m][k] = *(const PG8_LAS bf16x8*)(lds + PG8_SA(b, h) + aoff + m * 2048 + k * 1024); } while (0)
; #define PG8_LDB(dst, b, h) do { _Pragma("unroll") for (int n = 0; n < 2; ++n) _Pragma("unroll") for (int k = 0; k < 2; ++k) dst[n][k] = *(const PG8_LAS bf16x8*)(lds + PG8_SB(b, h) + boff + n * 2048 + k * 1024); } while (0)
; #define PG8_WAIT_V(n) asm volatile("s_waitcnt vmcnt(" #n ")" ::: "memory")
; #define PG8_WAIT_L(n) asm volatile("s_waitcnt lgkmcnt(" #n ")" ::: "memory")
; #define PG8_BAR __builtin_amdgcn_s_barrier()
; template <class Epi, class Sched, bool ALIGN_EPI = false, bool SP2 = false>
; __device__ __forceinline__ void gemm_phase(PG8_LAS unsigned char* lds, const Gemm g, const Sched& S, const Epi& E, int tid_in) {
;     ...
;             PG8_LDB(B0, 0, 0); PG8_LDB(B1, 0, 1); PG8_SCHED; PG8_LDA(At, 0, 0); PG8_STAGE(PG8_SA(1, 1), a1 + hstepA, voffA);
;             PG8_WAIT_V(8); PG8_WAIT_L(0); PG8_BAR; PG8_MMA(0, 0, At, B0); PG8_MMA(0, 1, At, B1); PG8_BAR; PG8_SCHED;
;             PG8_LDA(At, 0, 1); PG8_STAGE(PG8_SB(0, 0), b2, voffB); PG8_STAGE(PG8_SB(0, 1), b2 + hstepB, voffB); PG8_STAGE(PG8_SA(0, 0), a2, voffA);
;             PG8_WAIT_V(8); PG8_WAIT_L(0); PG8_BAR; PG8_MMA(1, 0, At, B0); PG8_MMA(1, 1, At, B1); PG8_BAR; PG8_SCHED;
;             PG8_LDB(B0, 1, 0); PG8_LDB(B1, 1, 1); PG8_SCHED; PG8_LDA(At, 1, 0); PG8_STAGE(PG8_SA(0, 1), a2 + hstepA, voffA);
;             PG8_WAIT_V(8); PG8_WAIT_L(0); PG8_BAR; PG8_MMA(0, 0, At, B0); PG8_MMA(0, 1, At, B1); PG8_BAR; PG8_SCHED;
;             PG8_LDA(At, 1, 1); PG8_STAGE(PG8_SB(1, 0), b3, voffB); PG8_STAGE(PG8_SB(1, 1), b3 + hstepB, voffB); PG8_STAGE(PG8_SA(1, 0), a3, voffA);
;             PG8_WAIT_V(8); PG8_WAIT_L(0); PG8_BAR; PG8_MMA(1, 0, At, B0); PG8_MMA(1, 1, At, B1); PG8_BAR; PG8_SCHED;
;     ...
;         if constexpr (ALIGN_EPI) { if (wr == 0) PG8_BAR; }
;         if constexpr (!Epi::AFTER_DRAIN) { E(acc, cur, wr, wc, fr, fq); S.done(cur); }
	v_mfma_f32_16x16x32_bf16 v[126:129], v[130:133], v[170:173], v[126:129]
	v_mfma_f32_16x16x32_bf16 v[122:125], v[146:149], v[170:173], v[122:125]
	v_mfma_f32_16x16x32_bf16 v[106:109], v[146:149], v[178:181], v[106:109]
	v_mfma_f32_16x16x32_bf16 v[110:113], v[130:133], v[178:181], v[110:113]
	v_mfma_f32_16x16x32_bf16 v[94:97], v[130:133], v[186:189], v[94:97]
	v_mfma_f32_16x16x32_bf16 v[90:93], v[146:149], v[186:189], v[90:93]
	v_mfma_f32_16x16x32_bf16 v[74:77], v[146:149], v[200:203], v[74:77]
	v_mfma_f32_16x16x32_bf16 v[78:81], v[130:133], v[200:203], v[78:81]
	v_mfma_f32_16x16x32_bf16 v[126:129], v[142:145], v[174:177], v[126:129]
	v_mfma_f32_16x16x32_bf16 v[122:125], v[150:153], v[174:177], v[122:125]
	v_mfma_f32_16x16x32_bf16 v[106:109], v[150:153], v[182:185], v[106:109]
	v_mfma_f32_16x16x32_bf16 v[110:113], v[142:145], v[182:185], v[110:113]
	v_mfma_f32_16x16x32_bf16 v[94:97], v[142:145], v[190:193], v[94:97]
	v_mfma_f32_16x16x32_bf16 v[90:93], v[150:153], v[190:193], v[90:93]
	v_mfma_f32_16x16x32_bf16 v[74:77], v[150:153], v[206:209], v[74:77]
	v_mfma_f32_16x16x32_bf16 v[78:81], v[142:145], v[206:209], v[78:81]
	v_mfma_f32_16x16x32_bf16 v[118:121], v[154:157], v[170:173], v[118:121]
	v_mfma_f32_16x16x32_bf16 v[114:117], v[162:165], v[170:173], v[114:117]
	v_mfma_f32_16x16x32_bf16 v[98:101], v[162:165], v[178:181], v[98:101]
	v_mfma_f32_16x16x32_bf16 v[102:105], v[154:157], v[178:181], v[102:105]
	v_mfma_f32_16x16x32_bf16 v[86:89], v[154:157], v[186:189], v[86:89]
	v_mfma_f32_16x16x32_bf16 v[82:85], v[162:165], v[186:189], v[82:85]
	v_mfma_f32_16x16x32_bf16 v[66:69], v[162:165], v[200:203], v[66:69]
	v_mfma_f32_16x16x32_bf16 v[70:73], v[154:157], v[200:203], v[70:73]
	v_mfma_f32_16x16x32_bf16 v[118:121], v[158:161], v[174:177], v[118:121]
	v_mfma_f32_16x16x32_bf16 v[114:117], v[166:169], v[174:177], v[114:117]
	v_mfma_f32_16x16x32_bf16 v[98:101], v[166:169], v[182:185], v[98:101]
	v_mfma_f32_16x16x32_bf16 v[102:105], v[158:161], v[182:185], v[102:105]
	v_mfma_f32_16x16x32_bf16 v[86:89], v[158:161], v[190:193], v[86:89]
	v_mfma_f32_16x16x32_bf16 v[82:85], v[166:169], v[190:193], v[82:85]
	v_mfma_f32_16x16x32_bf16 v[66:69], v[166:169], v[206:209], v[66:69]
	v_mfma_f32_16x16x32_bf16 v[70:73], v[158:161], v[206:209], v[70:73]
	s_barrier
	s_setprio 1
	s_mov_b32 m0, s53
	s_add_i32 s74, s16, 0x80
	ds_read_b128 v[170:173], v140 offset:49152
	ds_read_b128 v[174:177], v140 offset:50176
	ds_read_b128 v[178:181], v140 offset:51200
	ds_read_b128 v[182:185], v140 offset:52224
	ds_read_b128 v[186:189], v140 offset:53248
	ds_read_b128 v[190:193], v140 offset:54272
	ds_read_b128 v[200:203], v140 offset:55296
	ds_read_b128 v[206:209], v140 offset:56320
	buffer_load_dwordx4 v134, s[40:43], s74 offen lds
	s_mov_b32 m0, s60
	s_add_i32 s16, s16, 0x80080
	buffer_load_dwordx4 v136, s[40:43], s74 offen lds
	s_mov_b32 m0, s63
	s_addk_i32 s17, 0x80
	buffer_load_dwordx4 v134, s[40:43], s16 offen lds
	s_mov_b32 m0, s66
	s_nop 0
	buffer_load_dwordx4 v136, s[40:43], s16 offen lds
	s_mov_b32 m0, s61
	s_nop 0
	buffer_load_dwordx4 v0, s[4:7], s17 offen lds
	s_waitcnt vmcnt(7)
	s_waitcnt lgkmcnt(0)
	s_setprio 2
	s_barrier
	v_mfma_f32_16x16x32_bf16 v[62:65], v[130:133], v[170:173], v[62:65]
	v_mfma_f32_16x16x32_bf16 v[58:61], v[146:149], v[170:173], v[58:61]
	v_mfma_f32_16x16x32_bf16 v[42:45], v[146:149], v[178:181], v[42:45]
	v_mfma_f32_16x16x32_bf16 v[46:49], v[130:133], v[178:181], v[46:49]
	v_mfma_f32_16x16x32_bf16 v[30:33], v[130:133], v[186:189], v[30:33]
	v_mfma_f32_16x16x32_bf16 v[26:29], v[146:149], v[186:189], v[26:29]
	v_mfma_f32_16x16x32_bf16 v[10:13], v[146:149], v[200:203], v[10:13]
	v_mfma_f32_16x16x32_bf16 v[14:17], v[130:133], v[200:203], v[14:17]
	v_mfma_f32_16x16x32_bf16 v[62:65], v[142:145], v[174:177], v[62:65]
	v_mfma_f32_16x16x32_bf16 v[58:61], v[150:153], v[174:177], v[58:61]
	v_mfma_f32_16x16x32_bf16 v[42:45], v[150:153], v[182:185], v[42:45]
	v_mfma_f32_16x16x32_bf16 v[46:49], v[142:145], v[182:185], v[46:49]
	v_mfma_f32_16x16x32_bf16 v[30:33], v[142:145], v[190:193], v[30:33]
	v_mfma_f32_16x16x32_bf16 v[26:29], v[150:153], v[190:193], v[26:29]
	v_mfma_f32_16x16x32_bf16 v[10:13], v[150:153], v[206:209], v[10:13]
	v_mfma_f32_16x16x32_bf16 v[14:17], v[142:145], v[206:209], v[14:17]
	v_mfma_f32_16x16x32_bf16 v[54:57], v[154:157], v[170:173], v[54:57]
	v_mfma_f32_16x16x32_bf16 v[50:53], v[162:165], v[170:173], v[50:53]
	v_mfma_f32_16x16x32_bf16 v[34:37], v[162:165], v[178:181], v[34:37]
	v_mfma_f32_16x16x32_bf16 v[38:41], v[154:157], v[178:181], v[38:41]
	v_mfma_f32_16x16x32_bf16 v[22:25], v[154:157], v[186:189], v[22:25]
	v_mfma_f32_16x16x32_bf16 v[18:21], v[162:165], v[186:189], v[18:21]
	v_mfma_f32_16x16x32_bf16 v[2:5], v[162:165], v[200:203], v[2:5]
	v_mfma_f32_16x16x32_bf16 v[6:9], v[154:157], v[200:203], v[6:9]
	v_mfma_f32_16x16x32_bf16 v[54:57], v[158:161], v[174:177], v[54:57]
	v_mfma_f32_16x16x32_bf16 v[50:53], v[166:169], v[174:177], v[50:53]
	v_mfma_f32_16x16x32_bf16 v[34:37], v[166:169], v[182:185], v[34:37]
	v_mfma_f32_16x16x32_bf16 v[38:41], v[158:161], v[182:185], v[38:41]
	v_mfma_f32_16x16x32_bf16 v[22:25], v[158:161], v[190:193], v[22:25]
	v_mfma_f32_16x16x32_bf16 v[18:21], v[166:169], v[190:193], v[18:21]
	v_mfma_f32_16x16x32_bf16 v[2:5], v[166:169], v[206:209], v[2:5]
	v_mfma_f32_16x16x32_bf16 v[6:9], v[158:161], v[206:209], v[6:9]
	s_barrier
	s_setprio 1
	s_add_i32 s73, s73, 2
	s_add_u32 s19, s19, 0x100
	s_addc_u32 s21, s21, 0
	s_cmp_gt_u32 s73, 29
	s_mov_b64 s[16:17], s[38:39]
	s_cbranch_scc0 .Lyng_loop3
	s_setprio 0
.Lyng_after3:
	s_and_b64 vcc, exec, s[12:13]
	s_cbranch_vccz .LBB0_1517
	s_barrier

; #define PG8_STAGE(bufoff, gbase, voff) do { const int so_ = (int)(unsigned)((const char*)(gbase) - base_##voff); _Pragma("unroll") for (int _i = 0; _i < 2; ++_i) \
;         __builtin_amdgcn_raw_ptr_buffer_load_lds(rs_##voff, (PG8_LAS unsigned*)(lds + (bufoff) + ldsw + _i * 8192), 16, (int)(voff)[_i], so_, 0, 0); } while (0)
; #define PG8_LDA(dst, b, h) do { _Pragma("unroll") for (int m = 0; m < 4; ++m) _Pragma("unroll") for (int k = 0; k < 2; ++k) dst[m][k] = *(const PG8_LAS bf16x8*)(lds + PG8_SA(b, h) + aoff + m * 2048 + k * 1024); } while (0)
; #define PG8_WAIT_V(n) asm volatile("s_waitcnt vmcnt(" #n ")" ::: "memory")
; #define PG8_WAIT_L(n) asm volatile("s_waitcnt lgkmcnt(" #n ")" ::: "memory")
; template <class Epi, class Sched, bool ALIGN_EPI = false, bool SP2 = false>
; __device__ __forceinline__ void gemm_phase(PG8_LAS unsigned char* lds, const Gemm g, const Sched& S, const Epi& E, int tid_in) {
;     ...
;         for (int t = 0; t < nt; t += 2) {
;             const bool last = (t == nt - 2);
;             const char* a1 = cA + (size_t)(t + 1) * kstep;
;             const char* a2 = last ? nA : cA + (size_t)(t + 2) * kstep; const char* b2 = last ? nB : cB + (size_t)(t + 2) * kstep;
;             const char* a3 = a2 + kstep; const char* b3 = b2 + kstep;
;             if (last && has_next) S.a_ready(nxt);
;             if constexpr (SP2) {
;             PG8_LDB(B0, 0, 0); PG8_LDB(B1, 0, 1); PG8_SCHED; PG8_LDA(At, 0, 0); PG8_STAGE(PG8_SA(1, 1), a1 + hstepA, voffA);
;             PG8_WAIT_V(8); PG8_WAIT_L(0); PG8_BAR; PG8_MMA(0, 0, At, B0); PG8_MMA(0, 1, At, B1); PG8_BAR; PG8_SCHED;
;             PG8_LDA(At, 0, 1); PG8_STAGE(PG8_SB(0, 0), b2, voffB); PG8_STAGE(PG8_SB(0, 1), b2 + hstepB, voffB); PG8_STAGE(PG8_SA(0, 0), a2, voffA);
;             PG8_WAIT_V(8); PG8_WAIT_L(0); PG8_BAR; PG8_MMA(1, 0, At, B0); PG8_MMA(1, 1, At, B1); PG8_BAR; PG8_SCHED;
;             PG8_LDB(B0, 1, 0); PG8_LDB(B1, 1, 1); PG8_SCHED; PG8_LDA(At, 1, 0); PG8_STAGE(PG8_SA(0, 1), a2 + hstepA, voffA);
;             PG8_WAIT_V(8); PG8_WAIT_L(0); PG8_BAR; PG8_MMA(0, 0, At, B0); PG8_MMA(0, 1, At, B1); PG8_BAR; PG8_SCHED;
;             PG8_LDA(At, 1, 1); PG8_STAGE(PG8_SB(1, 0), b3, voffB); PG8_STAGE(PG8_SB(1, 1), b3 + hstepB, voffB); PG8_STAGE(PG8_SA(1, 0), a3, voffA);
;             PG8_WAIT_V(8); PG8_WAIT_L(0); PG8_BAR; PG8_MMA(1, 0, At, B0); PG8_MMA(1, 1, At, B1); PG8_BAR; PG8_SCHED;
.LBB0_1583:
	s_add_i32 s22, s14, s71
	s_add_i32 s38, s22, 0x160000
	s_mov_b32 s39, -2
	s_mov_b64 s[22:23], 0x100
	s_cmpk_lt_u32 s59, 0x100
	s_cbranch_scc0 .Lyng_loop4
.LBB0_1584:
	v_add_u32_e32 v133, 0x10000, v131
	ds_read_b128 v[134:137], v133
	ds_read_b128 v[138:141], v133 offset:1024
	ds_read_b128 v[142:145], v133 offset:2048
	ds_read_b128 v[146:149], v133 offset:3072
	v_add_u32_e32 v133, 0x14000, v131
	ds_read_b128 v[150:153], v133
	ds_read_b128 v[154:157], v133 offset:1024
	ds_read_b128 v[158:161], v133 offset:2048
	ds_read_b128 v[166:169], v133 offset:3072
	s_add_i32 s43, s38, s22
	s_add_i32 s42, s14, s22
	s_add_i32 s76, s12, s22
	s_addk_i32 s43, 0xff80
	s_sub_i32 s78, s43, 0x160000
	s_cmpk_eq_i32 s39, 0x54
	s_cselect_b32 s77, s16, s42
	s_mov_b32 m0, s68
	ds_read_b128 v[170:173], v132
	ds_read_b128 v[174:177], v132 offset:1024
	ds_read_b128 v[178:181], v132 offset:2048
	ds_read_b128 v[182:185], v132 offset:3072
	ds_read_b128 v[186:189], v132 offset:4096
	ds_read_b128 v[190:193], v132 offset:5120
	ds_read_b128 v[200:203], v132 offset:6144
	ds_read_b128 v[206:209], v132 offset:7168
	s_mov_b32 m0, s63
	s_nop 0
	buffer_load_dwordx4 v130, s[4:7], s78 offen lds
	s_mov_b32 m0, s68
	s_nop 0
	buffer_load_dwordx4 v0, s[4:7], s43 offen lds
	s_mov_b32 m0, s69
	s_nop 0
	buffer_load_dwordx4 v130, s[4:7], s43 offen lds
	s_waitcnt vmcnt(8)
	s_waitcnt lgkmcnt(0)
	s_setprio 1
	s_barrier
	v_mfma_f32_16x16x32_bf16 v[22:25], v[134:137], v[170:173], v[22:25]
	v_mfma_f32_16x16x32_bf16 v[14:17], v[142:145], v[170:173], v[14:17]
	v_mfma_f32_16x16x32_bf16 v[54:57], v[142:145], v[178:181], v[54:57]
	v_mfma_f32_16x16x32_bf16 v[74:77], v[134:137], v[178:181], v[74:77]
	v_mfma_f32_16x16x32_bf16 v[106:109], v[134:137], v[186:189], v[106:109]
	v_mfma_f32_16x16x32_bf16 v[102:105], v[142:145], v[186:189], v[102:105]
	v_mfma_f32_16x16x32_bf16 v[118:121], v[142:145], v[200:203], v[118:121]
	v_mfma_f32_16x16x32_bf16 v[122:125], v[134:137], v[200:203], v[122:125]
	v_mfma_f32_16x16x32_bf16 v[22:25], v[138:141], v[174:177], v[22:25]
	v_mfma_f32_16x16x32_bf16 v[14:17], v[146:149], v[174:177], v[14:17]
	v_mfma_f32_16x16x32_bf16 v[54:57], v[146:149], v[182:185], v[54:57]
	v_mfma_f32_16x16x32_bf16 v[74:77], v[138:141], v[182:185], v[74:77]
	v_mfma_f32_16x16x32_bf16 v[106:109], v[138:141], v[190:193], v[106:109]
	v_mfma_f32_16x16x32_bf16 v[102:105], v[146:149], v[190:193], v[102:105]
	v_mfma_f32_16x16x32_bf16 v[118:121], v[146:149], v[206:209], v[118:121]
	v_mfma_f32_16x16x32_bf16 v[122:125], v[138:141], v[206:209], v[122:125]
	v_mfma_f32_16x16x32_bf16 v[6:9], v[150:153], v[170:173], v[6:9]
	v_mfma_f32_16x16x32_bf16 v[18:21], v[158:161], v[170:173], v[18:21]
	v_mfma_f32_16x16x32_bf16 v[78:81], v[158:161], v[178:181], v[78:81]
	v_mfma_f32_16x16x32_bf16 v[50:53], v[150:153], v[178:181], v[50:53]
	v_mfma_f32_16x16x32_bf16 v[98:101], v[150:153], v[186:189], v[98:101]
	v_mfma_f32_16x16x32_bf16 v[110:113], v[158:161], v[186:189], v[110:113]
	v_mfma_f32_16x16x32_bf16 v[126:129], v[158:161], v[200:203], v[126:129]
	v_mfma_f32_16x16x32_bf16 v[114:117], v[150:153], v[200:203], v[114:117]
	v_mfma_f32_16x16x32_bf16 v[6:9], v[154:157], v[174:177], v[6:9]
	v_mfma_f32_16x16x32_bf16 v[18:21], v[166:169], v[174:177], v[18:21]
	v_mfma_f32_16x16x32_bf16 v[78:81], v[166:169], v[182:185], v[78:81]
	v_mfma_f32_16x16x32_bf16 v[50:53], v[154:157], v[182:185], v[50:53]
	v_mfma_f32_16x16x32_bf16 v[98:101], v[154:157], v[190:193], v[98:101]
	v_mfma_f32_16x16x32_bf16 v[110:113], v[166:169], v[190:193], v[110:113]
	v_mfma_f32_16x16x32_bf16 v[126:129], v[166:169], v[206:209], v[126:129]
	v_mfma_f32_16x16x32_bf16 v[114:117], v[154:157], v[206:209], v[114:117]
	s_barrier
	s_setprio 0
	s_cselect_b32 s76, s20, s76
	s_mov_b32 m0, s26
	s_mov_b32 s42, s6
	s_mov_b32 s43, s7
	s_sub_i32 s76, s76, s40
	ds_read_b128 v[170:173], v132 offset:16384
	ds_read_b128 v[174:177], v132 offset:17408
	ds_read_b128 v[178:181], v132 offset:18432
	ds_read_b128 v[182:185], v132 offset:19456
	ds_read_b128 v[186:189], v132 offset:20480
	ds_read_b128 v[190:193], v132 offset:21504
	ds_read_b128 v[200:203], v132 offset:22528
	ds_read_b128 v[206:209], v132 offset:23552
	buffer_load_dwordx4 v0, s[40:43], s76 offen lds
	s_mov_b32 m0, s44
	s_add_i32 s78, s76, 0x160000
	buffer_load_dwordx4 v130, s[40:43], s76 offen lds
	s_mov_b32 m0, s45
	s_sub_i32 s77, s77, s4
	buffer_load_dwordx4 v0, s[40:43], s78 offen lds
	s_mov_b32 m0, s46
	s_nop 0
	buffer_load_dwordx4 v130, s[40:43], s78 offen lds
	s_mov_b32 m0, s19
	s_nop 0
	buffer_load_dwordx4 v0, s[4:7], s77 offen lds
	s_waitcnt vmcnt(7)
	s_waitcnt lgkmcnt(0)
	s_setprio 1
	s_barrier
; #define PG8_STAGE(bufoff, gbase, voff) do { const int so_ = (int)(unsigned)((const char*)(gbase) - base_##voff); _Pragma("unroll") for (int _i = 0; _i < 2; ++_i) \
;         __builtin_amdgcn_raw_ptr_buffer_load_lds(rs_##voff, (PG8_LAS unsigned*)(lds + (bufoff) + ldsw + _i * 8192), 16, (int)(voff)[_i], so_, 0, 0); } while (0)
; #define PG8_LDA(dst, b, h) do { _Pragma("unroll") for (int m = 0; m < 4; ++m) _Pragma("unroll") for (int k = 0; k < 2; ++k) dst[m][k] = *(const PG8_LAS bf16x8*)(lds + PG8_SA(b, h) + aoff + m * 2048 + k * 1024); } while (0)
; #define PG8_LDB(dst, b, h) do { _Pragma("unroll") for (int n = 0; n < 2; ++n) _Pragma("unroll") for (int k = 0; k < 2; ++k) dst[n][k] = *(const PG8_LAS bf16x8*)(lds + PG8_SB(b, h) + boff + n * 2048 + k * 1024); } while (0)
; #define PG8_MMA(ai, bj, At, Bt) do { __builtin_amdgcn_s_setprio(1); _Pragma("unroll") for (int m = 0; m < 4; ++m) _Pragma("unroll") for (int n = 0; n < 2; ++n) _Pragma("unroll") for (int k = 0; k < 2; ++k) \
;         acc[ai][bj][m][n] = __builtin_amdgcn_mfma_f32_16x16x32_bf16(Bt[n][k], At[m][k], acc[ai][bj][m][n], 0, 0, 0); __builtin_amdgcn_s_setprio(0); } while (0)
; template <class Epi, class Sched, bool ALIGN_EPI = false, bool SP2 = false>
; __device__ __forceinline__ void gemm_phase(PG8_LAS unsigned char* lds, const Gemm g, const Sched& S, const Epi& E, int tid_in) {
;     ...
;             PG8_LDB(B0, 0, 0); PG8_LDB(B1, 0, 1); PG8_SCHED; PG8_LDA(At, 0, 0); PG8_STAGE(PG8_SA(1, 1), a1 + hstepA, voffA);
;             PG8_WAIT_V(8); PG8_WAIT_L(0); PG8_BAR; PG8_MMA(0, 0, At, B0); PG8_MMA(0, 1, At, B1); PG8_BAR; PG8_SCHED;
;             PG8_LDA(At, 0, 1); PG8_STAGE(PG8_SB(0, 0), b2, voffB); PG8_STAGE(PG8_SB(0, 1), b2 + hstepB, voffB); PG8_STAGE(PG8_SA(0, 0), a2, voffA);
;             PG8_WAIT_V(8); PG8_WAIT_L(0); PG8_BAR; PG8_MMA(1, 0, At, B0); PG8_MMA(1, 1, At, B1); PG8_BAR; PG8_SCHED;
;             PG8_LDB(B0, 1, 0); PG8_LDB(B1, 1, 1); PG8_SCHED; PG8_LDA(At, 1, 0); PG8_STAGE(PG8_SA(0, 1), a2 + hstepA, voffA);
;             PG8_WAIT_V(8); PG8_WAIT_L(0); PG8_BAR; PG8_MMA(0, 0, At, B0); PG8_MMA(0, 1, At, B1); PG8_BAR; PG8_SCHED;
;             PG8_LDA(At, 1, 1); PG8_STAGE(PG8_SB(1, 0), b3, voffB); PG8_STAGE(PG8_SB(1, 1), b3 + hstepB, voffB); PG8_STAGE(PG8_SA(1, 0), a3, voffA);
;             PG8_WAIT_V(8); PG8_WAIT_L(0); PG8_BAR; PG8_MMA(1, 0, At, B0); PG8_MMA(1, 1, At, B1); PG8_BAR; PG8_SCHED;
	v_mfma_f32_16x16x32_bf16 v[62:65], v[134:137], v[170:173], v[62:65]
	v_mfma_f32_16x16x32_bf16 v[46:49], v[142:145], v[170:173], v[46:49]
	v_mfma_f32_16x16x32_bf16 v[70:73], v[142:145], v[178:181], v[70:73]
	v_mfma_f32_16x16x32_bf16 v[82:85], v[134:137], v[178:181], v[82:85]
	v_mfma_f32_16x16x32_bf16 v[94:97], v[134:137], v[186:189], v[94:97]
	v_mfma_f32_16x16x32_bf16 v[90:93], v[142:145], v[186:189], v[90:93]
	v_mfma_f32_16x16x32_bf16 v[26:29], v[142:145], v[200:203], v[26:29]
	v_mfma_f32_16x16x32_bf16 v[38:41], v[134:137], v[200:203], v[38:41]
	v_mfma_f32_16x16x32_bf16 v[62:65], v[138:141], v[174:177], v[62:65]
	v_mfma_f32_16x16x32_bf16 v[46:49], v[146:149], v[174:177], v[46:49]
	v_mfma_f32_16x16x32_bf16 v[70:73], v[146:149], v[182:185], v[70:73]
	v_mfma_f32_16x16x32_bf16 v[82:85], v[138:141], v[182:185], v[82:85]
	v_mfma_f32_16x16x32_bf16 v[94:97], v[138:141], v[190:193], v[94:97]
	v_mfma_f32_16x16x32_bf16 v[90:93], v[146:149], v[190:193], v[90:93]
	v_mfma_f32_16x16x32_bf16 v[26:29], v[146:149], v[206:209], v[26:29]
	v_mfma_f32_16x16x32_bf16 v[38:41], v[138:141], v[206:209], v[38:41]
	v_mfma_f32_16x16x32_bf16 v[42:45], v[150:153], v[170:173], v[42:45]
	v_mfma_f32_16x16x32_bf16 v[30:33], v[158:161], v[170:173], v[30:33]
	v_mfma_f32_16x16x32_bf16 v[86:89], v[158:161], v[178:181], v[86:89]
	v_mfma_f32_16x16x32_bf16 v[66:69], v[150:153], v[178:181], v[66:69]
	v_mfma_f32_16x16x32_bf16 v[58:61], v[150:153], v[186:189], v[58:61]
	v_mfma_f32_16x16x32_bf16 v[34:37], v[158:161], v[186:189], v[34:37]
	v_mfma_f32_16x16x32_bf16 v[2:5], v[158:161], v[200:203], v[2:5]
	v_mfma_f32_16x16x32_bf16 v[10:13], v[150:153], v[200:203], v[10:13]
	v_mfma_f32_16x16x32_bf16 v[42:45], v[154:157], v[174:177], v[42:45]
	v_mfma_f32_16x16x32_bf16 v[30:33], v[166:169], v[174:177], v[30:33]
	v_mfma_f32_16x16x32_bf16 v[86:89], v[166:169], v[182:185], v[86:89]
	v_mfma_f32_16x16x32_bf16 v[66:69], v[154:157], v[182:185], v[66:69]
	v_mfma_f32_16x16x32_bf16 v[58:61], v[154:157], v[190:193], v[58:61]
	v_mfma_f32_16x16x32_bf16 v[34:37], v[166:169], v[190:193], v[34:37]
	v_mfma_f32_16x16x32_bf16 v[2:5], v[166:169], v[206:209], v[2:5]
	v_mfma_f32_16x16x32_bf16 v[10:13], v[154:157], v[206:209], v[10:13]
	s_barrier
	s_setprio 0
	v_add_u32_e32 v133, 0x18000, v131
	ds_read_b128 v[134:137], v133
	ds_read_b128 v[138:141], v133 offset:1024
	ds_read_b128 v[142:145], v133 offset:2048
	ds_read_b128 v[146:149], v133 offset:3072
	v_add_u32_e32 v133, 0x1c000, v131
	ds_read_b128 v[150:153], v133
	ds_read_b128 v[154:157], v133 offset:1024
	ds_read_b128 v[158:161], v133 offset:2048
	ds_read_b128 v[166:169], v133 offset:3072
	s_add_i32 s78, s77, 0x160000
	s_mov_b32 m0, s48
	ds_read_b128 v[170:173], v132 offset:32768
	ds_read_b128 v[174:177], v132 offset:33792
	ds_read_b128 v[178:181], v132 offset:34816
	ds_read_b128 v[182:185], v132 offset:35840
	ds_read_b128 v[186:189], v132 offset:36864
	ds_read_b128 v[190:193], v132 offset:37888
	ds_read_b128 v[200:203], v132 offset:38912
	ds_read_b128 v[206:209], v132 offset:39936
	s_mov_b32 m0, s47
	s_nop 0
	buffer_load_dwordx4 v130, s[4:7], s77 offen lds
	s_mov_b32 m0, s48
	s_nop 0
	buffer_load_dwordx4 v0, s[4:7], s78 offen lds
	s_mov_b32 m0, s49
	s_nop 0
	buffer_load_dwordx4 v130, s[4:7], s78 offen lds
	s_waitcnt vmcnt(8)
	s_waitcnt lgkmcnt(0)
	s_setprio 1
	s_barrier
	v_mfma_f32_16x16x32_bf16 v[22:25], v[134:137], v[170:173], v[22:25]
	v_mfma_f32_16x16x32_bf16 v[14:17], v[142:145], v[170:173], v[14:17]
	v_mfma_f32_16x16x32_bf16 v[54:57], v[142:145], v[178:181], v[54:57]
	v_mfma_f32_16x16x32_bf16 v[74:77], v[134:137], v[178:181], v[74:77]
	v_mfma_f32_16x16x32_bf16 v[106:109], v[134:137], v[186:189], v[106:109]
	v_mfma_f32_16x16x32_bf16 v[102:105], v[142:145], v[186:189], v[102:105]
	v_mfma_f32_16x16x32_bf16 v[118:121], v[142:145], v[200:203], v[118:121]
	v_mfma_f32_16x16x32_bf16 v[122:125], v[134:137], v[200:203], v[122:125]
	v_mfma_f32_16x16x32_bf16 v[22:25], v[138:141], v[174:177], v[22:25]
	v_mfma_f32_16x16x32_bf16 v[14:17], v[146:149], v[174:177], v[14:17]
	v_mfma_f32_16x16x32_bf16 v[54:57], v[146:149], v[182:185], v[54:57]
	v_mfma_f32_16x16x32_bf16 v[74:77], v[138:141], v[182:185], v[74:77]
	v_mfma_f32_16x16x32_bf16 v[106:109], v[138:141], v[190:193], v[106:109]
	v_mfma_f32_16x16x32_bf16 v[102:105], v[146:149], v[190:193], v[102:105]
	v_mfma_f32_16x16x32_bf16 v[118:121], v[146:149], v[206:209], v[118:121]
	v_mfma_f32_16x16x32_bf16 v[122:125], v[138:141], v[206:209], v[122:125]
	v_mfma_f32_16x16x32_bf16 v[6:9], v[150:153], v[170:173], v[6:9]
	v_mfma_f32_16x16x32_bf16 v[18:21], v[158:161], v[170:173], v[18:21]
	v_mfma_f32_16x16x32_bf16 v[78:81], v[158:161], v[178:181], v[78:81]
	v_mfma_f32_16x16x32_bf16 v[50:53], v[150:153], v[178:181], v[50:53]
	v_mfma_f32_16x16x32_bf16 v[98:101], v[150:153], v[186:189], v[98:101]
	v_mfma_f32_16x16x32_bf16 v[110:113], v[158:161], v[186:189], v[110:113]
	v_mfma_f32_16x16x32_bf16 v[126:129], v[158:161], v[200:203], v[126:129]
	v_mfma_f32_16x16x32_bf16 v[114:117], v[150:153], v[200:203], v[114:117]
	v_mfma_f32_16x16x32_bf16 v[6:9], v[154:157], v[174:177], v[6:9]
	v_mfma_f32_16x16x32_bf16 v[18:21], v[166:169], v[174:177], v[18:21]
	v_mfma_f32_16x16x32_bf16 v[78:81], v[166:169], v[182:185], v[78:81]
	v_mfma_f32_16x16x32_bf16 v[50:53], v[154:157], v[182:185], v[50:53]
	v_mfma_f32_16x16x32_bf16 v[98:101], v[154:157], v[190:193], v[98:101]
	v_mfma_f32_16x16x32_bf16 v[110:113], v[166:169], v[190:193], v[110:113]
	v_mfma_f32_16x16x32_bf16 v[126:129], v[166:169], v[206:209], v[126:129]
	v_mfma_f32_16x16x32_bf16 v[114:117], v[154:157], v[206:209], v[114:117]
	s_barrier
; #define PG8_STAGE(bufoff, gbase, voff) do { const int so_ = (int)(unsigned)((const char*)(gbase) - base_##voff); _Pragma("unroll") for (int _i = 0; _i < 2; ++_i) \
;         __builtin_amdgcn_raw_ptr_buffer_load_lds(rs_##voff, (PG8_LAS unsigned*)(lds + (bufoff) + ldsw + _i * 8192), 16, (int)(voff)[_i], so_, 0, 0); } while (0)
; #define PG8_LDA(dst, b, h) do { _Pragma("unroll") for (int m = 0; m < 4; ++m) _Pragma("unroll") for (int k = 0; k < 2; ++k) dst[m][k] = *(const PG8_LAS bf16x8*)(lds + PG8_SA(b, h) + aoff + m * 2048 + k * 1024); } while (0)
; #define PG8_LDB(dst, b, h) do { _Pragma("unroll") for (int n = 0; n < 2; ++n) _Pragma("unroll") for (int k = 0; k < 2; ++k) dst[n][k] = *(const PG8_LAS bf16x8*)(lds + PG8_SB(b, h) + boff + n * 2048 + k * 1024); } while (0)
; #define PG8_MMA(ai, bj, At, Bt) do { __builtin_amdgcn_s_setprio(1); _Pragma("unroll") for (int m = 0; m < 4; ++m) _Pragma("unroll") for (int n = 0; n < 2; ++n) _Pragma("unroll") for (int k = 0; k < 2; ++k) \
;         acc[ai][bj][m][n] = __builtin_amdgcn_mfma_f32_16x16x32_bf16(Bt[n][k], At[m][k], acc[ai][bj][m][n], 0, 0, 0); __builtin_amdgcn_s_setprio(0); } while (0)
; template <class Epi, class Sched, bool ALIGN_EPI = false, bool SP2 = false>
; __device__ __forceinline__ void gemm_phase(PG8_LAS unsigned char* lds, const Gemm g, const Sched& S, const Epi& E, int tid_in) {
;     ...
;             PG8_LDB(B0, 0, 0); PG8_LDB(B1, 0, 1); PG8_SCHED; PG8_LDA(At, 0, 0); PG8_STAGE(PG8_SA(1, 1), a1 + hstepA, voffA);
;             PG8_WAIT_V(8); PG8_WAIT_L(0); PG8_BAR; PG8_MMA(0, 0, At, B0); PG8_MMA(0, 1, At, B1); PG8_BAR; PG8_SCHED;
;             PG8_LDA(At, 0, 1); PG8_STAGE(PG8_SB(0, 0), b2, voffB); PG8_STAGE(PG8_SB(0, 1), b2 + hstepB, voffB); PG8_STAGE(PG8_SA(0, 0), a2, voffA);
;             PG8_WAIT_V(8); PG8_WAIT_L(0); PG8_BAR; PG8_MMA(1, 0, At, B0); PG8_MMA(1, 1, At, B1); PG8_BAR; PG8_SCHED;
;             PG8_LDB(B0, 1, 0); PG8_LDB(B1, 1, 1); PG8_SCHED; PG8_LDA(At, 1, 0); PG8_STAGE(PG8_SA(0, 1), a2 + hstepA, voffA);
;             PG8_WAIT_V(8); PG8_WAIT_L(0); PG8_BAR; PG8_MMA(0, 0, At, B0); PG8_MMA(0, 1, At, B1); PG8_BAR; PG8_SCHED;
;             PG8_LDA(At, 1, 1); PG8_STAGE(PG8_SB(1, 0), b3, voffB); PG8_STAGE(PG8_SB(1, 1), b3 + hstepB, voffB); PG8_STAGE(PG8_SA(1, 0), a3, voffA);
;             PG8_WAIT_V(8); PG8_WAIT_L(0); PG8_BAR; PG8_MMA(1, 0, At, B0); PG8_MMA(1, 1, At, B1); PG8_BAR; PG8_SCHED;
	s_setprio 0
	s_mov_b32 m0, s60
	s_add_i32 s78, s76, 0x80
	ds_read_b128 v[170:173], v132 offset:49152
	ds_read_b128 v[174:177], v132 offset:50176
	ds_read_b128 v[178:181], v132 offset:51200
	ds_read_b128 v[182:185], v132 offset:52224
	ds_read_b128 v[186:189], v132 offset:53248
	ds_read_b128 v[190:193], v132 offset:54272
	ds_read_b128 v[200:203], v132 offset:55296
	ds_read_b128 v[206:209], v132 offset:56320
	buffer_load_dwordx4 v0, s[40:43], s78 offen lds
	s_mov_b32 m0, s61
	s_add_i32 s76, s76, 0x160080
	buffer_load_dwordx4 v130, s[40:43], s78 offen lds
	s_mov_b32 m0, s66
	s_addk_i32 s77, 0x80
	buffer_load_dwordx4 v0, s[40:43], s76 offen lds
	s_mov_b32 m0, s67
	s_nop 0
	buffer_load_dwordx4 v130, s[40:43], s76 offen lds
	s_mov_b32 m0, s62
	s_nop 0
	buffer_load_dwordx4 v0, s[4:7], s77 offen lds
	s_waitcnt vmcnt(7)
	s_waitcnt lgkmcnt(0)
	s_setprio 1
	s_barrier
	v_mfma_f32_16x16x32_bf16 v[62:65], v[134:137], v[170:173], v[62:65]
	v_mfma_f32_16x16x32_bf16 v[46:49], v[142:145], v[170:173], v[46:49]
	v_mfma_f32_16x16x32_bf16 v[70:73], v[142:145], v[178:181], v[70:73]
	v_mfma_f32_16x16x32_bf16 v[82:85], v[134:137], v[178:181], v[82:85]
	v_mfma_f32_16x16x32_bf16 v[94:97], v[134:137], v[186:189], v[94:97]
	v_mfma_f32_16x16x32_bf16 v[90:93], v[142:145], v[186:189], v[90:93]
	v_mfma_f32_16x16x32_bf16 v[26:29], v[142:145], v[200:203], v[26:29]
	v_mfma_f32_16x16x32_bf16 v[38:41], v[134:137], v[200:203], v[38:41]
	v_mfma_f32_16x16x32_bf16 v[62:65], v[138:141], v[174:177], v[62:65]
	v_mfma_f32_16x16x32_bf16 v[46:49], v[146:149], v[174:177], v[46:49]
	v_mfma_f32_16x16x32_bf16 v[70:73], v[146:149], v[182:185], v[70:73]
	v_mfma_f32_16x16x32_bf16 v[82:85], v[138:141], v[182:185], v[82:85]
	v_mfma_f32_16x16x32_bf16 v[94:97], v[138:141], v[190:193], v[94:97]
	v_mfma_f32_16x16x32_bf16 v[90:93], v[146:149], v[190:193], v[90:93]
	v_mfma_f32_16x16x32_bf16 v[26:29], v[146:149], v[206:209], v[26:29]
	v_mfma_f32_16x16x32_bf16 v[38:41], v[138:141], v[206:209], v[38:41]
	v_mfma_f32_16x16x32_bf16 v[42:45], v[150:153], v[170:173], v[42:45]
	v_mfma_f32_16x16x32_bf16 v[30:33], v[158:161], v[170:173], v[30:33]
	v_mfma_f32_16x16x32_bf16 v[86:89], v[158:161], v[178:181], v[86:89]
	v_mfma_f32_16x16x32_bf16 v[66:69], v[150:153], v[178:181], v[66:69]
	v_mfma_f32_16x16x32_bf16 v[58:61], v[150:153], v[186:189], v[58:61]
	v_mfma_f32_16x16x32_bf16 v[34:37], v[158:161], v[186:189], v[34:37]
	v_mfma_f32_16x16x32_bf16 v[2:5], v[158:161], v[200:203], v[2:5]
	v_mfma_f32_16x16x32_bf16 v[10:13], v[150:153], v[200:203], v[10:13]
	v_mfma_f32_16x16x32_bf16 v[42:45], v[154:157], v[174:177], v[42:45]
	v_mfma_f32_16x16x32_bf16 v[30:33], v[166:169], v[174:177], v[30:33]
	v_mfma_f32_16x16x32_bf16 v[86:89], v[166:169], v[182:185], v[86:89]
	v_mfma_f32_16x16x32_bf16 v[66:69], v[154:157], v[182:185], v[66:69]
	v_mfma_f32_16x16x32_bf16 v[58:61], v[154:157], v[190:193], v[58:61]
	v_mfma_f32_16x16x32_bf16 v[34:37], v[166:169], v[190:193], v[34:37]
	v_mfma_f32_16x16x32_bf16 v[2:5], v[166:169], v[206:209], v[2:5]
	v_mfma_f32_16x16x32_bf16 v[10:13], v[154:157], v[206:209], v[10:13]
	s_barrier
	s_setprio 0
	s_add_i32 s39, s39, 2
	s_add_u32 s22, s22, 0x100
	s_addc_u32 s23, s23, 0
	s_cmpk_gt_u32 s39, 0x55
	s_cbranch_scc0 .LBB0_1584
	s_branch .Lyng_after4
.Lyng_loop4:
	v_add_u32_e32 v133, 0x10000, v131
	ds_read_b128 v[134:137], v133
	ds_read_b128 v[138:141], v133 offset:1024
	ds_read_b128 v[142:145], v133 offset:2048
	ds_read_b128 v[146:149], v133 offset:3072
	v_add_u32_e32 v133, 0x14000, v131
	ds_read_b128 v[150:153], v133
	ds_read_b128 v[154:157], v133 offset:1024
	ds_read_b128 v[158:161], v133 offset:2048
	ds_read_b128 v[166:169], v133 offset:3072
	s_add_i32 s43, s38, s22
	s_add_i32 s42, s14, s22
	s_add_i32 s76, s12, s22
	s_addk_i32 s43, 0xff80
	s_sub_i32 s78, s43, 0x160000
	s_cmpk_eq_i32 s39, 0x54
	s_cselect_b32 s77, s16, s42
	s_mov_b32 m0, s68
	ds_read_b128 v[170:173], v132
	ds_read_b128 v[174:177], v132 offset:1024
	ds_read_b128 v[178:181], v132 offset:2048
	ds_read_b128 v[182:185], v132 offset:3072
	ds_read_b128 v[186:189], v132 offset:4096
	ds_read_b128 v[190:193], v132 offset:5120
	ds_read_b128 v[200:203], v132 offset:6144
	ds_read_b128 v[206:209], v132 offset:7168
	s_mov_b32 m0, s63
	s_nop 0
	buffer_load_dwordx4 v130, s[4:7], s78 offen lds
	s_mov_b32 m0, s68
	s_nop 0
	buffer_load_dwordx4 v0, s[4:7], s43 offen lds
	s_mov_b32 m0, s69
	s_nop 0
	buffer_load_dwordx4 v130, s[4:7], s43 offen lds
	s_waitcnt vmcnt(8)
	s_waitcnt lgkmcnt(0)
	s_setprio 2
	s_barrier
	v_mfma_f32_16x16x32_bf16 v[22:25], v[134:137], v[170:173], v[22:25]
	v_mfma_f32_16x16x32_bf16 v[14:17], v[142:145], v[170:173], v[14:17]
	v_mfma_f32_16x16x32_bf16 v[54:57], v[142:145], v[178:181], v[54:57]
	v_mfma_f32_16x16x32_bf16 v[74:77], v[134:137], v[178:181], v[74:77]
	v_mfma_f32_16x16x32_bf16 v[106:109], v[134:137], v[186:189], v[106:109]
	v_mfma_f32_16x16x32_bf16 v[102:105], v[142:145], v[186:189], v[102:105]
	v_mfma_f32_16x16x32_bf16 v[118:121], v[142:145], v[200:203], v[118:121]
	v_mfma_f32_16x16x32_bf16 v[122:125], v[134:137], v[200:203], v[122:125]
	v_mfma_f32_16x16x32_bf16 v[22:25], v[138:141], v[174:177], v[22:25]
	v_mfma_f32_16x16x32_bf16 v[14:17], v[146:149], v[174:177], v[14:17]
	v_mfma_f32_16x16x32_bf16 v[54:57], v[146:149], v[182:185], v[54:57]
	v_mfma_f32_16x16x32_bf16 v[74:77], v[138:141], v[182:185], v[74:77]
	v_mfma_f32_16x16x32_bf16 v[106:109], v[138:141], v[190:193], v[106:109]
	v_mfma_f32_16x16x32_bf16 v[102:105], v[146:149], v[190:193], v[102:105]
	v_mfma_f32_16x16x32_bf16 v[118:121], v[146:149], v[206:209], v[118:121]
	v_mfma_f32_16x16x32_bf16 v[122:125], v[138:141], v[206:209], v[122:125]
	v_mfma_f32_16x16x32_bf16 v[6:9], v[150:153], v[170:173], v[6:9]
	v_mfma_f32_16x16x32_bf16 v[18:21], v[158:161], v[170:173], v[18:21]
	v_mfma_f32_16x16x32_bf16 v[78:81], v[158:161], v[178:181], v[78:81]
	v_mfma_f32_16x16x32_bf16 v[50:53], v[150:153], v[178:181], v[50:53]
	v_mfma_f32_16x16x32_bf16 v[98:101], v[150:153], v[186:189], v[98:101]
	v_mfma_f32_16x16x32_bf16 v[110:113], v[158:161], v[186:189], v[110:113]
	v_mfma_f32_16x16x32_bf16 v[126:129], v[158:161], v[200:203], v[126:129]
	v_mfma_f32_16x16x32_bf16 v[114:117], v[150:153], v[200:203], v[114:117]
	v_mfma_f32_16x16x32_bf16 v[6:9], v[154:157], v[174:177], v[6:9]
	v_mfma_f32_16x16x32_bf16 v[18:21], v[166:169], v[174:177], v[18:21]
	v_mfma_f32_16x16x32_bf16 v[78:81], v[166:169], v[182:185], v[78:81]
	v_mfma_f32_16x16x32_bf16 v[50:53], v[154:157], v[182:185], v[50:53]
	v_mfma_f32_16x16x32_bf16 v[98:101], v[154:157], v[190:193], v[98:101]
	v_mfma_f32_16x16x32_bf16 v[110:113], v[166:169], v[190:193], v[110:113]
	v_mfma_f32_16x16x32_bf16 v[126:129], v[166:169], v[206:209], v[126:129]
	v_mfma_f32_16x16x32_bf16 v[114:117], v[154:157], v[206:209], v[114:117]
	s_barrier
; #define PG8_STAGE(bufoff, gbase, voff) do { const int so_ = (int)(unsigned)((const char*)(gbase) - base_##voff); _Pragma("unroll") for (int _i = 0; _i < 2; ++_i) \
;         __builtin_amdgcn_raw_ptr_buffer_load_lds(rs_##voff, (PG8_LAS unsigned*)(lds + (bufoff) + ldsw + _i * 8192), 16, (int)(voff)[_i], so_, 0, 0); } while (0)
; #define PG8_LDA(dst, b, h) do { _Pragma("unroll") for (int m = 0; m < 4; ++m) _Pragma("unroll") for (int k = 0; k < 2; ++k) dst[m][k] = *(const PG8_LAS bf16x8*)(lds + PG8_SA(b, h) + aoff + m * 2048 + k * 1024); } while (0)
; #define PG8_LDB(dst, b, h) do { _Pragma("unroll") for (int n = 0; n < 2; ++n) _Pragma("unroll") for (int k = 0; k < 2; ++k) dst[n][k] = *(const PG8_LAS bf16x8*)(lds + PG8_SB(b, h) + boff + n * 2048 + k * 1024); } while (0)
; #define PG8_MMA(ai, bj, At, Bt) do { __builtin_amdgcn_s_setprio(1); _Pragma("unroll") for (int m = 0; m < 4; ++m) _Pragma("unroll") for (int n = 0; n < 2; ++n) _Pragma("unroll") for (int k = 0; k < 2; ++k) \
;         acc[ai][bj][m][n] = __builtin_amdgcn_mfma_f32_16x16x32_bf16(Bt[n][k], At[m][k], acc[ai][bj][m][n], 0, 0, 0); __builtin_amdgcn_s_setprio(0); } while (0)
; template <class Epi, class Sched, bool ALIGN_EPI = false, bool SP2 = false>
; __device__ __forceinline__ void gemm_phase(PG8_LAS unsigned char* lds, const Gemm g, const Sched& S, const Epi& E, int tid_in) {
;     ...
;             PG8_LDB(B0, 0, 0); PG8_LDB(B1, 0, 1); PG8_SCHED; PG8_LDA(At, 0, 0); PG8_STAGE(PG8_SA(1, 1), a1 + hstepA, voffA);
;             PG8_WAIT_V(8); PG8_WAIT_L(0); PG8_BAR; PG8_MMA(0, 0, At, B0); PG8_MMA(0, 1, At, B1); PG8_BAR; PG8_SCHED;
;             PG8_LDA(At, 0, 1); PG8_STAGE(PG8_SB(0, 0), b2, voffB); PG8_STAGE(PG8_SB(0, 1), b2 + hstepB, voffB); PG8_STAGE(PG8_SA(0, 0), a2, voffA);
;             PG8_WAIT_V(8); PG8_WAIT_L(0); PG8_BAR; PG8_MMA(1, 0, At, B0); PG8_MMA(1, 1, At, B1); PG8_BAR; PG8_SCHED;
;             PG8_LDB(B0, 1, 0); PG8_LDB(B1, 1, 1); PG8_SCHED; PG8_LDA(At, 1, 0); PG8_STAGE(PG8_SA(0, 1), a2 + hstepA, voffA);
;             PG8_WAIT_V(8); PG8_WAIT_L(0); PG8_BAR; PG8_MMA(0, 0, At, B0); PG8_MMA(0, 1, At, B1); PG8_BAR; PG8_SCHED;
;             PG8_LDA(At, 1, 1); PG8_STAGE(PG8_SB(1, 0), b3, voffB); PG8_STAGE(PG8_SB(1, 1), b3 + hstepB, voffB); PG8_STAGE(PG8_SA(1, 0), a3, voffA);
;             PG8_WAIT_V(8); PG8_WAIT_L(0); PG8_BAR; PG8_MMA(1, 0, At, B0); PG8_MMA(1, 1, At, B1); PG8_BAR; PG8_SCHED;
	s_setprio 1
	s_cselect_b32 s76, s20, s76
	s_mov_b32 m0, s26
	s_mov_b32 s42, s6
	s_mov_b32 s43, s7
	s_sub_i32 s76, s76, s40
	ds_read_b128 v[170:173], v132 offset:16384
	ds_read_b128 v[174:177], v132 offset:17408
	ds_read_b128 v[178:181], v132 offset:18432
	ds_read_b128 v[182:185], v132 offset:19456
	ds_read_b128 v[186:189], v132 offset:20480
	ds_read_b128 v[190:193], v132 offset:21504
	ds_read_b128 v[200:203], v132 offset:22528
	ds_read_b128 v[206:209], v132 offset:23552
	buffer_load_dwordx4 v0, s[40:43], s76 offen lds
	s_mov_b32 m0, s44
	s_add_i32 s78, s76, 0x160000
	buffer_load_dwordx4 v130, s[40:43], s76 offen lds
	s_mov_b32 m0, s45
	s_sub_i32 s77, s77, s4
	buffer_load_dwordx4 v0, s[40:43], s78 offen lds
	s_mov_b32 m0, s46
	s_nop 0
	buffer_load_dwordx4 v130, s[40:43], s78 offen lds
	s_mov_b32 m0, s19
	s_nop 0
	buffer_load_dwordx4 v0, s[4:7], s77 offen lds
	s_waitcnt vmcnt(7)
	s_waitcnt lgkmcnt(0)
	s_setprio 2
	s_barrier
	v_mfma_f32_16x16x32_bf16 v[62:65], v[134:137], v[170:173], v[62:65]
	v_mfma_f32_16x16x32_bf16 v[46:49], v[142:145], v[170:173], v[46:49]
	v_mfma_f32_16x16x32_bf16 v[70:73], v[142:145], v[178:181], v[70:73]
	v_mfma_f32_16x16x32_bf16 v[82:85], v[134:137], v[178:181], v[82:85]
	v_mfma_f32_16x16x32_bf16 v[94:97], v[134:137], v[186:189], v[94:97]
	v_mfma_f32_16x16x32_bf16 v[90:93], v[142:145], v[186:189], v[90:93]
	v_mfma_f32_16x16x32_bf16 v[26:29], v[142:145], v[200:203], v[26:29]
	v_mfma_f32_16x16x32_bf16 v[38:41], v[134:137], v[200:203], v[38:41]
	v_mfma_f32_16x16x32_bf16 v[62:65], v[138:141], v[174:177], v[62:65]
	v_mfma_f32_16x16x32_bf16 v[46:49], v[146:149], v[174:177], v[46:49]
	v_mfma_f32_16x16x32_bf16 v[70:73], v[146:149], v[182:185], v[70:73]
	v_mfma_f32_16x16x32_bf16 v[82:85], v[138:141], v[182:185], v[82:85]
	v_mfma_f32_16x16x32_bf16 v[94:97], v[138:141], v[190:193], v[94:97]
	v_mfma_f32_16x16x32_bf16 v[90:93], v[146:149], v[190:193], v[90:93]
	v_mfma_f32_16x16x32_bf16 v[26:29], v[146:149], v[206:209], v[26:29]
	v_mfma_f32_16x16x32_bf16 v[38:41], v[138:141], v[206:209], v[38:41]
	v_mfma_f32_16x16x32_bf16 v[42:45], v[150:153], v[170:173], v[42:45]
	v_mfma_f32_16x16x32_bf16 v[30:33], v[158:161], v[170:173], v[30:33]
	v_mfma_f32_16x16x32_bf16 v[86:89], v[158:161], v[178:181], v[86:89]
	v_mfma_f32_16x16x32_bf16 v[66:69], v[150:153], v[178:181], v[66:69]
	v_mfma_f32_16x16x32_bf16 v[58:61], v[150:153], v[186:189], v[58:61]
	v_mfma_f32_16x16x32_bf16 v[34:37], v[158:161], v[186:189], v[34:37]
	v_mfma_f32_16x16x32_bf16 v[2:5], v[158:161], v[200:203], v[2:5]
	v_mfma_f32_16x16x32_bf16 v[10:13], v[150:153], v[200:203], v[10:13]
	v_mfma_f32_16x16x32_bf16 v[42:45], v[154:157], v[174:177], v[42:45]
	v_mfma_f32_16x16x32_bf16 v[30:33], v[166:169], v[174:177], v[30:33]
	v_mfma_f32_16x16x32_bf16 v[86:89], v[166:169], v[182:185], v[86:89]
	v_mfma_f32_16x16x32_bf16 v[66:69], v[154:157], v[182:185], v[66:69]
	v_mfma_f32_16x16x32_bf16 v[58:61], v[154:157], v[190:193], v[58:61]
	v_mfma_f32_16x16x32_bf16 v[34:37], v[166:169], v[190:193], v[34:37]
	v_mfma_f32_16x16x32_bf16 v[2:5], v[166:169], v[206:209], v[2:5]
	v_mfma_f32_16x16x32_bf16 v[10:13], v[154:157], v[206:209], v[10:13]
	s_barrier
	s_setprio 1
	v_add_u32_e32 v133, 0x18000, v131
	ds_read_b128 v[134:137], v133
	ds_read_b128 v[138:141], v133 offset:1024
	ds_read_b128 v[142:145], v133 offset:2048
	ds_read_b128 v[146:149], v133 offset:3072
	v_add_u32_e32 v133, 0x1c000, v131
	ds_read_b128 v[150:153], v133
	ds_read_b128 v[154:157], v133 offset:1024
	ds_read_b128 v[158:161], v133 offset:2048
	ds_read_b128 v[166:169], v133 offset:3072
	s_add_i32 s78, s77, 0x160000
	s_mov_b32 m0, s48
	ds_read_b128 v[170:173], v132 offset:32768
	ds_read_b128 v[174:177], v132 offset:33792
	ds_read_b128 v[178:181], v132 offset:34816
	ds_read_b128 v[182:185], v132 offset:35840
	ds_read_b128 v[186:189], v132 offset:36864
	ds_read_b128 v[190:193], v132 offset:37888
	ds_read_b128 v[200:203], v132 offset:38912
	ds_read_b128 v[206:209], v132 offset:39936
	s_mov_b32 m0, s47
	s_nop 0
	buffer_load_dwordx4 v130, s[4:7], s77 offen lds
	s_mov_b32 m0, s48
	s_nop 0
	buffer_load_dwordx4 v0, s[4:7], s78 offen lds
	s_mov_b32 m0, s49
	s_nop 0
	buffer_load_dwordx4 v130, s[4:7], s78 offen lds
	s_waitcnt vmcnt(8)
	s_waitcnt lgkmcnt(0)
	s_setprio 2
	s_barrier
	v_mfma_f32_16x16x32_bf16 v[22:25], v[134:137], v[170:173], v[22:25]
	v_mfma_f32_16x16x32_bf16 v[14:17], v[142:145], v[170:173], v[14:17]
	v_mfma_f32_16x16x32_bf16 v[54:57], v[142:145], v[178:181], v[54:57]
	v_mfma_f32_16x16x32_bf16 v[74:77], v[134:137], v[178:181], v[74:77]
	v_mfma_f32_16x16x32_bf16 v[106:109], v[134:137], v[186:189], v[106:109]
	v_mfma_f32_16x16x32_bf16 v[102:105], v[142:145], v[186:189], v[102:105]
	v_mfma_f32_16x16x32_bf16 v[118:121], v[142:145], v[200:203], v[118:121]
	v_mfma_f32_16x16x32_bf16 v[122:125], v[134:137], v[200:203], v[122:125]
	v_mfma_f32_16x16x32_bf16 v[22:25], v[138:141], v[174:177], v[22:25]
	v_mfma_f32_16x16x32_bf16 v[14:17], v[146:149], v[174:177], v[14:17]
	v_mfma_f32_16x16x32_bf16 v[54:57], v[146:149], v[182:185], v[54:57]
	v_mfma_f32_16x16x32_bf16 v[74:77], v[138:141], v[182:185], v[74:77]
	v_mfma_f32_16x16x32_bf16 v[106:109], v[138:141], v[190:193], v[106:109]
	v_mfma_f32_16x16x32_bf16 v[102:105], v[146:149], v[190:193], v[102:105]
	v_mfma_f32_16x16x32_bf16 v[118:121], v[146:149], v[206:209], v[118:121]
	v_mfma_f32_16x16x32_bf16 v[122:125], v[138:141], v[206:209], v[122:125]
	v_mfma_f32_16x16x32_bf16 v[6:9], v[150:153], v[170:173], v[6:9]
	v_mfma_f32_16x16x32_bf16 v[18:21], v[158:161], v[170:173], v[18:21]
	v_mfma_f32_16x16x32_bf16 v[78:81], v[158:161], v[178:181], v[78:81]
	v_mfma_f32_16x16x32_bf16 v[50:53], v[150:153], v[178:181], v[50:53]
	v_mfma_f32_16x16x32_bf16 v[98:101], v[150:153], v[186:189], v[98:101]
	v_mfma_f32_16x16x32_bf16 v[110:113], v[158:161], v[186:189], v[110:113]
	v_mfma_f32_16x16x32_bf16 v[126:129], v[158:161], v[200:203], v[126:129]
	v_mfma_f32_16x16x32_bf16 v[114:117], v[150:153], v[200:203], v[114:117]
	v_mfma_f32_16x16x32_bf16 v[6:9], v[154:157], v[174:177], v[6:9]
	v_mfma_f32_16x16x32_bf16 v[18:21], v[166:169], v[174:177], v[18:21]
	v_mfma_f32_16x16x32_bf16 v[78:81], v[166:169], v[182:185], v[78:81]
	v_mfma_f32_16x16x32_bf16 v[50:53], v[154:157], v[182:185], v[50:53]
	v_mfma_f32_16x16x32_bf16 v[98:101], v[154:157], v[190:193], v[98:101]
	v_mfma_f32_16x16x32_bf16 v[110:113], v[166:169], v[190:193], v[110:113]
	v_mfma_f32_16x16x32_bf16 v[126:129], v[166:169], v[206:209], v[126:129]
	v_mfma_f32_16x16x32_bf16 v[114:117], v[154:157], v[206:209], v[114:117]
	s_barrier
;     static __device__ __forceinline__ bool last_of_chain(const Unit& u) { return (u.pn >> 3) == 2; }
; #define PG8_STAGE(bufoff, gbase, voff) do { const int so_ = (int)(unsigned)((const char*)(gbase) - base_##voff); _Pragma("unroll") for (int _i = 0; _i < 2; ++_i) \
;         __builtin_amdgcn_raw_ptr_buffer_load_lds(rs_##voff, (PG8_LAS unsigned*)(lds + (bufoff) + ldsw + _i * 8192), 16, (int)(voff)[_i], so_, 0, 0); } while (0)
; #define PG8_LDA(dst, b, h) do { _Pragma("unroll") for (int m = 0; m < 4; ++m) _Pragma("unroll") for (int k = 0; k < 2; ++k) dst[m][k] = *(const PG8_LAS bf16x8*)(lds + PG8_SA(b, h) + aoff + m * 2048 + k * 1024); } while (0)
; template <class Epi, class Sched, bool ALIGN_EPI = false, bool SP2 = false>
; __device__ __forceinline__ void gemm_phase(PG8_LAS unsigned char* lds, const Gemm g, const Sched& S, const Epi& E, int tid_in) {
;     ...
;             PG8_LDB(B0, 0, 0); PG8_LDB(B1, 0, 1); PG8_SCHED; PG8_LDA(At, 0, 0); PG8_STAGE(PG8_SA(1, 1), a1 + hstepA, voffA);
;             PG8_WAIT_V(8); PG8_WAIT_L(0); PG8_BAR; PG8_MMA(0, 0, At, B0); PG8_MMA(0, 1, At, B1); PG8_BAR; PG8_SCHED;
;             PG8_LDA(At, 0, 1); PG8_STAGE(PG8_SB(0, 0), b2, voffB); PG8_STAGE(PG8_SB(0, 1), b2 + hstepB, voffB); PG8_STAGE(PG8_SA(0, 0), a2, voffA);
;             PG8_WAIT_V(8); PG8_WAIT_L(0); PG8_BAR; PG8_MMA(1, 0, At, B0); PG8_MMA(1, 1, At, B1); PG8_BAR; PG8_SCHED;
;             PG8_LDB(B0, 1, 0); PG8_LDB(B1, 1, 1); PG8_SCHED; PG8_LDA(At, 1, 0); PG8_STAGE(PG8_SA(0, 1), a2 + hstepA, voffA);
;             PG8_WAIT_V(8); PG8_WAIT_L(0); PG8_BAR; PG8_MMA(0, 0, At, B0); PG8_MMA(0, 1, At, B1); PG8_BAR; PG8_SCHED;
;             PG8_LDA(At, 1, 1); PG8_STAGE(PG8_SB(1, 0), b3, voffB); PG8_STAGE(PG8_SB(1, 1), b3 + hstepB, voffB); PG8_STAGE(PG8_SA(1, 0), a3, voffA);
;             PG8_WAIT_V(8); PG8_WAIT_L(0); PG8_BAR; PG8_MMA(1, 0, At, B0); PG8_MMA(1, 1, At, B1); PG8_BAR; PG8_SCHED;
;     ...
;         if (!has_next) break;
;         bool zero_acc = true; if constexpr (Epi::CHAIN) zero_acc = Epi::last_of_chain(cur);
;         if (zero_acc) {
; #pragma unroll
;         for (int a = 0; a < 2; ++a)
; #pragma unroll
;             for (int b = 0; b < 2; ++b)
; #pragma unroll
;                 for (int m = 0; m < 4; ++m)
; #pragma unroll
;                     for (int n = 0; n < 2; ++n) acc[a][b][m][n] = (f32x4){0.f, 0.f, 0.f, 0.f};
;         }
;         cur = nxt; cA = nA; cB = nB; ++ui;
	s_setprio 1
	s_mov_b32 m0, s60
	s_add_i32 s78, s76, 0x80
	ds_read_b128 v[170:173], v132 offset:49152
	ds_read_b128 v[174:177], v132 offset:50176
	ds_read_b128 v[178:181], v132 offset:51200
	ds_read_b128 v[182:185], v132 offset:52224
	ds_read_b128 v[186:189], v132 offset:53248
	ds_read_b128 v[190:193], v132 offset:54272
	ds_read_b128 v[200:203], v132 offset:55296
	ds_read_b128 v[206:209], v132 offset:56320
	buffer_load_dwordx4 v0, s[40:43], s78 offen lds
	s_mov_b32 m0, s61
	s_add_i32 s76, s76, 0x160080
	buffer_load_dwordx4 v130, s[40:43], s78 offen lds
	s_mov_b32 m0, s66
	s_addk_i32 s77, 0x80
	buffer_load_dwordx4 v0, s[40:43], s76 offen lds
	s_mov_b32 m0, s67
	s_nop 0
	buffer_load_dwordx4 v130, s[40:43], s76 offen lds
	s_mov_b32 m0, s62
	s_nop 0
	buffer_load_dwordx4 v0, s[4:7], s77 offen lds
	s_waitcnt vmcnt(7)
	s_waitcnt lgkmcnt(0)
	s_setprio 2
	s_barrier
	v_mfma_f32_16x16x32_bf16 v[62:65], v[134:137], v[170:173], v[62:65]
	v_mfma_f32_16x16x32_bf16 v[46:49], v[142:145], v[170:173], v[46:49]
	v_mfma_f32_16x16x32_bf16 v[70:73], v[142:145], v[178:181], v[70:73]
	v_mfma_f32_16x16x32_bf16 v[82:85], v[134:137], v[178:181], v[82:85]
	v_mfma_f32_16x16x32_bf16 v[94:97], v[134:137], v[186:189], v[94:97]
	v_mfma_f32_16x16x32_bf16 v[90:93], v[142:145], v[186:189], v[90:93]
	v_mfma_f32_16x16x32_bf16 v[26:29], v[142:145], v[200:203], v[26:29]
	v_mfma_f32_16x16x32_bf16 v[38:41], v[134:137], v[200:203], v[38:41]
	v_mfma_f32_16x16x32_bf16 v[62:65], v[138:141], v[174:177], v[62:65]
	v_mfma_f32_16x16x32_bf16 v[46:49], v[146:149], v[174:177], v[46:49]
	v_mfma_f32_16x16x32_bf16 v[70:73], v[146:149], v[182:185], v[70:73]
	v_mfma_f32_16x16x32_bf16 v[82:85], v[138:141], v[182:185], v[82:85]
	v_mfma_f32_16x16x32_bf16 v[94:97], v[138:141], v[190:193], v[94:97]
	v_mfma_f32_16x16x32_bf16 v[90:93], v[146:149], v[190:193], v[90:93]
	v_mfma_f32_16x16x32_bf16 v[26:29], v[146:149], v[206:209], v[26:29]
	v_mfma_f32_16x16x32_bf16 v[38:41], v[138:141], v[206:209], v[38:41]
	v_mfma_f32_16x16x32_bf16 v[42:45], v[150:153], v[170:173], v[42:45]
	v_mfma_f32_16x16x32_bf16 v[30:33], v[158:161], v[170:173], v[30:33]
	v_mfma_f32_16x16x32_bf16 v[86:89], v[158:161], v[178:181], v[86:89]
	v_mfma_f32_16x16x32_bf16 v[66:69], v[150:153], v[178:181], v[66:69]
	v_mfma_f32_16x16x32_bf16 v[58:61], v[150:153], v[186:189], v[58:61]
	v_mfma_f32_16x16x32_bf16 v[34:37], v[158:161], v[186:189], v[34:37]
	v_mfma_f32_16x16x32_bf16 v[2:5], v[158:161], v[200:203], v[2:5]
	v_mfma_f32_16x16x32_bf16 v[10:13], v[150:153], v[200:203], v[10:13]
	v_mfma_f32_16x16x32_bf16 v[42:45], v[154:157], v[174:177], v[42:45]
	v_mfma_f32_16x16x32_bf16 v[30:33], v[166:169], v[174:177], v[30:33]
	v_mfma_f32_16x16x32_bf16 v[86:89], v[166:169], v[182:185], v[86:89]
	v_mfma_f32_16x16x32_bf16 v[66:69], v[154:157], v[182:185], v[66:69]
	v_mfma_f32_16x16x32_bf16 v[58:61], v[154:157], v[190:193], v[58:61]
	v_mfma_f32_16x16x32_bf16 v[34:37], v[166:169], v[190:193], v[34:37]
	v_mfma_f32_16x16x32_bf16 v[2:5], v[166:169], v[206:209], v[2:5]
	v_mfma_f32_16x16x32_bf16 v[10:13], v[154:157], v[206:209], v[10:13]
	s_barrier
	s_setprio 1
	s_add_i32 s39, s39, 2
	s_add_u32 s22, s22, 0x100
	s_addc_u32 s23, s23, 0
	s_cmpk_gt_u32 s39, 0x55
	s_cbranch_scc0 .Lyng_loop4
	s_setprio 0
.Lyng_after4:
	s_and_b64 vcc, exec, s[36:37]
	s_cbranch_vccnz .LBB0_1572
	v_mov_b32_e32 v2, 0
	s_mov_b32 s10, s73
	s_mov_b32 s25, s74
	s_mov_b64 s[12:13], s[20:21]
	s_mov_b64 s[14:15], s[16:17]
	s_mov_b32 s72, s75
	v_mov_b32_e32 v3, v2
	v_mov_b32_e32 v4, v2
	v_mov_b32_e32 v5, v2
	v_mov_b32_e32 v10, v2
	v_mov_b32_e32 v11, v2
	v_mov_b32_e32 v12, v2
	v_mov_b32_e32 v13, v2
	v_mov_b32_e32 v34, v2
	v_mov_b32_e32 v35, v2
	v_mov_b32_e32 v36, v2
	v_mov_b32_e32 v37, v2
	v_mov_b32_e32 v58, v2
	v_mov_b32_e32 v59, v2
	v_mov_b32_e32 v60, v2
	v_mov_b32_e32 v61, v2
	v_mov_b32_e32 v86, v2
	v_mov_b32_e32 v87, v2
	v_mov_b32_e32 v88, v2
	v_mov_b32_e32 v89, v2
	v_mov_b32_e32 v66, v2
	v_mov_b32_e32 v67, v2
	v_mov_b32_e32 v68, v2
	v_mov_b32_e32 v69, v2
	v_mov_b32_e32 v30, v2
	v_mov_b32_e32 v31, v2
	v_mov_b32_e32 v32, v2
	v_mov_b32_e32 v33, v2
	v_mov_b32_e32 v42, v2
	v_mov_b32_e32 v43, v2
	v_mov_b32_e32 v44, v2
	v_mov_b32_e32 v45, v2
	v_mov_b32_e32 v26, v2
	v_mov_b32_e32 v27, v2
	v_mov_b32_e32 v28, v2
	v_mov_b32_e32 v29, v2
	v_mov_b32_e32 v38, v2
	v_mov_b32_e32 v39, v2
	v_mov_b32_e32 v40, v2
	v_mov_b32_e32 v41, v2
	v_mov_b32_e32 v90, v2
	v_mov_b32_e32 v91, v2
	v_mov_b32_e32 v92, v2
	v_mov_b32_e32 v93, v2
	v_mov_b32_e32 v94, v2
	v_mov_b32_e32 v95, v2
	v_mov_b32_e32 v96, v2
	v_mov_b32_e32 v97, v2
	v_mov_b32_e32 v70, v2
	v_mov_b32_e32 v71, v2
	v_mov_b32_e32 v72, v2
	v_mov_b32_e32 v73, v2
	v_mov_b32_e32 v82, v2
	v_mov_b32_e32 v83, v2
	v_mov_b32_e32 v84, v2
	v_mov_b32_e32 v85, v2
	v_mov_b32_e32 v46, v2
	v_mov_b32_e32 v47, v2
	v_mov_b32_e32 v48, v2
	v_mov_b32_e32 v49, v2
	v_mov_b32_e32 v62, v2
	v_mov_b32_e32 v63, v2
	v_mov_b32_e32 v64, v2
	v_mov_b32_e32 v65, v2
	v_mov_b32_e32 v126, v2
	v_mov_b32_e32 v127, v2
	v_mov_b32_e32 v128, v2
	v_mov_b32_e32 v129, v2
	v_mov_b32_e32 v114, v2
	v_mov_b32_e32 v115, v2
	v_mov_b32_e32 v116, v2
	v_mov_b32_e32 v117, v2
	v_mov_b32_e32 v110, v2
	v_mov_b32_e32 v111, v2
	v_mov_b32_e32 v112, v2
	v_mov_b32_e32 v113, v2
	v_mov_b32_e32 v98, v2
	v_mov_b32_e32 v99, v2
	v_mov_b32_e32 v100, v2
	v_mov_b32_e32 v101, v2
	v_mov_b32_e32 v78, v2
	v_mov_b32_e32 v79, v2
	v_mov_b32_e32 v80, v2
	v_mov_b32_e32 v81, v2
	v_mov_b32_e32 v50, v2
	v_mov_b32_e32 v51, v2
	v_mov_b32_e32 v52, v2
	v_mov_b32_e32 v53, v2
	v_mov_b32_e32 v18, v2
	v_mov_b32_e32 v19, v2
	v_mov_b32_e32 v20, v2
	v_mov_b32_e32 v21, v2
	v_mov_b32_e32 v6, v2
	v_mov_b32_e32 v7, v2
	v_mov_b32_e32 v8, v2
	v_mov_b32_e32 v9, v2
	v_mov_b32_e32 v118, v2
	v_mov_b32_e32 v119, v2
	v_mov_b32_e32 v120, v2
	v_mov_b32_e32 v121, v2
	v_mov_b32_e32 v122, v2
	v_mov_b32_e32 v123, v2
	v_mov_b32_e32 v124, v2
	v_mov_b32_e32 v125, v2
	v_mov_b32_e32 v102, v2
	v_mov_b32_e32 v103, v2
	v_mov_b32_e32 v104, v2
	v_mov_b32_e32 v105, v2
	v_mov_b32_e32 v106, v2
	v_mov_b32_e32 v107, v2
	v_mov_b32_e32 v108, v2
	v_mov_b32_e32 v109, v2
	v_mov_b32_e32 v54, v2
	v_mov_b32_e32 v55, v2
	v_mov_b32_e32 v56, v2
	v_mov_b32_e32 v57, v2
	v_mov_b32_e32 v74, v2
	v_mov_b32_e32 v75, v2
	v_mov_b32_e32 v76, v2
	v_mov_b32_e32 v77, v2
	v_mov_b32_e32 v14, v2
	v_mov_b32_e32 v15, v2
	v_mov_b32_e32 v16, v2
	v_mov_b32_e32 v17, v2
	v_mov_b32_e32 v22, v2
	v_mov_b32_e32 v23, v2
	v_mov_b32_e32 v24, v2
	v_mov_b32_e32 v25, v2
	s_branch .LBB0_1572
